# GEMM K-loops: in every load segment the ds_read_b128 fragment reads are issued first, staging address arithmetic after them
# speedup vs baseline: 1.0085x; 1.0003x over previous
; #define STAGE(P, BASE, br, kt) STAGET(tid_, P, BASE, br, kt)
; #define LDA(dst, b, h) UFOR(m, 4) UFOR(k, 2) \
;     dst[m][k] = *reinterpret_cast<const bf16x8*>((char*)SA(b, h) + lds_byte(wr * 64 + m * 16 + fr, k * 32 + fq * 8))
; #define LDB(dst, b, h) UFOR(n, 2) UFOR(k, 2) \
;     dst[n][k] = *reinterpret_cast<const bf16x8*>((char*)SB(b, h) + lds_byte(wc * 32 + n * 16 + fr, k * 32 + fq * 8))
; #define MMA(ai, bj, At, Bq) do { __builtin_amdgcn_s_setprio(1); \
;     UFOR(m, 4) UFOR(n, 2) UFOR(k, 2) \
;       acc[ai][bj][m][n] = __builtin_amdgcn_mfma_f32_16x16x32_bf16(Bq[n][k], At[m][k], acc[ai][bj][m][n], 0, 0, 0); \
;     __builtin_amdgcn_s_setprio(0); } while (0)
; #define WAIT_V(n) asm volatile("s_waitcnt vmcnt(" #n ")" ::: "memory")
; #define WAIT_L(n) asm volatile("s_waitcnt lgkmcnt(" #n ")" ::: "memory")
; #define BAR __builtin_amdgcn_s_barrier()
; #define SCHED __builtin_amdgcn_sched_barrier(0)
; template <int EPI, int K, int KL> ...
;     ...
;   for (int t = 0; t < nt - 2; t += 2) {
;     LDB(B0, 0, 0); SCHED; LDA(At, 0, 0); STAGE(SA(1, 1), A, brow + HALF, t + 1);
;     WAIT_L(8); BAR; WAIT_L(0); MMA(0, 0, At, B0); BAR; SCHED;
;     LDB(B1, 0, 1); STAGE(SB(0, 0), Bt, bcol, t + 2);
;     BAR; WAIT_L(0); MMA(0, 1, At, B1); BAR;
;     LDA(At, 0, 1); STAGE(SA(0, 0), A, brow, t + 2);
;     BAR; WAIT_L(0); MMA(1, 0, At, B0); BAR; SCHED;
;     STAGE(SB(0, 1), Bt, bcol + HALF, t + 2);
;     WAIT_V(6); BAR; MMA(1, 1, At, B1); BAR;
;     LDB(B0, 1, 0); SCHED; LDA(At, 1, 0); STAGE(SA(0, 1), A, brow + HALF, t + 2);
;     WAIT_L(8); BAR; WAIT_L(0); MMA(0, 0, At, B0); BAR; SCHED;
.LBB0_236:
	ds_read_b128 v[174:177], v170
	ds_read_b128 v[178:181], v170 offset:1024
	ds_read_b128 v[182:185], v170 offset:2048
	ds_read_b128 v[186:189], v170 offset:3072
	ds_read_b128 v[190:193], v162
	ds_read_b128 v[194:197], v162 offset:1024
	ds_read_b128 v[198:201], v161
	ds_read_b128 v[202:205], v161 offset:1024
	ds_read_b128 v[218:221], v160
	ds_read_b128 v[222:225], v160 offset:1024
	ds_read_b128 v[226:229], v159
	ds_read_b128 v[230:233], v159 offset:1024
	v_add_u32_e32 v171, 0xc000, v157
	v_lshl_add_u64 v[136:137], s[92:93], 0, v[150:151]
	v_readfirstlane_b32 s18, v171
	v_lshl_add_u64 v[138:139], v[136:137], 0, s[88:89]
	s_mov_b32 m0, s18
	v_add_u32_e32 v172, 0xe000, v157
	global_load_lds_dwordx4 v[138:139], off
	v_lshl_add_u64 v[138:139], s[92:93], 0, v[152:153]
	v_readfirstlane_b32 s18, v172
	v_lshl_add_u64 v[208:209], v[138:139], 0, s[88:89]
	s_mov_b32 m0, s18
	s_nop 0
	global_load_lds_dwordx4 v[208:209], off
	s_waitcnt lgkmcnt(8)
	s_barrier
	s_waitcnt lgkmcnt(0)
	s_waitcnt lgkmcnt(0)
	v_mfma_f32_16x16x32_bf16 v[124:127], v[174:177], v[190:193], v[124:127]
	v_mfma_f32_16x16x32_bf16 v[120:123], v[182:185], v[190:193], v[120:123]
	v_mfma_f32_16x16x32_bf16 v[116:119], v[174:177], v[198:201], v[116:119]
	v_mfma_f32_16x16x32_bf16 v[112:115], v[182:185], v[198:201], v[112:115]
	v_mfma_f32_16x16x32_bf16 v[108:111], v[174:177], v[218:221], v[108:111]
	v_mfma_f32_16x16x32_bf16 v[104:107], v[182:185], v[218:221], v[104:107]
	v_mfma_f32_16x16x32_bf16 v[100:103], v[174:177], v[226:229], v[100:103]
	v_mfma_f32_16x16x32_bf16 v[96:99], v[182:185], v[226:229], v[96:99]
	v_mfma_f32_16x16x32_bf16 v[124:127], v[178:181], v[194:197], v[124:127]
	v_mfma_f32_16x16x32_bf16 v[120:123], v[186:189], v[194:197], v[120:123]
	v_mfma_f32_16x16x32_bf16 v[116:119], v[178:181], v[202:205], v[116:119]
	v_mfma_f32_16x16x32_bf16 v[112:115], v[186:189], v[202:205], v[112:115]
	v_mfma_f32_16x16x32_bf16 v[108:111], v[178:181], v[222:225], v[108:111]
	v_mfma_f32_16x16x32_bf16 v[104:107], v[186:189], v[222:225], v[104:107]
	v_mfma_f32_16x16x32_bf16 v[100:103], v[178:181], v[230:233], v[100:103]
	v_mfma_f32_16x16x32_bf16 v[96:99], v[186:189], v[230:233], v[96:99]
	s_barrier
	ds_read_b128 v[234:237], v168
	ds_read_b128 v[238:241], v168 offset:1024
	ds_read_b128 v[242:245], v168 offset:2048
	ds_read_b128 v[246:249], v168 offset:3072
	v_lshl_add_u64 v[208:209], s[92:93], 0, v[146:147]
	v_readfirstlane_b32 s18, v156
	v_lshl_add_u64 v[210:211], v[208:209], 0, s[52:53]
	s_mov_b32 m0, s18
	v_add_u32_e32 v134, 0x2000, v156
	global_load_lds_dwordx4 v[210:211], off
	v_lshl_add_u64 v[210:211], s[92:93], 0, v[148:149]
	v_readfirstlane_b32 s18, v134
	v_lshl_add_u64 v[214:215], v[210:211], 0, s[52:53]
	s_mov_b32 m0, s18
	s_nop 0
	global_load_lds_dwordx4 v[214:215], off
	s_barrier
	s_waitcnt lgkmcnt(0)
	s_waitcnt lgkmcnt(0)
	v_mfma_f32_16x16x32_bf16 v[92:95], v[234:237], v[190:193], v[92:95]
	v_mfma_f32_16x16x32_bf16 v[88:91], v[242:245], v[190:193], v[88:91]
	v_mfma_f32_16x16x32_bf16 v[84:87], v[234:237], v[198:201], v[84:87]
	v_mfma_f32_16x16x32_bf16 v[80:83], v[242:245], v[198:201], v[80:83]
	v_mfma_f32_16x16x32_bf16 v[76:79], v[234:237], v[218:221], v[76:79]
	v_mfma_f32_16x16x32_bf16 v[72:75], v[242:245], v[218:221], v[72:75]
	v_mfma_f32_16x16x32_bf16 v[68:71], v[234:237], v[226:229], v[68:71]
	v_mfma_f32_16x16x32_bf16 v[64:67], v[242:245], v[226:229], v[64:67]
	v_mfma_f32_16x16x32_bf16 v[92:95], v[238:241], v[194:197], v[92:95]
	v_mfma_f32_16x16x32_bf16 v[88:91], v[246:249], v[194:197], v[88:91]
	v_mfma_f32_16x16x32_bf16 v[84:87], v[238:241], v[202:205], v[84:87]
	v_mfma_f32_16x16x32_bf16 v[80:83], v[246:249], v[202:205], v[80:83]
	v_mfma_f32_16x16x32_bf16 v[76:79], v[238:241], v[222:225], v[76:79]
	v_mfma_f32_16x16x32_bf16 v[72:75], v[246:249], v[222:225], v[72:75]
	v_mfma_f32_16x16x32_bf16 v[68:71], v[238:241], v[230:233], v[68:71]
	v_mfma_f32_16x16x32_bf16 v[64:67], v[246:249], v[230:233], v[64:67]
	v_readfirstlane_b32 s18, v157
	v_add_u32_e32 v134, 0x2000, v157
	v_lshl_add_u64 v[214:215], v[136:137], 0, s[8:9]
	s_mov_b32 m0, s18
	v_readfirstlane_b32 s18, v134
	s_barrier
	ds_read_b128 v[190:193], v162 offset:16384
	ds_read_b128 v[194:197], v162 offset:17408
	ds_read_b128 v[198:201], v161 offset:16384
	ds_read_b128 v[202:205], v161 offset:17408
	ds_read_b128 v[218:221], v160 offset:16384
	ds_read_b128 v[222:225], v160 offset:17408
	ds_read_b128 v[226:229], v159 offset:16384
	ds_read_b128 v[230:233], v159 offset:17408
	global_load_lds_dwordx4 v[214:215], off
	v_lshl_add_u64 v[214:215], v[138:139], 0, s[8:9]
	s_mov_b32 m0, s18
	s_nop 0
	global_load_lds_dwordx4 v[214:215], off
	s_barrier
	s_waitcnt lgkmcnt(0)
	s_waitcnt lgkmcnt(0)
	v_mfma_f32_16x16x32_bf16 v[60:63], v[174:177], v[190:193], v[60:63]
	v_mfma_f32_16x16x32_bf16 v[56:59], v[182:185], v[190:193], v[56:59]
	v_mfma_f32_16x16x32_bf16 v[52:55], v[174:177], v[198:201], v[52:55]
	v_mfma_f32_16x16x32_bf16 v[48:51], v[182:185], v[198:201], v[48:51]
	v_mfma_f32_16x16x32_bf16 v[44:47], v[174:177], v[218:221], v[44:47]
	v_mfma_f32_16x16x32_bf16 v[40:43], v[182:185], v[218:221], v[40:43]
	v_mfma_f32_16x16x32_bf16 v[36:39], v[174:177], v[226:229], v[36:39]
	v_mfma_f32_16x16x32_bf16 v[32:35], v[182:185], v[226:229], v[32:35]
	v_mfma_f32_16x16x32_bf16 v[60:63], v[178:181], v[194:197], v[60:63]
	v_mfma_f32_16x16x32_bf16 v[56:59], v[186:189], v[194:197], v[56:59]
	v_mfma_f32_16x16x32_bf16 v[52:55], v[178:181], v[202:205], v[52:55]
	v_mfma_f32_16x16x32_bf16 v[48:51], v[186:189], v[202:205], v[48:51]
	v_mfma_f32_16x16x32_bf16 v[44:47], v[178:181], v[222:225], v[44:47]
	v_mfma_f32_16x16x32_bf16 v[40:43], v[186:189], v[222:225], v[40:43]
	v_mfma_f32_16x16x32_bf16 v[36:39], v[178:181], v[230:233], v[36:39]
	v_mfma_f32_16x16x32_bf16 v[32:35], v[186:189], v[230:233], v[32:35]
	s_barrier
; #define STAGE(P, BASE, br, kt) STAGET(tid_, P, BASE, br, kt)
; #define LDA(dst, b, h) UFOR(m, 4) UFOR(k, 2) \
;     dst[m][k] = *reinterpret_cast<const bf16x8*>((char*)SA(b, h) + lds_byte(wr * 64 + m * 16 + fr, k * 32 + fq * 8))
; #define LDB(dst, b, h) UFOR(n, 2) UFOR(k, 2) \
;     dst[n][k] = *reinterpret_cast<const bf16x8*>((char*)SB(b, h) + lds_byte(wc * 32 + n * 16 + fr, k * 32 + fq * 8))
; #define MMA(ai, bj, At, Bq) do { __builtin_amdgcn_s_setprio(1); \
;     UFOR(m, 4) UFOR(n, 2) UFOR(k, 2) \
;       acc[ai][bj][m][n] = __builtin_amdgcn_mfma_f32_16x16x32_bf16(Bq[n][k], At[m][k], acc[ai][bj][m][n], 0, 0, 0); \
;     __builtin_amdgcn_s_setprio(0); } while (0)
; #define WAIT_V(n) asm volatile("s_waitcnt vmcnt(" #n ")" ::: "memory")
; #define WAIT_L(n) asm volatile("s_waitcnt lgkmcnt(" #n ")" ::: "memory")
; #define BAR __builtin_amdgcn_s_barrier()
; #define SCHED __builtin_amdgcn_sched_barrier(0)
; template <int EPI, int K, int KL> ...
;     ...
;     WAIT_V(6); BAR; MMA(1, 1, At, B1); BAR;
;     LDB(B0, 1, 0); SCHED; LDA(At, 1, 0); STAGE(SA(0, 1), A, brow + HALF, t + 2);
;     WAIT_L(8); BAR; WAIT_L(0); MMA(0, 0, At, B0); BAR; SCHED;
;     LDB(B1, 1, 1); STAGE(SB(1, 0), Bt, bcol, t + 3);
;     BAR; WAIT_L(0); MMA(0, 1, At, B1); BAR;
;     LDA(At, 1, 1); STAGE(SA(1, 0), A, brow, t + 3);
;     BAR; WAIT_L(0); MMA(1, 0, At, B0); BAR; SCHED;
	v_readfirstlane_b32 s18, v158
	v_add_u32_e32 v134, 0x2000, v158
	v_lshl_add_u64 v[174:175], v[208:209], 0, s[54:55]
	s_mov_b32 m0, s18
	v_readfirstlane_b32 s18, v134
	global_load_lds_dwordx4 v[174:175], off
	v_lshl_add_u64 v[174:175], v[210:211], 0, s[54:55]
	s_mov_b32 m0, s18
	s_nop 0
	global_load_lds_dwordx4 v[174:175], off
	s_waitcnt vmcnt(6)
	s_barrier
	v_mfma_f32_16x16x32_bf16 v[28:31], v[234:237], v[190:193], v[28:31]
	v_mfma_f32_16x16x32_bf16 v[24:27], v[242:245], v[190:193], v[24:27]
	v_mfma_f32_16x16x32_bf16 v[20:23], v[234:237], v[198:201], v[20:23]
	v_mfma_f32_16x16x32_bf16 v[16:19], v[242:245], v[198:201], v[16:19]
	v_mfma_f32_16x16x32_bf16 v[12:15], v[234:237], v[218:221], v[12:15]
	v_mfma_f32_16x16x32_bf16 v[8:11], v[242:245], v[218:221], v[8:11]
	v_mfma_f32_16x16x32_bf16 v[4:7], v[234:237], v[226:229], v[4:7]
	v_mfma_f32_16x16x32_bf16 v[0:3], v[242:245], v[226:229], v[0:3]
	v_mfma_f32_16x16x32_bf16 v[28:31], v[238:241], v[194:197], v[28:31]
	v_mfma_f32_16x16x32_bf16 v[24:27], v[246:249], v[194:197], v[24:27]
	v_mfma_f32_16x16x32_bf16 v[20:23], v[238:241], v[202:205], v[20:23]
	v_mfma_f32_16x16x32_bf16 v[16:19], v[246:249], v[202:205], v[16:19]
	v_mfma_f32_16x16x32_bf16 v[12:15], v[238:241], v[222:225], v[12:15]
	v_mfma_f32_16x16x32_bf16 v[8:11], v[246:249], v[222:225], v[8:11]
	v_mfma_f32_16x16x32_bf16 v[4:7], v[238:241], v[230:233], v[4:7]
	v_mfma_f32_16x16x32_bf16 v[0:3], v[246:249], v[230:233], v[0:3]
	s_barrier
	ds_read_b128 v[174:177], v164
	ds_read_b128 v[178:181], v164 offset:1024
	ds_read_b128 v[182:185], v164 offset:2048
	ds_read_b128 v[186:189], v164 offset:3072
	ds_read_b128 v[190:193], v162 offset:32768
	ds_read_b128 v[194:197], v162 offset:33792
	ds_read_b128 v[198:201], v161 offset:32768
	ds_read_b128 v[202:205], v161 offset:33792
	ds_read_b128 v[218:221], v160 offset:32768
	ds_read_b128 v[222:225], v160 offset:33792
	ds_read_b128 v[226:229], v159 offset:32768
	ds_read_b128 v[230:233], v159 offset:33792
	v_add_u32_e32 v134, 0x4000, v157
	v_lshl_add_u64 v[214:215], v[136:137], 0, s[12:13]
	v_readfirstlane_b32 s18, v134
	v_add_u32_e32 v134, 0x6000, v157
	s_mov_b32 m0, s18
	v_readfirstlane_b32 s18, v134
	global_load_lds_dwordx4 v[214:215], off
	v_lshl_add_u64 v[214:215], v[138:139], 0, s[12:13]
	s_mov_b32 m0, s18
	s_nop 0
	global_load_lds_dwordx4 v[214:215], off
	s_waitcnt lgkmcnt(8)
	s_barrier
	s_waitcnt lgkmcnt(0)
	s_waitcnt lgkmcnt(0)
	v_mfma_f32_16x16x32_bf16 v[124:127], v[174:177], v[190:193], v[124:127]
	v_mfma_f32_16x16x32_bf16 v[120:123], v[182:185], v[190:193], v[120:123]
	v_mfma_f32_16x16x32_bf16 v[116:119], v[174:177], v[198:201], v[116:119]
	v_mfma_f32_16x16x32_bf16 v[112:115], v[182:185], v[198:201], v[112:115]
	v_mfma_f32_16x16x32_bf16 v[108:111], v[174:177], v[218:221], v[108:111]
	v_mfma_f32_16x16x32_bf16 v[104:107], v[182:185], v[218:221], v[104:107]
	v_mfma_f32_16x16x32_bf16 v[100:103], v[174:177], v[226:229], v[100:103]
	v_mfma_f32_16x16x32_bf16 v[96:99], v[182:185], v[226:229], v[96:99]
	v_mfma_f32_16x16x32_bf16 v[124:127], v[178:181], v[194:197], v[124:127]
	v_mfma_f32_16x16x32_bf16 v[120:123], v[186:189], v[194:197], v[120:123]
	v_mfma_f32_16x16x32_bf16 v[116:119], v[178:181], v[202:205], v[116:119]
	v_mfma_f32_16x16x32_bf16 v[112:115], v[186:189], v[202:205], v[112:115]
	v_mfma_f32_16x16x32_bf16 v[108:111], v[178:181], v[222:225], v[108:111]
	v_mfma_f32_16x16x32_bf16 v[104:107], v[186:189], v[222:225], v[104:107]
	v_mfma_f32_16x16x32_bf16 v[100:103], v[178:181], v[230:233], v[100:103]
	v_mfma_f32_16x16x32_bf16 v[96:99], v[186:189], v[230:233], v[96:99]
	s_barrier
	ds_read_b128 v[234:237], v163
	ds_read_b128 v[238:241], v163 offset:1024
	ds_read_b128 v[242:245], v163 offset:2048
	ds_read_b128 v[246:249], v163 offset:3072
	v_readfirstlane_b32 s18, v165
	v_add_u32_e32 v134, 0x2000, v165
	v_lshl_add_u64 v[214:215], v[208:209], 0, s[56:57]
	s_mov_b32 m0, s18
	v_readfirstlane_b32 s18, v134
	global_load_lds_dwordx4 v[214:215], off
	v_lshl_add_u64 v[214:215], v[210:211], 0, s[56:57]
	s_mov_b32 m0, s18
	s_nop 0
	global_load_lds_dwordx4 v[214:215], off
	s_barrier
	s_waitcnt lgkmcnt(0)
	s_waitcnt lgkmcnt(0)
	v_mfma_f32_16x16x32_bf16 v[92:95], v[234:237], v[190:193], v[92:95]
	v_mfma_f32_16x16x32_bf16 v[88:91], v[242:245], v[190:193], v[88:91]
	v_mfma_f32_16x16x32_bf16 v[84:87], v[234:237], v[198:201], v[84:87]
	v_mfma_f32_16x16x32_bf16 v[80:83], v[242:245], v[198:201], v[80:83]
	v_mfma_f32_16x16x32_bf16 v[76:79], v[234:237], v[218:221], v[76:79]
	v_mfma_f32_16x16x32_bf16 v[72:75], v[242:245], v[218:221], v[72:75]
	v_mfma_f32_16x16x32_bf16 v[68:71], v[234:237], v[226:229], v[68:71]
	v_mfma_f32_16x16x32_bf16 v[64:67], v[242:245], v[226:229], v[64:67]
	v_mfma_f32_16x16x32_bf16 v[92:95], v[238:241], v[194:197], v[92:95]
	v_mfma_f32_16x16x32_bf16 v[88:91], v[246:249], v[194:197], v[88:91]
	v_mfma_f32_16x16x32_bf16 v[84:87], v[238:241], v[202:205], v[84:87]
	v_mfma_f32_16x16x32_bf16 v[80:83], v[246:249], v[202:205], v[80:83]
	v_mfma_f32_16x16x32_bf16 v[76:79], v[238:241], v[222:225], v[76:79]
	v_mfma_f32_16x16x32_bf16 v[72:75], v[246:249], v[222:225], v[72:75]
	v_mfma_f32_16x16x32_bf16 v[68:71], v[238:241], v[230:233], v[68:71]
	v_mfma_f32_16x16x32_bf16 v[64:67], v[246:249], v[230:233], v[64:67]
	v_readfirstlane_b32 s18, v166
	v_lshl_add_u64 v[136:137], v[136:137], 0, s[16:17]
	s_mov_b32 m0, s18
	v_readfirstlane_b32 s18, v167
	s_barrier
	ds_read_b128 v[190:193], v162 offset:49152
	ds_read_b128 v[194:197], v162 offset:50176
	ds_read_b128 v[198:201], v161 offset:49152
	ds_read_b128 v[202:205], v161 offset:50176
	ds_read_b128 v[218:221], v160 offset:49152
	ds_read_b128 v[222:225], v160 offset:50176
	ds_read_b128 v[226:229], v159 offset:49152
	ds_read_b128 v[230:233], v159 offset:50176
	global_load_lds_dwordx4 v[136:137], off
	v_lshl_add_u64 v[136:137], v[138:139], 0, s[16:17]
	s_mov_b32 m0, s18
	s_nop 0
	global_load_lds_dwordx4 v[136:137], off
	s_barrier
; #define STAGE(P, BASE, br, kt) STAGET(tid_, P, BASE, br, kt)
; #define LDA(dst, b, h) UFOR(m, 4) UFOR(k, 2) \
;     dst[m][k] = *reinterpret_cast<const bf16x8*>((char*)SA(b, h) + lds_byte(wr * 64 + m * 16 + fr, k * 32 + fq * 8))
; #define LDB(dst, b, h) UFOR(n, 2) UFOR(k, 2) \
;     dst[n][k] = *reinterpret_cast<const bf16x8*>((char*)SB(b, h) + lds_byte(wc * 32 + n * 16 + fr, k * 32 + fq * 8))
; #define MMA(ai, bj, At, Bq) do { __builtin_amdgcn_s_setprio(1); \
;     UFOR(m, 4) UFOR(n, 2) UFOR(k, 2) \
;       acc[ai][bj][m][n] = __builtin_amdgcn_mfma_f32_16x16x32_bf16(Bq[n][k], At[m][k], acc[ai][bj][m][n], 0, 0, 0); \
;     __builtin_amdgcn_s_setprio(0); } while (0)
; #define WAIT_V(n) asm volatile("s_waitcnt vmcnt(" #n ")" ::: "memory")
; #define WAIT_L(n) asm volatile("s_waitcnt lgkmcnt(" #n ")" ::: "memory")
; #define BAR __builtin_amdgcn_s_barrier()
; #define SCHED __builtin_amdgcn_sched_barrier(0)
; template <int EPI, int K, int KL> ...
;     ...
;     BAR; WAIT_L(0); MMA(1, 0, At, B0); BAR; SCHED;
;     STAGE(SB(1, 1), Bt, bcol + HALF, t + 3);
;     WAIT_V(6); BAR; MMA(1, 1, At, B1); BAR;
;   }
;   { LDB(B0, 0, 0); LDA(At, 0, 0); STAGE(SA(1, 1), A, brow + HALF, nt - 1);
;     BAR; WAIT_L(0); MMA(0, 0, At, B0); BAR;
;     LDB(B1, 0, 1); BAR; WAIT_L(0); MMA(0, 1, At, B1); BAR;
;     LDA(At, 0, 1); WAIT_V(4); BAR; WAIT_L(0); MMA(1, 0, At, B0); MMA(1, 1, At, B1); BAR; }
	s_waitcnt lgkmcnt(0)
	s_waitcnt lgkmcnt(0)
	v_mfma_f32_16x16x32_bf16 v[60:63], v[174:177], v[190:193], v[60:63]
	v_mfma_f32_16x16x32_bf16 v[56:59], v[182:185], v[190:193], v[56:59]
	v_mfma_f32_16x16x32_bf16 v[52:55], v[174:177], v[198:201], v[52:55]
	v_mfma_f32_16x16x32_bf16 v[48:51], v[182:185], v[198:201], v[48:51]
	v_mfma_f32_16x16x32_bf16 v[44:47], v[174:177], v[218:221], v[44:47]
	v_mfma_f32_16x16x32_bf16 v[40:43], v[182:185], v[218:221], v[40:43]
	v_mfma_f32_16x16x32_bf16 v[36:39], v[174:177], v[226:229], v[36:39]
	v_mfma_f32_16x16x32_bf16 v[32:35], v[182:185], v[226:229], v[32:35]
	v_mfma_f32_16x16x32_bf16 v[60:63], v[178:181], v[194:197], v[60:63]
	v_mfma_f32_16x16x32_bf16 v[56:59], v[186:189], v[194:197], v[56:59]
	v_mfma_f32_16x16x32_bf16 v[52:55], v[178:181], v[202:205], v[52:55]
	v_mfma_f32_16x16x32_bf16 v[48:51], v[186:189], v[202:205], v[48:51]
	v_mfma_f32_16x16x32_bf16 v[44:47], v[178:181], v[222:225], v[44:47]
	v_mfma_f32_16x16x32_bf16 v[40:43], v[186:189], v[222:225], v[40:43]
	v_mfma_f32_16x16x32_bf16 v[36:39], v[178:181], v[230:233], v[36:39]
	v_mfma_f32_16x16x32_bf16 v[32:35], v[186:189], v[230:233], v[32:35]
	s_barrier
	v_readfirstlane_b32 s18, v169
	v_add_u32_e32 v134, 0x2000, v169
	v_lshl_add_u64 v[136:137], v[208:209], 0, s[58:59]
	s_mov_b32 m0, s18
	v_readfirstlane_b32 s18, v134
	global_load_lds_dwordx4 v[136:137], off
	v_lshl_add_u64 v[136:137], v[210:211], 0, s[58:59]
	s_mov_b32 m0, s18
	s_nop 0
	global_load_lds_dwordx4 v[136:137], off
	s_waitcnt vmcnt(6)
	s_barrier
	v_mfma_f32_16x16x32_bf16 v[28:31], v[234:237], v[190:193], v[28:31]
	v_mfma_f32_16x16x32_bf16 v[24:27], v[242:245], v[190:193], v[24:27]
	v_mfma_f32_16x16x32_bf16 v[20:23], v[234:237], v[198:201], v[20:23]
	v_mfma_f32_16x16x32_bf16 v[16:19], v[242:245], v[198:201], v[16:19]
	v_mfma_f32_16x16x32_bf16 v[12:15], v[234:237], v[218:221], v[12:15]
	v_mfma_f32_16x16x32_bf16 v[8:11], v[242:245], v[218:221], v[8:11]
	v_mfma_f32_16x16x32_bf16 v[4:7], v[234:237], v[226:229], v[4:7]
	v_mfma_f32_16x16x32_bf16 v[0:3], v[242:245], v[226:229], v[0:3]
	v_mfma_f32_16x16x32_bf16 v[28:31], v[238:241], v[194:197], v[28:31]
	v_mfma_f32_16x16x32_bf16 v[24:27], v[246:249], v[194:197], v[24:27]
	v_mfma_f32_16x16x32_bf16 v[20:23], v[238:241], v[202:205], v[20:23]
	v_mfma_f32_16x16x32_bf16 v[16:19], v[246:249], v[202:205], v[16:19]
	v_mfma_f32_16x16x32_bf16 v[12:15], v[238:241], v[222:225], v[12:15]
	v_mfma_f32_16x16x32_bf16 v[8:11], v[246:249], v[222:225], v[8:11]
	v_mfma_f32_16x16x32_bf16 v[4:7], v[238:241], v[230:233], v[4:7]
	v_mfma_f32_16x16x32_bf16 v[0:3], v[246:249], v[230:233], v[0:3]
	s_add_i32 s15, s15, 2
	v_lshl_add_u64 v[146:147], v[146:147], 0, s[20:21]
	v_lshl_add_u64 v[148:149], v[148:149], 0, s[20:21]
	v_lshl_add_u64 v[150:151], v[150:151], 0, s[20:21]
	s_cmp_lt_u32 s15, 28
	v_lshl_add_u64 v[152:153], v[152:153], 0, s[20:21]
	s_cbranch_scc1 .Lkrot_236
	s_barrier
	s_add_u32 s18, s50, 0x80f80
	s_addc_u32 s19, s51, 0
	v_lshl_add_u64 v[136:137], s[18:19], 0, v[140:141]
	v_readfirstlane_b32 s15, v171
	v_lshl_add_u64 v[130:131], v[130:131], 1, v[136:137]
	s_mov_b32 m0, s15
	ds_read_b128 v[146:149], v170
	ds_read_b128 v[150:153], v170 offset:1024
	ds_read_b128 v[174:177], v170 offset:2048
	ds_read_b128 v[178:181], v170 offset:3072
	ds_read_b128 v[182:185], v162
	ds_read_b128 v[186:189], v162 offset:1024
	ds_read_b128 v[190:193], v161
	ds_read_b128 v[194:197], v161 offset:1024
	ds_read_b128 v[198:201], v160
	ds_read_b128 v[202:205], v160 offset:1024
	ds_read_b128 v[218:221], v159
	ds_read_b128 v[222:225], v159 offset:1024
	global_load_lds_dwordx4 v[130:131], off
	v_lshl_add_u64 v[130:131], s[18:19], 0, v[144:145]
	v_readfirstlane_b32 s15, v172
	v_lshl_add_u64 v[130:131], v[142:143], 1, v[130:131]
	s_mov_b32 m0, s15
	s_nop 0
	global_load_lds_dwordx4 v[130:131], off
	s_barrier
	s_waitcnt lgkmcnt(0)
	s_waitcnt lgkmcnt(0)
	v_mfma_f32_16x16x32_bf16 v[124:127], v[146:149], v[182:185], v[124:127]
	v_mfma_f32_16x16x32_bf16 v[120:123], v[174:177], v[182:185], v[120:123]
	v_mfma_f32_16x16x32_bf16 v[116:119], v[146:149], v[190:193], v[116:119]
	v_mfma_f32_16x16x32_bf16 v[112:115], v[174:177], v[190:193], v[112:115]
	v_mfma_f32_16x16x32_bf16 v[108:111], v[146:149], v[198:201], v[108:111]
	v_mfma_f32_16x16x32_bf16 v[104:107], v[174:177], v[198:201], v[104:107]
	v_mfma_f32_16x16x32_bf16 v[100:103], v[146:149], v[218:221], v[100:103]
	v_mfma_f32_16x16x32_bf16 v[96:99], v[174:177], v[218:221], v[96:99]
	v_mfma_f32_16x16x32_bf16 v[124:127], v[150:153], v[186:189], v[124:127]
	v_mfma_f32_16x16x32_bf16 v[120:123], v[178:181], v[186:189], v[120:123]
	v_mfma_f32_16x16x32_bf16 v[116:119], v[150:153], v[194:197], v[116:119]
	v_mfma_f32_16x16x32_bf16 v[112:115], v[178:181], v[194:197], v[112:115]
	v_mfma_f32_16x16x32_bf16 v[108:111], v[150:153], v[202:205], v[108:111]
	v_mfma_f32_16x16x32_bf16 v[104:107], v[178:181], v[202:205], v[104:107]
	v_mfma_f32_16x16x32_bf16 v[100:103], v[150:153], v[222:225], v[100:103]
	v_mfma_f32_16x16x32_bf16 v[96:99], v[178:181], v[222:225], v[96:99]
	s_barrier
	ds_read_b128 v[140:143], v168
	ds_read_b128 v[170:173], v168 offset:1024
	ds_read_b128 v[226:229], v168 offset:2048
	ds_read_b128 v[166:169], v168 offset:3072
	s_barrier
; #define LDA(dst, b, h) UFOR(m, 4) UFOR(k, 2) \
;     dst[m][k] = *reinterpret_cast<const bf16x8*>((char*)SA(b, h) + lds_byte(wr * 64 + m * 16 + fr, k * 32 + fq * 8))
; #define LDB(dst, b, h) UFOR(n, 2) UFOR(k, 2) \
;     dst[n][k] = *reinterpret_cast<const bf16x8*>((char*)SB(b, h) + lds_byte(wc * 32 + n * 16 + fr, k * 32 + fq * 8))
; #define MMA(ai, bj, At, Bq) do { __builtin_amdgcn_s_setprio(1); \
;     UFOR(m, 4) UFOR(n, 2) UFOR(k, 2) \
;       acc[ai][bj][m][n] = __builtin_amdgcn_mfma_f32_16x16x32_bf16(Bq[n][k], At[m][k], acc[ai][bj][m][n], 0, 0, 0); \
;     __builtin_amdgcn_s_setprio(0); } while (0)
; #define WAIT_V(n) asm volatile("s_waitcnt vmcnt(" #n ")" ::: "memory")
; #define WAIT_L(n) asm volatile("s_waitcnt lgkmcnt(" #n ")" ::: "memory")
; #define BAR __builtin_amdgcn_s_barrier()
; template <int EPI, int K, int KL> ...
;     ...
;     BAR; WAIT_L(0); MMA(0, 0, At, B0); BAR;
;     LDB(B1, 0, 1); BAR; WAIT_L(0); MMA(0, 1, At, B1); BAR;
;     LDA(At, 0, 1); WAIT_V(4); BAR; WAIT_L(0); MMA(1, 0, At, B0); MMA(1, 1, At, B1); BAR; }
;   { LDB(B0, 1, 0); LDA(At, 1, 0); WAIT_V(2); BAR; WAIT_L(0); MMA(0, 0, At, B0); BAR;
;     LDB(B1, 1, 1); WAIT_V(0); BAR; WAIT_L(0); MMA(0, 1, At, B1); BAR;
	s_waitcnt lgkmcnt(0)
	s_waitcnt lgkmcnt(0)
	v_mfma_f32_16x16x32_bf16 v[92:95], v[140:143], v[182:185], v[92:95]
	v_mfma_f32_16x16x32_bf16 v[88:91], v[226:229], v[182:185], v[88:91]
	v_mfma_f32_16x16x32_bf16 v[84:87], v[140:143], v[190:193], v[84:87]
	v_mfma_f32_16x16x32_bf16 v[80:83], v[226:229], v[190:193], v[80:83]
	v_mfma_f32_16x16x32_bf16 v[76:79], v[140:143], v[198:201], v[76:79]
	v_mfma_f32_16x16x32_bf16 v[72:75], v[226:229], v[198:201], v[72:75]
	v_mfma_f32_16x16x32_bf16 v[68:71], v[140:143], v[218:221], v[68:71]
	v_mfma_f32_16x16x32_bf16 v[64:67], v[226:229], v[218:221], v[64:67]
	v_mfma_f32_16x16x32_bf16 v[92:95], v[170:173], v[186:189], v[92:95]
	v_mfma_f32_16x16x32_bf16 v[88:91], v[166:169], v[186:189], v[88:91]
	v_mfma_f32_16x16x32_bf16 v[84:87], v[170:173], v[194:197], v[84:87]
	v_mfma_f32_16x16x32_bf16 v[80:83], v[166:169], v[194:197], v[80:83]
	v_mfma_f32_16x16x32_bf16 v[76:79], v[170:173], v[202:205], v[76:79]
	v_mfma_f32_16x16x32_bf16 v[72:75], v[166:169], v[202:205], v[72:75]
	v_mfma_f32_16x16x32_bf16 v[68:71], v[170:173], v[222:225], v[68:71]
	v_mfma_f32_16x16x32_bf16 v[64:67], v[166:169], v[222:225], v[64:67]
	s_barrier
	ds_read_b128 v[182:185], v162 offset:16384
	ds_read_b128 v[186:189], v162 offset:17408
	ds_read_b128 v[190:193], v161 offset:16384
	ds_read_b128 v[194:197], v161 offset:17408
	ds_read_b128 v[198:201], v160 offset:16384
	ds_read_b128 v[202:205], v160 offset:17408
	ds_read_b128 v[218:221], v159 offset:16384
	ds_read_b128 v[222:225], v159 offset:17408
	s_waitcnt vmcnt(4)
	s_barrier
	s_waitcnt lgkmcnt(0)
	s_waitcnt lgkmcnt(0)
	v_mfma_f32_16x16x32_bf16 v[60:63], v[146:149], v[182:185], v[60:63]
	v_mfma_f32_16x16x32_bf16 v[56:59], v[174:177], v[182:185], v[56:59]
	v_mfma_f32_16x16x32_bf16 v[52:55], v[146:149], v[190:193], v[52:55]
	v_mfma_f32_16x16x32_bf16 v[48:51], v[174:177], v[190:193], v[48:51]
	v_mfma_f32_16x16x32_bf16 v[44:47], v[146:149], v[198:201], v[44:47]
	v_mfma_f32_16x16x32_bf16 v[40:43], v[174:177], v[198:201], v[40:43]
	v_mfma_f32_16x16x32_bf16 v[36:39], v[146:149], v[218:221], v[36:39]
	v_mfma_f32_16x16x32_bf16 v[32:35], v[174:177], v[218:221], v[32:35]
	v_mfma_f32_16x16x32_bf16 v[60:63], v[150:153], v[186:189], v[60:63]
	v_mfma_f32_16x16x32_bf16 v[56:59], v[178:181], v[186:189], v[56:59]
	v_mfma_f32_16x16x32_bf16 v[52:55], v[150:153], v[194:197], v[52:55]
	v_mfma_f32_16x16x32_bf16 v[48:51], v[178:181], v[194:197], v[48:51]
	v_mfma_f32_16x16x32_bf16 v[44:47], v[150:153], v[202:205], v[44:47]
	v_mfma_f32_16x16x32_bf16 v[40:43], v[178:181], v[202:205], v[40:43]
	v_mfma_f32_16x16x32_bf16 v[36:39], v[150:153], v[222:225], v[36:39]
	v_mfma_f32_16x16x32_bf16 v[32:35], v[178:181], v[222:225], v[32:35]
	v_mfma_f32_16x16x32_bf16 v[28:31], v[140:143], v[182:185], v[28:31]
	v_mfma_f32_16x16x32_bf16 v[24:27], v[226:229], v[182:185], v[24:27]
	v_mfma_f32_16x16x32_bf16 v[20:23], v[140:143], v[190:193], v[20:23]
	v_mfma_f32_16x16x32_bf16 v[16:19], v[226:229], v[190:193], v[16:19]
	v_mfma_f32_16x16x32_bf16 v[12:15], v[140:143], v[198:201], v[12:15]
	v_mfma_f32_16x16x32_bf16 v[8:11], v[226:229], v[198:201], v[8:11]
	v_mfma_f32_16x16x32_bf16 v[4:7], v[140:143], v[218:221], v[4:7]
	v_mfma_f32_16x16x32_bf16 v[0:3], v[226:229], v[218:221], v[0:3]
	v_mfma_f32_16x16x32_bf16 v[28:31], v[170:173], v[186:189], v[28:31]
	v_mfma_f32_16x16x32_bf16 v[24:27], v[166:169], v[186:189], v[24:27]
	v_mfma_f32_16x16x32_bf16 v[20:23], v[170:173], v[194:197], v[20:23]
	v_mfma_f32_16x16x32_bf16 v[16:19], v[166:169], v[194:197], v[16:19]
	v_mfma_f32_16x16x32_bf16 v[12:15], v[170:173], v[202:205], v[12:15]
	v_mfma_f32_16x16x32_bf16 v[8:11], v[166:169], v[202:205], v[8:11]
	v_mfma_f32_16x16x32_bf16 v[4:7], v[170:173], v[222:225], v[4:7]
	v_mfma_f32_16x16x32_bf16 v[0:3], v[166:169], v[222:225], v[0:3]
	s_barrier
	ds_read_b128 v[140:143], v164
	ds_read_b128 v[144:147], v164 offset:1024
	ds_read_b128 v[148:151], v164 offset:2048
	ds_read_b128 v[164:167], v164 offset:3072
	ds_read_b128 v[168:171], v162 offset:32768
	ds_read_b128 v[172:175], v162 offset:33792
	ds_read_b128 v[176:179], v161 offset:32768
	ds_read_b128 v[180:183], v161 offset:33792
	ds_read_b128 v[184:187], v160 offset:32768
	ds_read_b128 v[188:191], v160 offset:33792
	ds_read_b128 v[192:195], v159 offset:32768
	ds_read_b128 v[196:199], v159 offset:33792
	s_waitcnt vmcnt(2)
	s_barrier
; #define LDA(dst, b, h) UFOR(m, 4) UFOR(k, 2) \
;     dst[m][k] = *reinterpret_cast<const bf16x8*>((char*)SA(b, h) + lds_byte(wr * 64 + m * 16 + fr, k * 32 + fq * 8))
; #define LDB(dst, b, h) UFOR(n, 2) UFOR(k, 2) \
;     dst[n][k] = *reinterpret_cast<const bf16x8*>((char*)SB(b, h) + lds_byte(wc * 32 + n * 16 + fr, k * 32 + fq * 8))
; #define MMA(ai, bj, At, Bq) do { __builtin_amdgcn_s_setprio(1); \
;     UFOR(m, 4) UFOR(n, 2) UFOR(k, 2) \
;       acc[ai][bj][m][n] = __builtin_amdgcn_mfma_f32_16x16x32_bf16(Bq[n][k], At[m][k], acc[ai][bj][m][n], 0, 0, 0); \
;     __builtin_amdgcn_s_setprio(0); } while (0)
; #define WAIT_V(n) asm volatile("s_waitcnt vmcnt(" #n ")" ::: "memory")
; #define WAIT_L(n) asm volatile("s_waitcnt lgkmcnt(" #n ")" ::: "memory")
; #define BAR __builtin_amdgcn_s_barrier()
; template <int EPI, int K, int KL> ...
;     ...
;   { LDB(B0, 1, 0); LDA(At, 1, 0); WAIT_V(2); BAR; WAIT_L(0); MMA(0, 0, At, B0); BAR;
;     LDB(B1, 1, 1); WAIT_V(0); BAR; WAIT_L(0); MMA(0, 1, At, B1); BAR;
;     LDA(At, 1, 1); BAR; WAIT_L(0); MMA(1, 0, At, B0); MMA(1, 1, At, B1); BAR; }
;   if (wr == 0) BAR;
	s_waitcnt lgkmcnt(0)
	s_waitcnt lgkmcnt(0)
	v_mfma_f32_16x16x32_bf16 v[124:127], v[140:143], v[168:171], v[124:127]
	v_mfma_f32_16x16x32_bf16 v[120:123], v[148:151], v[168:171], v[120:123]
	v_mfma_f32_16x16x32_bf16 v[116:119], v[140:143], v[176:179], v[116:119]
	v_mfma_f32_16x16x32_bf16 v[112:115], v[148:151], v[176:179], v[112:115]
	v_mfma_f32_16x16x32_bf16 v[108:111], v[140:143], v[184:187], v[108:111]
	v_mfma_f32_16x16x32_bf16 v[104:107], v[148:151], v[184:187], v[104:107]
	v_mfma_f32_16x16x32_bf16 v[100:103], v[140:143], v[192:195], v[100:103]
	v_mfma_f32_16x16x32_bf16 v[96:99], v[148:151], v[192:195], v[96:99]
	v_mfma_f32_16x16x32_bf16 v[124:127], v[144:147], v[172:175], v[124:127]
	v_mfma_f32_16x16x32_bf16 v[120:123], v[164:167], v[172:175], v[120:123]
	v_mfma_f32_16x16x32_bf16 v[116:119], v[144:147], v[180:183], v[116:119]
	v_mfma_f32_16x16x32_bf16 v[112:115], v[164:167], v[180:183], v[112:115]
	v_mfma_f32_16x16x32_bf16 v[108:111], v[144:147], v[188:191], v[108:111]
	v_mfma_f32_16x16x32_bf16 v[104:107], v[164:167], v[188:191], v[104:107]
	v_mfma_f32_16x16x32_bf16 v[100:103], v[144:147], v[196:199], v[100:103]
	v_mfma_f32_16x16x32_bf16 v[96:99], v[164:167], v[196:199], v[96:99]
	s_barrier
	ds_read_b128 v[200:203], v163
	ds_read_b128 v[218:221], v163 offset:1024
	ds_read_b128 v[222:225], v163 offset:2048
	ds_read_b128 v[226:229], v163 offset:3072
	s_waitcnt vmcnt(0)
	s_barrier
	s_waitcnt lgkmcnt(0)
	s_waitcnt lgkmcnt(0)
	v_mfma_f32_16x16x32_bf16 v[92:95], v[200:203], v[168:171], v[92:95]
	v_mfma_f32_16x16x32_bf16 v[88:91], v[222:225], v[168:171], v[88:91]
	v_mfma_f32_16x16x32_bf16 v[84:87], v[200:203], v[176:179], v[84:87]
	v_mfma_f32_16x16x32_bf16 v[80:83], v[222:225], v[176:179], v[80:83]
	v_mfma_f32_16x16x32_bf16 v[76:79], v[200:203], v[184:187], v[76:79]
	v_mfma_f32_16x16x32_bf16 v[72:75], v[222:225], v[184:187], v[72:75]
	v_mfma_f32_16x16x32_bf16 v[68:71], v[200:203], v[192:195], v[68:71]
	v_mfma_f32_16x16x32_bf16 v[64:67], v[222:225], v[192:195], v[64:67]
	v_mfma_f32_16x16x32_bf16 v[92:95], v[218:221], v[172:175], v[92:95]
	v_mfma_f32_16x16x32_bf16 v[88:91], v[226:229], v[172:175], v[88:91]
	v_mfma_f32_16x16x32_bf16 v[84:87], v[218:221], v[180:183], v[84:87]
	v_mfma_f32_16x16x32_bf16 v[80:83], v[226:229], v[180:183], v[80:83]
	v_mfma_f32_16x16x32_bf16 v[76:79], v[218:221], v[188:191], v[76:79]
	v_mfma_f32_16x16x32_bf16 v[72:75], v[226:229], v[188:191], v[72:75]
	v_mfma_f32_16x16x32_bf16 v[68:71], v[218:221], v[196:199], v[68:71]
	v_mfma_f32_16x16x32_bf16 v[64:67], v[226:229], v[196:199], v[64:67]
	s_barrier
	ds_read_b128 v[168:171], v162 offset:49152
	ds_read_b128 v[172:175], v162 offset:50176
	ds_read_b128 v[176:179], v161 offset:49152
	ds_read_b128 v[180:183], v161 offset:50176
	ds_read_b128 v[184:187], v160 offset:49152
	ds_read_b128 v[160:163], v160 offset:50176
	ds_read_b128 v[188:191], v159 offset:49152
	ds_read_b128 v[156:159], v159 offset:50176
	s_barrier
	s_waitcnt lgkmcnt(0)
	s_waitcnt lgkmcnt(0)
	v_mfma_f32_16x16x32_bf16 v[60:63], v[140:143], v[168:171], v[60:63]
	v_mfma_f32_16x16x32_bf16 v[56:59], v[148:151], v[168:171], v[56:59]
	v_mfma_f32_16x16x32_bf16 v[52:55], v[140:143], v[176:179], v[52:55]
	v_mfma_f32_16x16x32_bf16 v[48:51], v[148:151], v[176:179], v[48:51]
	v_mfma_f32_16x16x32_bf16 v[44:47], v[140:143], v[184:187], v[44:47]
	v_mfma_f32_16x16x32_bf16 v[40:43], v[148:151], v[184:187], v[40:43]
	v_mfma_f32_16x16x32_bf16 v[36:39], v[140:143], v[188:191], v[36:39]
	v_mfma_f32_16x16x32_bf16 v[32:35], v[148:151], v[188:191], v[32:35]
	v_mfma_f32_16x16x32_bf16 v[60:63], v[144:147], v[172:175], v[60:63]
	v_mfma_f32_16x16x32_bf16 v[56:59], v[164:167], v[172:175], v[56:59]
	v_mfma_f32_16x16x32_bf16 v[52:55], v[144:147], v[180:183], v[52:55]
	v_mfma_f32_16x16x32_bf16 v[48:51], v[164:167], v[180:183], v[48:51]
	v_mfma_f32_16x16x32_bf16 v[44:47], v[144:147], v[160:163], v[44:47]
	v_mfma_f32_16x16x32_bf16 v[40:43], v[164:167], v[160:163], v[40:43]
	v_mfma_f32_16x16x32_bf16 v[36:39], v[144:147], v[156:159], v[36:39]
	v_mfma_f32_16x16x32_bf16 v[32:35], v[164:167], v[156:159], v[32:35]
	v_mfma_f32_16x16x32_bf16 v[28:31], v[200:203], v[168:171], v[28:31]
	v_mfma_f32_16x16x32_bf16 v[24:27], v[222:225], v[168:171], v[24:27]
	v_mfma_f32_16x16x32_bf16 v[20:23], v[200:203], v[176:179], v[20:23]
	v_mfma_f32_16x16x32_bf16 v[16:19], v[222:225], v[176:179], v[16:19]
	v_mfma_f32_16x16x32_bf16 v[12:15], v[200:203], v[184:187], v[12:15]
	v_mfma_f32_16x16x32_bf16 v[8:11], v[222:225], v[184:187], v[8:11]
	v_mfma_f32_16x16x32_bf16 v[4:7], v[200:203], v[188:191], v[4:7]
	v_mfma_f32_16x16x32_bf16 v[0:3], v[222:225], v[188:191], v[0:3]
	v_mfma_f32_16x16x32_bf16 v[28:31], v[218:221], v[172:175], v[28:31]
	v_mfma_f32_16x16x32_bf16 v[24:27], v[226:229], v[172:175], v[24:27]
	v_mfma_f32_16x16x32_bf16 v[20:23], v[218:221], v[180:183], v[20:23]
	v_mfma_f32_16x16x32_bf16 v[16:19], v[226:229], v[180:183], v[16:19]
	v_mfma_f32_16x16x32_bf16 v[12:15], v[218:221], v[160:163], v[12:15]
	v_mfma_f32_16x16x32_bf16 v[8:11], v[226:229], v[160:163], v[8:11]
	v_mfma_f32_16x16x32_bf16 v[4:7], v[218:221], v[156:159], v[4:7]
	v_mfma_f32_16x16x32_bf16 v[0:3], v[226:229], v[156:159], v[0:3]
	s_movk_i32 s15, 0x100
	v_cmp_gt_u32_e32 vcc, s15, v129
	s_barrier
	s_and_saveexec_b64 s[50:51], vcc
	s_cbranch_execz .LBB0_239
	s_barrier

; #define STAGE(P, BASE, br, kt) STAGET(tid_, P, BASE, br, kt)
; #define LDA(dst, b, h) UFOR(m, 4) UFOR(k, 2) \
;     dst[m][k] = *reinterpret_cast<const bf16x8*>((char*)SA(b, h) + lds_byte(wr * 64 + m * 16 + fr, k * 32 + fq * 8))
; #define LDB(dst, b, h) UFOR(n, 2) UFOR(k, 2) \
;     dst[n][k] = *reinterpret_cast<const bf16x8*>((char*)SB(b, h) + lds_byte(wc * 32 + n * 16 + fr, k * 32 + fq * 8))
; #define MMA(ai, bj, At, Bq) do { __builtin_amdgcn_s_setprio(1); \
;     UFOR(m, 4) UFOR(n, 2) UFOR(k, 2) \
;       acc[ai][bj][m][n] = __builtin_amdgcn_mfma_f32_16x16x32_bf16(Bq[n][k], At[m][k], acc[ai][bj][m][n], 0, 0, 0); \
;     __builtin_amdgcn_s_setprio(0); } while (0)
; #define WAIT_V(n) asm volatile("s_waitcnt vmcnt(" #n ")" ::: "memory")
; #define WAIT_L(n) asm volatile("s_waitcnt lgkmcnt(" #n ")" ::: "memory")
; #define BAR __builtin_amdgcn_s_barrier()
; #define SCHED __builtin_amdgcn_sched_barrier(0)
; template <int EPI, int K, int KL> ...
;     ...
;   for (int t = 0; t < nt - 2; t += 2) {
;     LDB(B0, 0, 0); SCHED; LDA(At, 0, 0); STAGE(SA(1, 1), A, brow + HALF, t + 1);
;     WAIT_L(8); BAR; WAIT_L(0); MMA(0, 0, At, B0); BAR; SCHED;
;     LDB(B1, 0, 1); STAGE(SB(0, 0), Bt, bcol, t + 2);
;     BAR; WAIT_L(0); MMA(0, 1, At, B1); BAR;
;     LDA(At, 0, 1); STAGE(SA(0, 0), A, brow, t + 2);
;     BAR; WAIT_L(0); MMA(1, 0, At, B0); BAR; SCHED;
;     STAGE(SB(0, 1), Bt, bcol + HALF, t + 2);
;     WAIT_V(6); BAR; MMA(1, 1, At, B1); BAR;
;     LDB(B0, 1, 0); SCHED; LDA(At, 1, 0); STAGE(SA(0, 1), A, brow + HALF, t + 2);
;     WAIT_L(8); BAR; WAIT_L(0); MMA(0, 0, At, B0); BAR; SCHED;
.LBB0_940:
	ds_read_b128 v[174:177], v170
	ds_read_b128 v[178:181], v170 offset:1024
	ds_read_b128 v[182:185], v170 offset:2048
	ds_read_b128 v[186:189], v170 offset:3072
	ds_read_b128 v[190:193], v162
	ds_read_b128 v[194:197], v162 offset:1024
	ds_read_b128 v[198:201], v161
	ds_read_b128 v[202:205], v161 offset:1024
	ds_read_b128 v[218:221], v160
	ds_read_b128 v[222:225], v160 offset:1024
	ds_read_b128 v[226:229], v159
	ds_read_b128 v[230:233], v159 offset:1024
	v_add_u32_e32 v171, 0xc000, v157
	v_lshl_add_u64 v[136:137], s[92:93], 0, v[148:149]
	v_readfirstlane_b32 s60, v171
	v_lshl_add_u64 v[138:139], v[136:137], 0, s[88:89]
	s_mov_b32 m0, s60
	v_add_u32_e32 v172, 0xe000, v157
	global_load_lds_dwordx4 v[138:139], off
	v_lshl_add_u64 v[138:139], s[92:93], 0, v[150:151]
	v_readfirstlane_b32 s60, v172
	v_lshl_add_u64 v[208:209], v[138:139], 0, s[88:89]
	s_mov_b32 m0, s60
	s_nop 0
	global_load_lds_dwordx4 v[208:209], off
	s_waitcnt lgkmcnt(8)
	s_barrier
	s_waitcnt lgkmcnt(0)
	s_waitcnt lgkmcnt(0)
	v_mfma_f32_16x16x32_bf16 v[124:127], v[174:177], v[190:193], v[124:127]
	v_mfma_f32_16x16x32_bf16 v[120:123], v[182:185], v[190:193], v[120:123]
	v_mfma_f32_16x16x32_bf16 v[116:119], v[174:177], v[198:201], v[116:119]
	v_mfma_f32_16x16x32_bf16 v[112:115], v[182:185], v[198:201], v[112:115]
	v_mfma_f32_16x16x32_bf16 v[108:111], v[174:177], v[218:221], v[108:111]
	v_mfma_f32_16x16x32_bf16 v[104:107], v[182:185], v[218:221], v[104:107]
	v_mfma_f32_16x16x32_bf16 v[100:103], v[174:177], v[226:229], v[100:103]
	v_mfma_f32_16x16x32_bf16 v[96:99], v[182:185], v[226:229], v[96:99]
	v_mfma_f32_16x16x32_bf16 v[124:127], v[178:181], v[194:197], v[124:127]
	v_mfma_f32_16x16x32_bf16 v[120:123], v[186:189], v[194:197], v[120:123]
	v_mfma_f32_16x16x32_bf16 v[116:119], v[178:181], v[202:205], v[116:119]
	v_mfma_f32_16x16x32_bf16 v[112:115], v[186:189], v[202:205], v[112:115]
	v_mfma_f32_16x16x32_bf16 v[108:111], v[178:181], v[222:225], v[108:111]
	v_mfma_f32_16x16x32_bf16 v[104:107], v[186:189], v[222:225], v[104:107]
	v_mfma_f32_16x16x32_bf16 v[100:103], v[178:181], v[230:233], v[100:103]
	v_mfma_f32_16x16x32_bf16 v[96:99], v[186:189], v[230:233], v[96:99]
	s_barrier
	ds_read_b128 v[234:237], v168
	ds_read_b128 v[238:241], v168 offset:1024
	ds_read_b128 v[242:245], v168 offset:2048
	ds_read_b128 v[246:249], v168 offset:3072
	v_lshl_add_u64 v[208:209], s[92:93], 0, v[144:145]
	v_readfirstlane_b32 s60, v156
	v_lshl_add_u64 v[210:211], v[208:209], 0, s[62:63]
	s_mov_b32 m0, s60
	v_add_u32_e32 v134, 0x2000, v156
	global_load_lds_dwordx4 v[210:211], off
	v_lshl_add_u64 v[210:211], s[92:93], 0, v[146:147]
	v_readfirstlane_b32 s60, v134
	v_lshl_add_u64 v[214:215], v[210:211], 0, s[62:63]
	s_mov_b32 m0, s60
	s_nop 0
	global_load_lds_dwordx4 v[214:215], off
	s_barrier
	s_waitcnt lgkmcnt(0)
	s_waitcnt lgkmcnt(0)
	v_mfma_f32_16x16x32_bf16 v[92:95], v[234:237], v[190:193], v[92:95]
	v_mfma_f32_16x16x32_bf16 v[88:91], v[242:245], v[190:193], v[88:91]
	v_mfma_f32_16x16x32_bf16 v[84:87], v[234:237], v[198:201], v[84:87]
	v_mfma_f32_16x16x32_bf16 v[80:83], v[242:245], v[198:201], v[80:83]
	v_mfma_f32_16x16x32_bf16 v[76:79], v[234:237], v[218:221], v[76:79]
	v_mfma_f32_16x16x32_bf16 v[72:75], v[242:245], v[218:221], v[72:75]
	v_mfma_f32_16x16x32_bf16 v[68:71], v[234:237], v[226:229], v[68:71]
	v_mfma_f32_16x16x32_bf16 v[64:67], v[242:245], v[226:229], v[64:67]
	v_mfma_f32_16x16x32_bf16 v[92:95], v[238:241], v[194:197], v[92:95]
	v_mfma_f32_16x16x32_bf16 v[88:91], v[246:249], v[194:197], v[88:91]
	v_mfma_f32_16x16x32_bf16 v[84:87], v[238:241], v[202:205], v[84:87]
	v_mfma_f32_16x16x32_bf16 v[80:83], v[246:249], v[202:205], v[80:83]
	v_mfma_f32_16x16x32_bf16 v[76:79], v[238:241], v[222:225], v[76:79]
	v_mfma_f32_16x16x32_bf16 v[72:75], v[246:249], v[222:225], v[72:75]
	v_mfma_f32_16x16x32_bf16 v[68:71], v[238:241], v[230:233], v[68:71]
	v_mfma_f32_16x16x32_bf16 v[64:67], v[246:249], v[230:233], v[64:67]
	v_readfirstlane_b32 s60, v157
	v_add_u32_e32 v134, 0x2000, v157
	v_lshl_add_u64 v[214:215], v[136:137], 0, s[8:9]
	s_mov_b32 m0, s60
	v_readfirstlane_b32 s60, v134
	s_barrier
	ds_read_b128 v[190:193], v162 offset:16384
	ds_read_b128 v[194:197], v162 offset:17408
	ds_read_b128 v[198:201], v161 offset:16384
	ds_read_b128 v[202:205], v161 offset:17408
	ds_read_b128 v[218:221], v160 offset:16384
	ds_read_b128 v[222:225], v160 offset:17408
	ds_read_b128 v[226:229], v159 offset:16384
	ds_read_b128 v[230:233], v159 offset:17408
	global_load_lds_dwordx4 v[214:215], off
	v_lshl_add_u64 v[214:215], v[138:139], 0, s[8:9]
	s_mov_b32 m0, s60
	s_nop 0
	global_load_lds_dwordx4 v[214:215], off
	s_barrier
	s_waitcnt lgkmcnt(0)
	s_waitcnt lgkmcnt(0)
	v_mfma_f32_16x16x32_bf16 v[60:63], v[174:177], v[190:193], v[60:63]
	v_mfma_f32_16x16x32_bf16 v[56:59], v[182:185], v[190:193], v[56:59]
	v_mfma_f32_16x16x32_bf16 v[52:55], v[174:177], v[198:201], v[52:55]
	v_mfma_f32_16x16x32_bf16 v[48:51], v[182:185], v[198:201], v[48:51]
	v_mfma_f32_16x16x32_bf16 v[44:47], v[174:177], v[218:221], v[44:47]
	v_mfma_f32_16x16x32_bf16 v[40:43], v[182:185], v[218:221], v[40:43]
	v_mfma_f32_16x16x32_bf16 v[36:39], v[174:177], v[226:229], v[36:39]
	v_mfma_f32_16x16x32_bf16 v[32:35], v[182:185], v[226:229], v[32:35]
	v_mfma_f32_16x16x32_bf16 v[60:63], v[178:181], v[194:197], v[60:63]
	v_mfma_f32_16x16x32_bf16 v[56:59], v[186:189], v[194:197], v[56:59]
	v_mfma_f32_16x16x32_bf16 v[52:55], v[178:181], v[202:205], v[52:55]
	v_mfma_f32_16x16x32_bf16 v[48:51], v[186:189], v[202:205], v[48:51]
	v_mfma_f32_16x16x32_bf16 v[44:47], v[178:181], v[222:225], v[44:47]
	v_mfma_f32_16x16x32_bf16 v[40:43], v[186:189], v[222:225], v[40:43]
	v_mfma_f32_16x16x32_bf16 v[36:39], v[178:181], v[230:233], v[36:39]
	v_mfma_f32_16x16x32_bf16 v[32:35], v[186:189], v[230:233], v[32:35]
	s_barrier
; #define STAGE(P, BASE, br, kt) STAGET(tid_, P, BASE, br, kt)
; #define LDA(dst, b, h) UFOR(m, 4) UFOR(k, 2) \
;     dst[m][k] = *reinterpret_cast<const bf16x8*>((char*)SA(b, h) + lds_byte(wr * 64 + m * 16 + fr, k * 32 + fq * 8))
; #define LDB(dst, b, h) UFOR(n, 2) UFOR(k, 2) \
;     dst[n][k] = *reinterpret_cast<const bf16x8*>((char*)SB(b, h) + lds_byte(wc * 32 + n * 16 + fr, k * 32 + fq * 8))
; #define MMA(ai, bj, At, Bq) do { __builtin_amdgcn_s_setprio(1); \
;     UFOR(m, 4) UFOR(n, 2) UFOR(k, 2) \
;       acc[ai][bj][m][n] = __builtin_amdgcn_mfma_f32_16x16x32_bf16(Bq[n][k], At[m][k], acc[ai][bj][m][n], 0, 0, 0); \
;     __builtin_amdgcn_s_setprio(0); } while (0)
; #define WAIT_V(n) asm volatile("s_waitcnt vmcnt(" #n ")" ::: "memory")
; #define WAIT_L(n) asm volatile("s_waitcnt lgkmcnt(" #n ")" ::: "memory")
; #define BAR __builtin_amdgcn_s_barrier()
; #define SCHED __builtin_amdgcn_sched_barrier(0)
; template <int EPI, int K, int KL> ...
;     ...
;     WAIT_V(6); BAR; MMA(1, 1, At, B1); BAR;
;     LDB(B0, 1, 0); SCHED; LDA(At, 1, 0); STAGE(SA(0, 1), A, brow + HALF, t + 2);
;     WAIT_L(8); BAR; WAIT_L(0); MMA(0, 0, At, B0); BAR; SCHED;
;     LDB(B1, 1, 1); STAGE(SB(1, 0), Bt, bcol, t + 3);
;     BAR; WAIT_L(0); MMA(0, 1, At, B1); BAR;
;     LDA(At, 1, 1); STAGE(SA(1, 0), A, brow, t + 3);
;     BAR; WAIT_L(0); MMA(1, 0, At, B0); BAR; SCHED;
	v_readfirstlane_b32 s60, v158
	v_add_u32_e32 v134, 0x2000, v158
	v_lshl_add_u64 v[174:175], v[208:209], 0, s[66:67]
	s_mov_b32 m0, s60
	v_readfirstlane_b32 s60, v134
	global_load_lds_dwordx4 v[174:175], off
	v_lshl_add_u64 v[174:175], v[210:211], 0, s[66:67]
	s_mov_b32 m0, s60
	s_nop 0
	global_load_lds_dwordx4 v[174:175], off
	s_waitcnt vmcnt(6)
	s_barrier
	v_mfma_f32_16x16x32_bf16 v[28:31], v[234:237], v[190:193], v[28:31]
	v_mfma_f32_16x16x32_bf16 v[24:27], v[242:245], v[190:193], v[24:27]
	v_mfma_f32_16x16x32_bf16 v[20:23], v[234:237], v[198:201], v[20:23]
	v_mfma_f32_16x16x32_bf16 v[16:19], v[242:245], v[198:201], v[16:19]
	v_mfma_f32_16x16x32_bf16 v[12:15], v[234:237], v[218:221], v[12:15]
	v_mfma_f32_16x16x32_bf16 v[8:11], v[242:245], v[218:221], v[8:11]
	v_mfma_f32_16x16x32_bf16 v[4:7], v[234:237], v[226:229], v[4:7]
	v_mfma_f32_16x16x32_bf16 v[0:3], v[242:245], v[226:229], v[0:3]
	v_mfma_f32_16x16x32_bf16 v[28:31], v[238:241], v[194:197], v[28:31]
	v_mfma_f32_16x16x32_bf16 v[24:27], v[246:249], v[194:197], v[24:27]
	v_mfma_f32_16x16x32_bf16 v[20:23], v[238:241], v[202:205], v[20:23]
	v_mfma_f32_16x16x32_bf16 v[16:19], v[246:249], v[202:205], v[16:19]
	v_mfma_f32_16x16x32_bf16 v[12:15], v[238:241], v[222:225], v[12:15]
	v_mfma_f32_16x16x32_bf16 v[8:11], v[246:249], v[222:225], v[8:11]
	v_mfma_f32_16x16x32_bf16 v[4:7], v[238:241], v[230:233], v[4:7]
	v_mfma_f32_16x16x32_bf16 v[0:3], v[246:249], v[230:233], v[0:3]
	s_barrier
	ds_read_b128 v[174:177], v165
	ds_read_b128 v[178:181], v165 offset:1024
	ds_read_b128 v[182:185], v165 offset:2048
	ds_read_b128 v[186:189], v165 offset:3072
	ds_read_b128 v[190:193], v162 offset:32768
	ds_read_b128 v[194:197], v162 offset:33792
	ds_read_b128 v[198:201], v161 offset:32768
	ds_read_b128 v[202:205], v161 offset:33792
	ds_read_b128 v[218:221], v160 offset:32768
	ds_read_b128 v[222:225], v160 offset:33792
	ds_read_b128 v[226:229], v159 offset:32768
	ds_read_b128 v[230:233], v159 offset:33792
	v_add_u32_e32 v134, 0x4000, v157
	v_lshl_add_u64 v[214:215], v[136:137], 0, s[12:13]
	v_readfirstlane_b32 s60, v134
	v_add_u32_e32 v134, 0x6000, v157
	s_mov_b32 m0, s60
	v_readfirstlane_b32 s60, v134
	global_load_lds_dwordx4 v[214:215], off
	v_lshl_add_u64 v[214:215], v[138:139], 0, s[12:13]
	s_mov_b32 m0, s60
	s_nop 0
	global_load_lds_dwordx4 v[214:215], off
	s_waitcnt lgkmcnt(8)
	s_barrier
	s_waitcnt lgkmcnt(0)
	s_waitcnt lgkmcnt(0)
	v_mfma_f32_16x16x32_bf16 v[124:127], v[174:177], v[190:193], v[124:127]
	v_mfma_f32_16x16x32_bf16 v[120:123], v[182:185], v[190:193], v[120:123]
	v_mfma_f32_16x16x32_bf16 v[116:119], v[174:177], v[198:201], v[116:119]
	v_mfma_f32_16x16x32_bf16 v[112:115], v[182:185], v[198:201], v[112:115]
	v_mfma_f32_16x16x32_bf16 v[108:111], v[174:177], v[218:221], v[108:111]
	v_mfma_f32_16x16x32_bf16 v[104:107], v[182:185], v[218:221], v[104:107]
	v_mfma_f32_16x16x32_bf16 v[100:103], v[174:177], v[226:229], v[100:103]
	v_mfma_f32_16x16x32_bf16 v[96:99], v[182:185], v[226:229], v[96:99]
	v_mfma_f32_16x16x32_bf16 v[124:127], v[178:181], v[194:197], v[124:127]
	v_mfma_f32_16x16x32_bf16 v[120:123], v[186:189], v[194:197], v[120:123]
	v_mfma_f32_16x16x32_bf16 v[116:119], v[178:181], v[202:205], v[116:119]
	v_mfma_f32_16x16x32_bf16 v[112:115], v[186:189], v[202:205], v[112:115]
	v_mfma_f32_16x16x32_bf16 v[108:111], v[178:181], v[222:225], v[108:111]
	v_mfma_f32_16x16x32_bf16 v[104:107], v[186:189], v[222:225], v[104:107]
	v_mfma_f32_16x16x32_bf16 v[100:103], v[178:181], v[230:233], v[100:103]
	v_mfma_f32_16x16x32_bf16 v[96:99], v[186:189], v[230:233], v[96:99]
	s_barrier
	ds_read_b128 v[234:237], v163
	ds_read_b128 v[238:241], v163 offset:1024
	ds_read_b128 v[242:245], v163 offset:2048
	ds_read_b128 v[246:249], v163 offset:3072
	v_readfirstlane_b32 s60, v164
	v_add_u32_e32 v134, 0x2000, v164
	v_lshl_add_u64 v[214:215], v[208:209], 0, s[70:71]
	s_mov_b32 m0, s60
	v_readfirstlane_b32 s60, v134
	global_load_lds_dwordx4 v[214:215], off
	v_lshl_add_u64 v[214:215], v[210:211], 0, s[70:71]
	s_mov_b32 m0, s60
	s_nop 0
	global_load_lds_dwordx4 v[214:215], off
	s_barrier
	s_waitcnt lgkmcnt(0)
	s_waitcnt lgkmcnt(0)
	v_mfma_f32_16x16x32_bf16 v[92:95], v[234:237], v[190:193], v[92:95]
	v_mfma_f32_16x16x32_bf16 v[88:91], v[242:245], v[190:193], v[88:91]
	v_mfma_f32_16x16x32_bf16 v[84:87], v[234:237], v[198:201], v[84:87]
	v_mfma_f32_16x16x32_bf16 v[80:83], v[242:245], v[198:201], v[80:83]
	v_mfma_f32_16x16x32_bf16 v[76:79], v[234:237], v[218:221], v[76:79]
	v_mfma_f32_16x16x32_bf16 v[72:75], v[242:245], v[218:221], v[72:75]
	v_mfma_f32_16x16x32_bf16 v[68:71], v[234:237], v[226:229], v[68:71]
	v_mfma_f32_16x16x32_bf16 v[64:67], v[242:245], v[226:229], v[64:67]
	v_mfma_f32_16x16x32_bf16 v[92:95], v[238:241], v[194:197], v[92:95]
	v_mfma_f32_16x16x32_bf16 v[88:91], v[246:249], v[194:197], v[88:91]
	v_mfma_f32_16x16x32_bf16 v[84:87], v[238:241], v[202:205], v[84:87]
	v_mfma_f32_16x16x32_bf16 v[80:83], v[246:249], v[202:205], v[80:83]
	v_mfma_f32_16x16x32_bf16 v[76:79], v[238:241], v[222:225], v[76:79]
	v_mfma_f32_16x16x32_bf16 v[72:75], v[246:249], v[222:225], v[72:75]
	v_mfma_f32_16x16x32_bf16 v[68:71], v[238:241], v[230:233], v[68:71]
	v_mfma_f32_16x16x32_bf16 v[64:67], v[246:249], v[230:233], v[64:67]
	v_readfirstlane_b32 s60, v166
	v_lshl_add_u64 v[136:137], v[136:137], 0, s[16:17]
	s_mov_b32 m0, s60
	v_readfirstlane_b32 s60, v167
	s_barrier
	ds_read_b128 v[190:193], v162 offset:49152
	ds_read_b128 v[194:197], v162 offset:50176
	ds_read_b128 v[198:201], v161 offset:49152
	ds_read_b128 v[202:205], v161 offset:50176
	ds_read_b128 v[218:221], v160 offset:49152
	ds_read_b128 v[222:225], v160 offset:50176
	ds_read_b128 v[226:229], v159 offset:49152
	ds_read_b128 v[230:233], v159 offset:50176
	global_load_lds_dwordx4 v[136:137], off
	v_lshl_add_u64 v[136:137], v[138:139], 0, s[16:17]
	s_mov_b32 m0, s60
	s_nop 0
	global_load_lds_dwordx4 v[136:137], off
	s_barrier
; #define STAGE(P, BASE, br, kt) STAGET(tid_, P, BASE, br, kt)
; #define LDA(dst, b, h) UFOR(m, 4) UFOR(k, 2) \
;     dst[m][k] = *reinterpret_cast<const bf16x8*>((char*)SA(b, h) + lds_byte(wr * 64 + m * 16 + fr, k * 32 + fq * 8))
; #define LDB(dst, b, h) UFOR(n, 2) UFOR(k, 2) \
;     dst[n][k] = *reinterpret_cast<const bf16x8*>((char*)SB(b, h) + lds_byte(wc * 32 + n * 16 + fr, k * 32 + fq * 8))
; #define MMA(ai, bj, At, Bq) do { __builtin_amdgcn_s_setprio(1); \
;     UFOR(m, 4) UFOR(n, 2) UFOR(k, 2) \
;       acc[ai][bj][m][n] = __builtin_amdgcn_mfma_f32_16x16x32_bf16(Bq[n][k], At[m][k], acc[ai][bj][m][n], 0, 0, 0); \
;     __builtin_amdgcn_s_setprio(0); } while (0)
; #define WAIT_V(n) asm volatile("s_waitcnt vmcnt(" #n ")" ::: "memory")
; #define WAIT_L(n) asm volatile("s_waitcnt lgkmcnt(" #n ")" ::: "memory")
; #define BAR __builtin_amdgcn_s_barrier()
; #define SCHED __builtin_amdgcn_sched_barrier(0)
; template <int EPI, int K, int KL> ...
;     ...
;     BAR; WAIT_L(0); MMA(1, 0, At, B0); BAR; SCHED;
;     STAGE(SB(1, 1), Bt, bcol + HALF, t + 3);
;     WAIT_V(6); BAR; MMA(1, 1, At, B1); BAR;
;   }
;   { LDB(B0, 0, 0); LDA(At, 0, 0); STAGE(SA(1, 1), A, brow + HALF, nt - 1);
;     BAR; WAIT_L(0); MMA(0, 0, At, B0); BAR;
;     LDB(B1, 0, 1); BAR; WAIT_L(0); MMA(0, 1, At, B1); BAR;
;     LDA(At, 0, 1); WAIT_V(4); BAR; WAIT_L(0); MMA(1, 0, At, B0); MMA(1, 1, At, B1); BAR; }
	s_waitcnt lgkmcnt(0)
	s_waitcnt lgkmcnt(0)
	v_mfma_f32_16x16x32_bf16 v[60:63], v[174:177], v[190:193], v[60:63]
	v_mfma_f32_16x16x32_bf16 v[56:59], v[182:185], v[190:193], v[56:59]
	v_mfma_f32_16x16x32_bf16 v[52:55], v[174:177], v[198:201], v[52:55]
	v_mfma_f32_16x16x32_bf16 v[48:51], v[182:185], v[198:201], v[48:51]
	v_mfma_f32_16x16x32_bf16 v[44:47], v[174:177], v[218:221], v[44:47]
	v_mfma_f32_16x16x32_bf16 v[40:43], v[182:185], v[218:221], v[40:43]
	v_mfma_f32_16x16x32_bf16 v[36:39], v[174:177], v[226:229], v[36:39]
	v_mfma_f32_16x16x32_bf16 v[32:35], v[182:185], v[226:229], v[32:35]
	v_mfma_f32_16x16x32_bf16 v[60:63], v[178:181], v[194:197], v[60:63]
	v_mfma_f32_16x16x32_bf16 v[56:59], v[186:189], v[194:197], v[56:59]
	v_mfma_f32_16x16x32_bf16 v[52:55], v[178:181], v[202:205], v[52:55]
	v_mfma_f32_16x16x32_bf16 v[48:51], v[186:189], v[202:205], v[48:51]
	v_mfma_f32_16x16x32_bf16 v[44:47], v[178:181], v[222:225], v[44:47]
	v_mfma_f32_16x16x32_bf16 v[40:43], v[186:189], v[222:225], v[40:43]
	v_mfma_f32_16x16x32_bf16 v[36:39], v[178:181], v[230:233], v[36:39]
	v_mfma_f32_16x16x32_bf16 v[32:35], v[186:189], v[230:233], v[32:35]
	s_barrier
	v_readfirstlane_b32 s60, v169
	v_add_u32_e32 v134, 0x2000, v169
	v_lshl_add_u64 v[136:137], v[208:209], 0, s[74:75]
	s_mov_b32 m0, s60
	v_readfirstlane_b32 s60, v134
	global_load_lds_dwordx4 v[136:137], off
	v_lshl_add_u64 v[136:137], v[210:211], 0, s[74:75]
	s_mov_b32 m0, s60
	s_nop 0
	global_load_lds_dwordx4 v[136:137], off
	s_waitcnt vmcnt(6)
	s_barrier
	v_mfma_f32_16x16x32_bf16 v[28:31], v[234:237], v[190:193], v[28:31]
	v_mfma_f32_16x16x32_bf16 v[24:27], v[242:245], v[190:193], v[24:27]
	v_mfma_f32_16x16x32_bf16 v[20:23], v[234:237], v[198:201], v[20:23]
	v_mfma_f32_16x16x32_bf16 v[16:19], v[242:245], v[198:201], v[16:19]
	v_mfma_f32_16x16x32_bf16 v[12:15], v[234:237], v[218:221], v[12:15]
	v_mfma_f32_16x16x32_bf16 v[8:11], v[242:245], v[218:221], v[8:11]
	v_mfma_f32_16x16x32_bf16 v[4:7], v[234:237], v[226:229], v[4:7]
	v_mfma_f32_16x16x32_bf16 v[0:3], v[242:245], v[226:229], v[0:3]
	v_mfma_f32_16x16x32_bf16 v[28:31], v[238:241], v[194:197], v[28:31]
	v_mfma_f32_16x16x32_bf16 v[24:27], v[246:249], v[194:197], v[24:27]
	v_mfma_f32_16x16x32_bf16 v[20:23], v[238:241], v[202:205], v[20:23]
	v_mfma_f32_16x16x32_bf16 v[16:19], v[246:249], v[202:205], v[16:19]
	v_mfma_f32_16x16x32_bf16 v[12:15], v[238:241], v[222:225], v[12:15]
	v_mfma_f32_16x16x32_bf16 v[8:11], v[246:249], v[222:225], v[8:11]
	v_mfma_f32_16x16x32_bf16 v[4:7], v[238:241], v[230:233], v[4:7]
	v_mfma_f32_16x16x32_bf16 v[0:3], v[246:249], v[230:233], v[0:3]
	s_add_i32 s55, s55, 2
	v_lshl_add_u64 v[144:145], v[144:145], 0, s[20:21]
	v_lshl_add_u64 v[146:147], v[146:147], 0, s[20:21]
	v_lshl_add_u64 v[148:149], v[148:149], 0, s[20:21]
	s_cmp_lt_u32 s55, 28
	v_lshl_add_u64 v[150:151], v[150:151], 0, s[20:21]
	s_cbranch_scc1 .Lkrot_940
	s_barrier
	s_add_u32 s58, s58, 0x80f80
	s_addc_u32 s59, s59, 0
	v_lshl_add_u64 v[130:131], s[58:59], 0, v[130:131]
	v_readfirstlane_b32 s55, v171
	v_lshl_add_u64 v[128:129], v[128:129], 1, v[130:131]
	s_mov_b32 m0, s55
	ds_read_b128 v[144:147], v170
	ds_read_b128 v[148:151], v170 offset:1024
	ds_read_b128 v[174:177], v170 offset:2048
	ds_read_b128 v[178:181], v170 offset:3072
	ds_read_b128 v[182:185], v162
	ds_read_b128 v[186:189], v162 offset:1024
	ds_read_b128 v[190:193], v161
	ds_read_b128 v[194:197], v161 offset:1024
	ds_read_b128 v[198:201], v160
	ds_read_b128 v[202:205], v160 offset:1024
	ds_read_b128 v[218:221], v159
	ds_read_b128 v[222:225], v159 offset:1024
	global_load_lds_dwordx4 v[128:129], off
	v_lshl_add_u64 v[128:129], s[58:59], 0, v[142:143]
	v_readfirstlane_b32 s55, v172
	v_lshl_add_u64 v[128:129], v[140:141], 1, v[128:129]
	s_mov_b32 m0, s55
	s_nop 0
	global_load_lds_dwordx4 v[128:129], off
	s_barrier
	s_waitcnt lgkmcnt(0)
	s_waitcnt lgkmcnt(0)
	v_mfma_f32_16x16x32_bf16 v[124:127], v[144:147], v[182:185], v[124:127]
	v_mfma_f32_16x16x32_bf16 v[120:123], v[174:177], v[182:185], v[120:123]
	v_mfma_f32_16x16x32_bf16 v[116:119], v[144:147], v[190:193], v[116:119]
	v_mfma_f32_16x16x32_bf16 v[112:115], v[174:177], v[190:193], v[112:115]
	v_mfma_f32_16x16x32_bf16 v[108:111], v[144:147], v[198:201], v[108:111]
	v_mfma_f32_16x16x32_bf16 v[104:107], v[174:177], v[198:201], v[104:107]
	v_mfma_f32_16x16x32_bf16 v[100:103], v[144:147], v[218:221], v[100:103]
	v_mfma_f32_16x16x32_bf16 v[96:99], v[174:177], v[218:221], v[96:99]
	v_mfma_f32_16x16x32_bf16 v[124:127], v[148:151], v[186:189], v[124:127]
	v_mfma_f32_16x16x32_bf16 v[120:123], v[178:181], v[186:189], v[120:123]
	v_mfma_f32_16x16x32_bf16 v[116:119], v[148:151], v[194:197], v[116:119]
	v_mfma_f32_16x16x32_bf16 v[112:115], v[178:181], v[194:197], v[112:115]
	v_mfma_f32_16x16x32_bf16 v[108:111], v[148:151], v[202:205], v[108:111]
	v_mfma_f32_16x16x32_bf16 v[104:107], v[178:181], v[202:205], v[104:107]
	v_mfma_f32_16x16x32_bf16 v[100:103], v[148:151], v[222:225], v[100:103]
	v_mfma_f32_16x16x32_bf16 v[96:99], v[178:181], v[222:225], v[96:99]
	s_barrier
	ds_read_b128 v[128:131], v168
	ds_read_b128 v[140:143], v168 offset:1024
	ds_read_b128 v[170:173], v168 offset:2048
	ds_read_b128 v[166:169], v168 offset:3072
	s_barrier
; #define LDA(dst, b, h) UFOR(m, 4) UFOR(k, 2) \
;     dst[m][k] = *reinterpret_cast<const bf16x8*>((char*)SA(b, h) + lds_byte(wr * 64 + m * 16 + fr, k * 32 + fq * 8))
; #define LDB(dst, b, h) UFOR(n, 2) UFOR(k, 2) \
;     dst[n][k] = *reinterpret_cast<const bf16x8*>((char*)SB(b, h) + lds_byte(wc * 32 + n * 16 + fr, k * 32 + fq * 8))
; #define MMA(ai, bj, At, Bq) do { __builtin_amdgcn_s_setprio(1); \
;     UFOR(m, 4) UFOR(n, 2) UFOR(k, 2) \
;       acc[ai][bj][m][n] = __builtin_amdgcn_mfma_f32_16x16x32_bf16(Bq[n][k], At[m][k], acc[ai][bj][m][n], 0, 0, 0); \
;     __builtin_amdgcn_s_setprio(0); } while (0)
; #define WAIT_V(n) asm volatile("s_waitcnt vmcnt(" #n ")" ::: "memory")
; #define WAIT_L(n) asm volatile("s_waitcnt lgkmcnt(" #n ")" ::: "memory")
; #define BAR __builtin_amdgcn_s_barrier()
; template <int EPI, int K, int KL> ...
;     ...
;     BAR; WAIT_L(0); MMA(0, 0, At, B0); BAR;
;     LDB(B1, 0, 1); BAR; WAIT_L(0); MMA(0, 1, At, B1); BAR;
;     LDA(At, 0, 1); WAIT_V(4); BAR; WAIT_L(0); MMA(1, 0, At, B0); MMA(1, 1, At, B1); BAR; }
;   { LDB(B0, 1, 0); LDA(At, 1, 0); WAIT_V(2); BAR; WAIT_L(0); MMA(0, 0, At, B0); BAR;
;     LDB(B1, 1, 1); WAIT_V(0); BAR; WAIT_L(0); MMA(0, 1, At, B1); BAR;
	s_waitcnt lgkmcnt(0)
	s_waitcnt lgkmcnt(0)
	v_mfma_f32_16x16x32_bf16 v[80:83], v[170:173], v[190:193], v[80:83]
	v_mfma_f32_16x16x32_bf16 v[72:75], v[170:173], v[198:201], v[72:75]
	v_mfma_f32_16x16x32_bf16 v[68:71], v[128:131], v[218:221], v[68:71]
	v_mfma_f32_16x16x32_bf16 v[64:67], v[170:173], v[218:221], v[64:67]
	v_mfma_f32_16x16x32_bf16 v[92:95], v[128:131], v[182:185], v[92:95]
	v_mfma_f32_16x16x32_bf16 v[88:91], v[170:173], v[182:185], v[88:91]
	v_mfma_f32_16x16x32_bf16 v[84:87], v[128:131], v[190:193], v[84:87]
	v_mfma_f32_16x16x32_bf16 v[80:83], v[166:169], v[194:197], v[80:83]
	v_mfma_f32_16x16x32_bf16 v[76:79], v[128:131], v[198:201], v[76:79]
	v_mfma_f32_16x16x32_bf16 v[72:75], v[166:169], v[202:205], v[72:75]
	v_mfma_f32_16x16x32_bf16 v[68:71], v[140:143], v[222:225], v[68:71]
	v_mfma_f32_16x16x32_bf16 v[64:67], v[166:169], v[222:225], v[64:67]
	v_mfma_f32_16x16x32_bf16 v[226:229], v[140:143], v[186:189], v[92:95]
	v_mfma_f32_16x16x32_bf16 v[182:185], v[166:169], v[186:189], v[88:91]
	v_mfma_f32_16x16x32_bf16 v[186:189], v[140:143], v[194:197], v[84:87]
	v_mfma_f32_16x16x32_bf16 v[190:193], v[140:143], v[202:205], v[76:79]
	s_barrier
	s_nop 0
	ds_read_b128 v[76:79], v162 offset:16384
	ds_read_b128 v[84:87], v162 offset:17408
	ds_read_b128 v[88:91], v161 offset:16384
	ds_read_b128 v[92:95], v161 offset:17408
	ds_read_b128 v[194:197], v160 offset:16384
	ds_read_b128 v[198:201], v160 offset:17408
	ds_read_b128 v[202:205], v159 offset:16384
	ds_read_b128 v[218:221], v159 offset:17408
	s_waitcnt vmcnt(4)
	s_barrier
	s_waitcnt lgkmcnt(0)
	s_waitcnt lgkmcnt(0)
	v_mfma_f32_16x16x32_bf16 v[48:51], v[174:177], v[88:91], v[48:51]
	v_mfma_f32_16x16x32_bf16 v[40:43], v[174:177], v[194:197], v[40:43]
	v_mfma_f32_16x16x32_bf16 v[36:39], v[144:147], v[202:205], v[36:39]
	v_mfma_f32_16x16x32_bf16 v[32:35], v[174:177], v[202:205], v[32:35]
	v_mfma_f32_16x16x32_bf16 v[60:63], v[144:147], v[76:79], v[60:63]
	v_mfma_f32_16x16x32_bf16 v[56:59], v[174:177], v[76:79], v[56:59]
	v_mfma_f32_16x16x32_bf16 v[52:55], v[144:147], v[88:91], v[52:55]
	v_mfma_f32_16x16x32_bf16 v[48:51], v[178:181], v[92:95], v[48:51]
	v_mfma_f32_16x16x32_bf16 v[44:47], v[144:147], v[194:197], v[44:47]
	v_mfma_f32_16x16x32_bf16 v[40:43], v[178:181], v[198:201], v[40:43]
	v_mfma_f32_16x16x32_bf16 v[36:39], v[148:151], v[218:221], v[36:39]
	v_mfma_f32_16x16x32_bf16 v[32:35], v[178:181], v[218:221], v[32:35]
	v_mfma_f32_16x16x32_bf16 v[222:225], v[148:151], v[84:87], v[60:63]
	v_mfma_f32_16x16x32_bf16 v[230:233], v[178:181], v[84:87], v[56:59]
	v_mfma_f32_16x16x32_bf16 v[234:237], v[148:151], v[92:95], v[52:55]
	v_mfma_f32_16x16x32_bf16 v[238:241], v[148:151], v[198:201], v[44:47]
	v_mfma_f32_16x16x32_bf16 v[0:3], v[170:173], v[202:205], v[0:3]
	v_mfma_f32_16x16x32_bf16 v[28:31], v[128:131], v[76:79], v[28:31]
	v_mfma_f32_16x16x32_bf16 v[24:27], v[170:173], v[76:79], v[24:27]
	v_mfma_f32_16x16x32_bf16 v[20:23], v[128:131], v[88:91], v[20:23]
	v_mfma_f32_16x16x32_bf16 v[16:19], v[170:173], v[88:91], v[16:19]
	v_mfma_f32_16x16x32_bf16 v[12:15], v[128:131], v[194:197], v[12:15]
	v_mfma_f32_16x16x32_bf16 v[8:11], v[170:173], v[194:197], v[8:11]
	v_mfma_f32_16x16x32_bf16 v[4:7], v[128:131], v[202:205], v[4:7]
	v_mfma_f32_16x16x32_bf16 v[0:3], v[166:169], v[218:221], v[0:3]
	v_mfma_f32_16x16x32_bf16 v[144:147], v[140:143], v[84:87], v[28:31]
	v_mfma_f32_16x16x32_bf16 v[148:151], v[166:169], v[84:87], v[24:27]
	v_mfma_f32_16x16x32_bf16 v[174:177], v[140:143], v[92:95], v[20:23]
	v_mfma_f32_16x16x32_bf16 v[178:181], v[166:169], v[92:95], v[16:19]
	v_mfma_f32_16x16x32_bf16 v[242:245], v[140:143], v[198:201], v[12:15]
	v_mfma_f32_16x16x32_bf16 v[194:197], v[166:169], v[198:201], v[8:11]
	v_mfma_f32_16x16x32_bf16 v[128:131], v[140:143], v[218:221], v[4:7]
	s_barrier
	s_nop 0
	ds_read_b128 v[4:7], v165
	ds_read_b128 v[8:11], v165 offset:1024
	ds_read_b128 v[16:19], v165 offset:2048
	ds_read_b128 v[140:143], v165 offset:3072
	ds_read_b128 v[12:15], v162 offset:32768
	ds_read_b128 v[20:23], v162 offset:33792
	ds_read_b128 v[24:27], v161 offset:32768
	ds_read_b128 v[44:47], v161 offset:33792
	ds_read_b128 v[164:167], v160 offset:32768
	ds_read_b128 v[168:171], v160 offset:33792
	ds_read_b128 v[198:201], v159 offset:32768
	ds_read_b128 v[202:205], v159 offset:33792
	s_waitcnt vmcnt(2)
	s_barrier
; #define LDA(dst, b, h) UFOR(m, 4) UFOR(k, 2) \
;     dst[m][k] = *reinterpret_cast<const bf16x8*>((char*)SA(b, h) + lds_byte(wr * 64 + m * 16 + fr, k * 32 + fq * 8))
; #define LDB(dst, b, h) UFOR(n, 2) UFOR(k, 2) \
;     dst[n][k] = *reinterpret_cast<const bf16x8*>((char*)SB(b, h) + lds_byte(wc * 32 + n * 16 + fr, k * 32 + fq * 8))
; #define MMA(ai, bj, At, Bq) do { __builtin_amdgcn_s_setprio(1); \
;     UFOR(m, 4) UFOR(n, 2) UFOR(k, 2) \
;       acc[ai][bj][m][n] = __builtin_amdgcn_mfma_f32_16x16x32_bf16(Bq[n][k], At[m][k], acc[ai][bj][m][n], 0, 0, 0); \
;     __builtin_amdgcn_s_setprio(0); } while (0)
; #define WAIT_V(n) asm volatile("s_waitcnt vmcnt(" #n ")" ::: "memory")
; #define WAIT_L(n) asm volatile("s_waitcnt lgkmcnt(" #n ")" ::: "memory")
; #define BAR __builtin_amdgcn_s_barrier()
; template <int EPI, int K, int KL> ...
;     ...
;   { LDB(B0, 1, 0); LDA(At, 1, 0); WAIT_V(2); BAR; WAIT_L(0); MMA(0, 0, At, B0); BAR;
;     LDB(B1, 1, 1); WAIT_V(0); BAR; WAIT_L(0); MMA(0, 1, At, B1); BAR;
;     LDA(At, 1, 1); BAR; WAIT_L(0); MMA(1, 0, At, B0); MMA(1, 1, At, B1); BAR; }
;   if (wr == 0) BAR;
	s_waitcnt lgkmcnt(0)
	s_waitcnt lgkmcnt(0)
	v_mfma_f32_16x16x32_bf16 v[28:31], v[4:7], v[12:15], v[124:127]
	v_mfma_f32_16x16x32_bf16 v[124:127], v[8:11], v[20:23], v[28:31]
	v_mfma_f32_16x16x32_bf16 v[28:31], v[16:19], v[12:15], v[120:123]
	v_mfma_f32_16x16x32_bf16 v[92:95], v[140:143], v[20:23], v[28:31]
	v_mfma_f32_16x16x32_bf16 v[28:31], v[4:7], v[24:27], v[116:119]
	v_mfma_f32_16x16x32_bf16 v[120:123], v[8:11], v[44:47], v[28:31]
	v_mfma_f32_16x16x32_bf16 v[28:31], v[16:19], v[24:27], v[112:115]
	v_mfma_f32_16x16x32_bf16 v[88:91], v[140:143], v[44:47], v[28:31]
	v_mfma_f32_16x16x32_bf16 v[28:31], v[4:7], v[164:167], v[108:111]
	v_mfma_f32_16x16x32_bf16 v[116:119], v[8:11], v[168:171], v[28:31]
	v_mfma_f32_16x16x32_bf16 v[28:31], v[16:19], v[164:167], v[104:107]
	v_mfma_f32_16x16x32_bf16 v[84:87], v[140:143], v[168:171], v[28:31]
	v_mfma_f32_16x16x32_bf16 v[28:31], v[4:7], v[198:201], v[100:103]
	v_mfma_f32_16x16x32_bf16 v[108:111], v[8:11], v[202:205], v[28:31]
	v_mfma_f32_16x16x32_bf16 v[28:31], v[16:19], v[198:201], v[96:99]
	v_mfma_f32_16x16x32_bf16 v[76:79], v[140:143], v[202:205], v[28:31]
	s_barrier
	ds_read_b128 v[218:221], v163
	ds_read_b128 v[246:249], v163 offset:1024
	ds_read_b128 v[136:139], v163 offset:2048
	ds_read_b128 v[208:211], v163 offset:3072
	s_waitcnt vmcnt(0)
	s_barrier
	s_waitcnt lgkmcnt(0)
	s_waitcnt lgkmcnt(0)
	v_mfma_f32_16x16x32_bf16 v[28:31], v[218:221], v[12:15], v[226:229]
	v_mfma_f32_16x16x32_bf16 v[12:15], v[136:139], v[12:15], v[182:185]
	v_mfma_f32_16x16x32_bf16 v[60:63], v[246:249], v[20:23], v[28:31]
	v_mfma_f32_16x16x32_bf16 v[28:31], v[208:211], v[20:23], v[12:15]
	v_mfma_f32_16x16x32_bf16 v[12:15], v[218:221], v[24:27], v[186:189]
	v_mfma_f32_16x16x32_bf16 v[56:59], v[246:249], v[44:47], v[12:15]
	v_mfma_f32_16x16x32_bf16 v[12:15], v[136:139], v[24:27], v[80:83]
	v_mfma_f32_16x16x32_bf16 v[24:27], v[208:211], v[44:47], v[12:15]
	v_mfma_f32_16x16x32_bf16 v[12:15], v[218:221], v[164:167], v[190:193]
	v_mfma_f32_16x16x32_bf16 v[52:55], v[246:249], v[168:171], v[12:15]
	v_mfma_f32_16x16x32_bf16 v[12:15], v[136:139], v[164:167], v[72:75]
	v_mfma_f32_16x16x32_bf16 v[20:23], v[208:211], v[168:171], v[12:15]
	v_mfma_f32_16x16x32_bf16 v[12:15], v[218:221], v[198:201], v[68:71]
	v_mfma_f32_16x16x32_bf16 v[44:47], v[246:249], v[202:205], v[12:15]
	v_mfma_f32_16x16x32_bf16 v[12:15], v[136:139], v[198:201], v[64:67]
	v_mfma_f32_16x16x32_bf16 v[12:15], v[208:211], v[202:205], v[12:15]
	s_barrier
	ds_read_b128 v[164:167], v162 offset:49152
	ds_read_b128 v[168:171], v162 offset:50176
	ds_read_b128 v[182:185], v161 offset:49152
	ds_read_b128 v[186:189], v161 offset:50176
	ds_read_b128 v[190:193], v160 offset:49152
	ds_read_b128 v[160:163], v160 offset:50176
	ds_read_b128 v[198:201], v159 offset:49152
	ds_read_b128 v[156:159], v159 offset:50176
	s_barrier
	s_waitcnt lgkmcnt(0)
	s_waitcnt lgkmcnt(0)
	v_mfma_f32_16x16x32_bf16 v[64:67], v[4:7], v[164:167], v[222:225]
	v_mfma_f32_16x16x32_bf16 v[112:115], v[8:11], v[168:171], v[64:67]
	v_mfma_f32_16x16x32_bf16 v[64:67], v[16:19], v[164:167], v[230:233]
	v_mfma_f32_16x16x32_bf16 v[48:51], v[16:19], v[182:185], v[48:51]
	v_mfma_f32_16x16x32_bf16 v[80:83], v[140:143], v[168:171], v[64:67]
	v_mfma_f32_16x16x32_bf16 v[64:67], v[4:7], v[182:185], v[234:237]
	v_mfma_f32_16x16x32_bf16 v[72:75], v[140:143], v[186:189], v[48:51]
	v_mfma_f32_16x16x32_bf16 v[48:51], v[4:7], v[190:193], v[238:241]
	v_mfma_f32_16x16x32_bf16 v[4:7], v[4:7], v[198:201], v[36:39]
	v_mfma_f32_16x16x32_bf16 v[40:43], v[16:19], v[190:193], v[40:43]
	v_mfma_f32_16x16x32_bf16 v[96:99], v[8:11], v[156:159], v[4:7]
	v_mfma_f32_16x16x32_bf16 v[4:7], v[16:19], v[198:201], v[32:35]
	v_mfma_f32_16x16x32_bf16 v[104:107], v[8:11], v[186:189], v[64:67]
	v_mfma_f32_16x16x32_bf16 v[100:103], v[8:11], v[160:163], v[48:51]
	v_mfma_f32_16x16x32_bf16 v[68:71], v[140:143], v[160:163], v[40:43]
	v_mfma_f32_16x16x32_bf16 v[64:67], v[140:143], v[156:159], v[4:7]
	v_mfma_f32_16x16x32_bf16 v[4:7], v[218:221], v[164:167], v[144:147]
	v_mfma_f32_16x16x32_bf16 v[48:51], v[246:249], v[168:171], v[4:7]
	v_mfma_f32_16x16x32_bf16 v[4:7], v[136:139], v[164:167], v[148:151]
	v_mfma_f32_16x16x32_bf16 v[16:19], v[208:211], v[168:171], v[4:7]
	v_mfma_f32_16x16x32_bf16 v[4:7], v[218:221], v[182:185], v[174:177]
	v_mfma_f32_16x16x32_bf16 v[40:43], v[246:249], v[186:189], v[4:7]
	v_mfma_f32_16x16x32_bf16 v[4:7], v[136:139], v[182:185], v[178:181]
	v_mfma_f32_16x16x32_bf16 v[8:11], v[208:211], v[186:189], v[4:7]
	v_mfma_f32_16x16x32_bf16 v[4:7], v[218:221], v[190:193], v[242:245]
	v_mfma_f32_16x16x32_bf16 v[36:39], v[246:249], v[160:163], v[4:7]
	v_mfma_f32_16x16x32_bf16 v[4:7], v[136:139], v[190:193], v[194:197]
	v_mfma_f32_16x16x32_bf16 v[32:35], v[218:221], v[198:201], v[128:131]
	v_mfma_f32_16x16x32_bf16 v[0:3], v[136:139], v[198:201], v[0:3]
	v_mfma_f32_16x16x32_bf16 v[4:7], v[208:211], v[160:163], v[4:7]
	v_mfma_f32_16x16x32_bf16 v[32:35], v[246:249], v[156:159], v[32:35]
	v_mfma_f32_16x16x32_bf16 v[0:3], v[208:211], v[156:159], v[0:3]
	s_movk_i32 s55, 0x100
	v_cmp_gt_u32_e32 vcc, s55, v154
	s_barrier
	s_and_saveexec_b64 s[58:59], vcc
	s_cbranch_execz .LBB0_943
	s_barrier

; #define STAGE(P, BASE, br, kt) STAGET(tid_, P, BASE, br, kt)
; #define LDA(dst, b, h) UFOR(m, 4) UFOR(k, 2) \
;     dst[m][k] = *reinterpret_cast<const bf16x8*>((char*)SA(b, h) + lds_byte(wr * 64 + m * 16 + fr, k * 32 + fq * 8))
; #define LDB(dst, b, h) UFOR(n, 2) UFOR(k, 2) \
;     dst[n][k] = *reinterpret_cast<const bf16x8*>((char*)SB(b, h) + lds_byte(wc * 32 + n * 16 + fr, k * 32 + fq * 8))
; #define MMA(ai, bj, At, Bq) do { __builtin_amdgcn_s_setprio(1); \
;     UFOR(m, 4) UFOR(n, 2) UFOR(k, 2) \
;       acc[ai][bj][m][n] = __builtin_amdgcn_mfma_f32_16x16x32_bf16(Bq[n][k], At[m][k], acc[ai][bj][m][n], 0, 0, 0); \
;     __builtin_amdgcn_s_setprio(0); } while (0)
; #define WAIT_V(n) asm volatile("s_waitcnt vmcnt(" #n ")" ::: "memory")
; #define WAIT_L(n) asm volatile("s_waitcnt lgkmcnt(" #n ")" ::: "memory")
; #define BAR __builtin_amdgcn_s_barrier()
; #define SCHED __builtin_amdgcn_sched_barrier(0)
; template <int EPI, int K, int KL> ...
;     ...
;   for (int t = 0; t < nt - 2; t += 2) {
;     LDB(B0, 0, 0); SCHED; LDA(At, 0, 0); STAGE(SA(1, 1), A, brow + HALF, t + 1);
;     WAIT_L(8); BAR; WAIT_L(0); MMA(0, 0, At, B0); BAR; SCHED;
;     LDB(B1, 0, 1); STAGE(SB(0, 0), Bt, bcol, t + 2);
;     BAR; WAIT_L(0); MMA(0, 1, At, B1); BAR;
;     LDA(At, 0, 1); STAGE(SA(0, 0), A, brow, t + 2);
;     BAR; WAIT_L(0); MMA(1, 0, At, B0); BAR; SCHED;
;     STAGE(SB(0, 1), Bt, bcol + HALF, t + 2);
;     WAIT_V(6); BAR; MMA(1, 1, At, B1); BAR;
;     LDB(B0, 1, 0); SCHED; LDA(At, 1, 0); STAGE(SA(0, 1), A, brow + HALF, t + 2);
;     WAIT_L(8); BAR; WAIT_L(0); MMA(0, 0, At, B0); BAR; SCHED;
.LBB0_1107:
	ds_read_b128 v[136:139], v171
	ds_read_b128 v[174:177], v171 offset:1024
	ds_read_b128 v[178:181], v171 offset:2048
	ds_read_b128 v[182:185], v171 offset:3072
	ds_read_b128 v[186:189], v163
	ds_read_b128 v[190:193], v163 offset:1024
	ds_read_b128 v[194:197], v162
	ds_read_b128 v[198:201], v162 offset:1024
	ds_read_b128 v[202:205], v161
	ds_read_b128 v[208:211], v161 offset:1024
	ds_read_b128 v[218:221], v160
	ds_read_b128 v[222:225], v160 offset:1024
	v_add_u32_e32 v172, 0xc000, v158
	v_lshl_add_u64 v[214:215], s[92:93], 0, v[148:149]
	v_readfirstlane_b32 s56, v172
	v_lshl_add_u64 v[216:217], v[214:215], 0, s[88:89]
	s_mov_b32 m0, s56
	v_add_u32_e32 v173, 0xe000, v158
	global_load_lds_dwordx4 v[216:217], off
	v_lshl_add_u64 v[216:217], s[92:93], 0, v[150:151]
	v_readfirstlane_b32 s56, v173
	v_lshl_add_u64 v[226:227], v[216:217], 0, s[88:89]
	s_mov_b32 m0, s56
	s_nop 0
	global_load_lds_dwordx4 v[226:227], off
	s_waitcnt lgkmcnt(8)
	s_barrier
	s_waitcnt lgkmcnt(0)
	s_waitcnt lgkmcnt(0)
	v_mfma_f32_16x16x32_bf16 v[0:3], v[136:139], v[186:189], v[0:3]
	v_mfma_f32_16x16x32_bf16 v[4:7], v[178:181], v[186:189], v[4:7]
	v_mfma_f32_16x16x32_bf16 v[8:11], v[136:139], v[194:197], v[8:11]
	v_mfma_f32_16x16x32_bf16 v[16:19], v[178:181], v[194:197], v[16:19]
	v_mfma_f32_16x16x32_bf16 v[28:31], v[136:139], v[202:205], v[28:31]
	v_mfma_f32_16x16x32_bf16 v[40:43], v[178:181], v[202:205], v[40:43]
	v_mfma_f32_16x16x32_bf16 v[52:55], v[136:139], v[218:221], v[52:55]
	v_mfma_f32_16x16x32_bf16 v[64:67], v[178:181], v[218:221], v[64:67]
	v_mfma_f32_16x16x32_bf16 v[0:3], v[174:177], v[190:193], v[0:3]
	v_mfma_f32_16x16x32_bf16 v[4:7], v[182:185], v[190:193], v[4:7]
	v_mfma_f32_16x16x32_bf16 v[8:11], v[174:177], v[198:201], v[8:11]
	v_mfma_f32_16x16x32_bf16 v[16:19], v[182:185], v[198:201], v[16:19]
	v_mfma_f32_16x16x32_bf16 v[28:31], v[174:177], v[208:211], v[28:31]
	v_mfma_f32_16x16x32_bf16 v[40:43], v[182:185], v[208:211], v[40:43]
	v_mfma_f32_16x16x32_bf16 v[52:55], v[174:177], v[222:225], v[52:55]
	v_mfma_f32_16x16x32_bf16 v[64:67], v[182:185], v[222:225], v[64:67]
	s_barrier
	ds_read_b128 v[226:229], v169
	ds_read_b128 v[230:233], v169 offset:1024
	ds_read_b128 v[234:237], v169 offset:2048
	ds_read_b128 v[238:241], v169 offset:3072
	v_lshl_add_u64 v[242:243], s[92:93], 0, v[144:145]
	v_readfirstlane_b32 s56, v157
	v_lshl_add_u64 v[244:245], v[242:243], 0, s[2:3]
	s_mov_b32 m0, s56
	v_add_u32_e32 v134, 0x2000, v157
	global_load_lds_dwordx4 v[244:245], off
	v_lshl_add_u64 v[244:245], s[92:93], 0, v[146:147]
	v_readfirstlane_b32 s56, v134
	v_lshl_add_u64 v[246:247], v[244:245], 0, s[2:3]
	s_mov_b32 m0, s56
	s_nop 0
	global_load_lds_dwordx4 v[246:247], off
	s_barrier
	s_waitcnt lgkmcnt(0)
	s_waitcnt lgkmcnt(0)
	v_mfma_f32_16x16x32_bf16 v[12:15], v[226:229], v[186:189], v[12:15]
	v_mfma_f32_16x16x32_bf16 v[24:27], v[234:237], v[186:189], v[24:27]
	v_mfma_f32_16x16x32_bf16 v[36:39], v[226:229], v[194:197], v[36:39]
	v_mfma_f32_16x16x32_bf16 v[48:51], v[234:237], v[194:197], v[48:51]
	v_mfma_f32_16x16x32_bf16 v[60:63], v[226:229], v[202:205], v[60:63]
	v_mfma_f32_16x16x32_bf16 v[72:75], v[234:237], v[202:205], v[72:75]
	v_mfma_f32_16x16x32_bf16 v[80:83], v[226:229], v[218:221], v[80:83]
	v_mfma_f32_16x16x32_bf16 v[88:91], v[234:237], v[218:221], v[88:91]
	v_mfma_f32_16x16x32_bf16 v[12:15], v[230:233], v[190:193], v[12:15]
	v_mfma_f32_16x16x32_bf16 v[24:27], v[238:241], v[190:193], v[24:27]
	v_mfma_f32_16x16x32_bf16 v[36:39], v[230:233], v[198:201], v[36:39]
	v_mfma_f32_16x16x32_bf16 v[48:51], v[238:241], v[198:201], v[48:51]
	v_mfma_f32_16x16x32_bf16 v[60:63], v[230:233], v[208:211], v[60:63]
	v_mfma_f32_16x16x32_bf16 v[72:75], v[238:241], v[208:211], v[72:75]
	v_mfma_f32_16x16x32_bf16 v[80:83], v[230:233], v[222:225], v[80:83]
	v_mfma_f32_16x16x32_bf16 v[88:91], v[238:241], v[222:225], v[88:91]
	v_readfirstlane_b32 s56, v158
	v_add_u32_e32 v134, 0x2000, v158
	v_lshl_add_u64 v[246:247], v[214:215], 0, s[8:9]
	s_mov_b32 m0, s56
	v_readfirstlane_b32 s56, v134
	s_barrier
	ds_read_b128 v[186:189], v163 offset:16384
	ds_read_b128 v[190:193], v163 offset:17408
	ds_read_b128 v[194:197], v162 offset:16384
	ds_read_b128 v[198:201], v162 offset:17408
	ds_read_b128 v[202:205], v161 offset:16384
	ds_read_b128 v[208:211], v161 offset:17408
	ds_read_b128 v[218:221], v160 offset:16384
	ds_read_b128 v[222:225], v160 offset:17408
	global_load_lds_dwordx4 v[246:247], off
	v_lshl_add_u64 v[246:247], v[216:217], 0, s[8:9]
	s_mov_b32 m0, s56
	s_nop 0
	global_load_lds_dwordx4 v[246:247], off
	s_barrier
	s_waitcnt lgkmcnt(0)
	s_waitcnt lgkmcnt(0)
	v_mfma_f32_16x16x32_bf16 v[20:23], v[136:139], v[186:189], v[20:23]
	v_mfma_f32_16x16x32_bf16 v[32:35], v[178:181], v[186:189], v[32:35]
	v_mfma_f32_16x16x32_bf16 v[44:47], v[136:139], v[194:197], v[44:47]
	v_mfma_f32_16x16x32_bf16 v[56:59], v[178:181], v[194:197], v[56:59]
	v_mfma_f32_16x16x32_bf16 v[68:71], v[136:139], v[202:205], v[68:71]
	v_mfma_f32_16x16x32_bf16 v[76:79], v[178:181], v[202:205], v[76:79]
	v_mfma_f32_16x16x32_bf16 v[84:87], v[136:139], v[218:221], v[84:87]
	v_mfma_f32_16x16x32_bf16 v[92:95], v[178:181], v[218:221], v[92:95]
	v_mfma_f32_16x16x32_bf16 v[20:23], v[174:177], v[190:193], v[20:23]
	v_mfma_f32_16x16x32_bf16 v[32:35], v[182:185], v[190:193], v[32:35]
	v_mfma_f32_16x16x32_bf16 v[44:47], v[174:177], v[198:201], v[44:47]
	v_mfma_f32_16x16x32_bf16 v[56:59], v[182:185], v[198:201], v[56:59]
	v_mfma_f32_16x16x32_bf16 v[68:71], v[174:177], v[208:211], v[68:71]
	v_mfma_f32_16x16x32_bf16 v[76:79], v[182:185], v[208:211], v[76:79]
	v_mfma_f32_16x16x32_bf16 v[84:87], v[174:177], v[222:225], v[84:87]
	v_mfma_f32_16x16x32_bf16 v[92:95], v[182:185], v[222:225], v[92:95]
	s_barrier
; #define STAGE(P, BASE, br, kt) STAGET(tid_, P, BASE, br, kt)
; #define LDA(dst, b, h) UFOR(m, 4) UFOR(k, 2) \
;     dst[m][k] = *reinterpret_cast<const bf16x8*>((char*)SA(b, h) + lds_byte(wr * 64 + m * 16 + fr, k * 32 + fq * 8))
; #define LDB(dst, b, h) UFOR(n, 2) UFOR(k, 2) \
;     dst[n][k] = *reinterpret_cast<const bf16x8*>((char*)SB(b, h) + lds_byte(wc * 32 + n * 16 + fr, k * 32 + fq * 8))
; #define MMA(ai, bj, At, Bq) do { __builtin_amdgcn_s_setprio(1); \
;     UFOR(m, 4) UFOR(n, 2) UFOR(k, 2) \
;       acc[ai][bj][m][n] = __builtin_amdgcn_mfma_f32_16x16x32_bf16(Bq[n][k], At[m][k], acc[ai][bj][m][n], 0, 0, 0); \
;     __builtin_amdgcn_s_setprio(0); } while (0)
; #define WAIT_V(n) asm volatile("s_waitcnt vmcnt(" #n ")" ::: "memory")
; #define WAIT_L(n) asm volatile("s_waitcnt lgkmcnt(" #n ")" ::: "memory")
; #define BAR __builtin_amdgcn_s_barrier()
; #define SCHED __builtin_amdgcn_sched_barrier(0)
; template <int EPI, int K, int KL> ...
;     ...
;     WAIT_V(6); BAR; MMA(1, 1, At, B1); BAR;
;     LDB(B0, 1, 0); SCHED; LDA(At, 1, 0); STAGE(SA(0, 1), A, brow + HALF, t + 2);
;     WAIT_L(8); BAR; WAIT_L(0); MMA(0, 0, At, B0); BAR; SCHED;
;     LDB(B1, 1, 1); STAGE(SB(1, 0), Bt, bcol, t + 3);
;     BAR; WAIT_L(0); MMA(0, 1, At, B1); BAR;
;     LDA(At, 1, 1); STAGE(SA(1, 0), A, brow, t + 3);
;     BAR; WAIT_L(0); MMA(1, 0, At, B0); BAR; SCHED;
	v_readfirstlane_b32 s56, v159
	v_add_u32_e32 v134, 0x2000, v159
	v_lshl_add_u64 v[136:137], v[242:243], 0, s[96:97]
	s_mov_b32 m0, s56
	v_readfirstlane_b32 s56, v134
	global_load_lds_dwordx4 v[136:137], off
	v_lshl_add_u64 v[136:137], v[244:245], 0, s[96:97]
	s_mov_b32 m0, s56
	s_nop 0
	global_load_lds_dwordx4 v[136:137], off
	s_waitcnt vmcnt(6)
	s_barrier
	v_mfma_f32_16x16x32_bf16 v[96:99], v[226:229], v[186:189], v[96:99]
	v_mfma_f32_16x16x32_bf16 v[100:103], v[234:237], v[186:189], v[100:103]
	v_mfma_f32_16x16x32_bf16 v[104:107], v[226:229], v[194:197], v[104:107]
	v_mfma_f32_16x16x32_bf16 v[108:111], v[234:237], v[194:197], v[108:111]
	v_mfma_f32_16x16x32_bf16 v[112:115], v[226:229], v[202:205], v[112:115]
	v_mfma_f32_16x16x32_bf16 v[116:119], v[234:237], v[202:205], v[116:119]
	v_mfma_f32_16x16x32_bf16 v[120:123], v[226:229], v[218:221], v[120:123]
	v_mfma_f32_16x16x32_bf16 v[124:127], v[234:237], v[218:221], v[124:127]
	v_mfma_f32_16x16x32_bf16 v[96:99], v[230:233], v[190:193], v[96:99]
	v_mfma_f32_16x16x32_bf16 v[100:103], v[238:241], v[190:193], v[100:103]
	v_mfma_f32_16x16x32_bf16 v[104:107], v[230:233], v[198:201], v[104:107]
	v_mfma_f32_16x16x32_bf16 v[108:111], v[238:241], v[198:201], v[108:111]
	v_mfma_f32_16x16x32_bf16 v[112:115], v[230:233], v[208:211], v[112:115]
	v_mfma_f32_16x16x32_bf16 v[116:119], v[238:241], v[208:211], v[116:119]
	v_mfma_f32_16x16x32_bf16 v[120:123], v[230:233], v[222:225], v[120:123]
	v_mfma_f32_16x16x32_bf16 v[124:127], v[238:241], v[222:225], v[124:127]
	s_barrier
	ds_read_b128 v[136:139], v166
	ds_read_b128 v[174:177], v166 offset:1024
	ds_read_b128 v[178:181], v166 offset:2048
	ds_read_b128 v[182:185], v166 offset:3072
	ds_read_b128 v[186:189], v163 offset:32768
	ds_read_b128 v[190:193], v163 offset:33792
	ds_read_b128 v[194:197], v162 offset:32768
	ds_read_b128 v[198:201], v162 offset:33792
	ds_read_b128 v[202:205], v161 offset:32768
	ds_read_b128 v[208:211], v161 offset:33792
	ds_read_b128 v[218:221], v160 offset:32768
	ds_read_b128 v[222:225], v160 offset:33792
	v_add_u32_e32 v134, 0x4000, v158
	v_lshl_add_u64 v[226:227], v[214:215], 0, s[12:13]
	v_readfirstlane_b32 s56, v134
	v_add_u32_e32 v134, 0x6000, v158
	s_mov_b32 m0, s56
	v_readfirstlane_b32 s56, v134
	global_load_lds_dwordx4 v[226:227], off
	v_lshl_add_u64 v[226:227], v[216:217], 0, s[12:13]
	s_mov_b32 m0, s56
	s_nop 0
	global_load_lds_dwordx4 v[226:227], off
	s_waitcnt lgkmcnt(8)
	s_barrier
	s_waitcnt lgkmcnt(0)
	s_waitcnt lgkmcnt(0)
	v_mfma_f32_16x16x32_bf16 v[0:3], v[136:139], v[186:189], v[0:3]
	v_mfma_f32_16x16x32_bf16 v[4:7], v[178:181], v[186:189], v[4:7]
	v_mfma_f32_16x16x32_bf16 v[8:11], v[136:139], v[194:197], v[8:11]
	v_mfma_f32_16x16x32_bf16 v[16:19], v[178:181], v[194:197], v[16:19]
	v_mfma_f32_16x16x32_bf16 v[28:31], v[136:139], v[202:205], v[28:31]
	v_mfma_f32_16x16x32_bf16 v[40:43], v[178:181], v[202:205], v[40:43]
	v_mfma_f32_16x16x32_bf16 v[52:55], v[136:139], v[218:221], v[52:55]
	v_mfma_f32_16x16x32_bf16 v[64:67], v[178:181], v[218:221], v[64:67]
	v_mfma_f32_16x16x32_bf16 v[0:3], v[174:177], v[190:193], v[0:3]
	v_mfma_f32_16x16x32_bf16 v[4:7], v[182:185], v[190:193], v[4:7]
	v_mfma_f32_16x16x32_bf16 v[8:11], v[174:177], v[198:201], v[8:11]
	v_mfma_f32_16x16x32_bf16 v[16:19], v[182:185], v[198:201], v[16:19]
	v_mfma_f32_16x16x32_bf16 v[28:31], v[174:177], v[208:211], v[28:31]
	v_mfma_f32_16x16x32_bf16 v[40:43], v[182:185], v[208:211], v[40:43]
	v_mfma_f32_16x16x32_bf16 v[52:55], v[174:177], v[222:225], v[52:55]
	v_mfma_f32_16x16x32_bf16 v[64:67], v[182:185], v[222:225], v[64:67]
	s_barrier
	ds_read_b128 v[226:229], v164
	ds_read_b128 v[230:233], v164 offset:1024
	ds_read_b128 v[234:237], v164 offset:2048
	ds_read_b128 v[238:241], v164 offset:3072
	v_readfirstlane_b32 s56, v165
	v_add_u32_e32 v134, 0x2000, v165
	v_lshl_add_u64 v[246:247], v[242:243], 0, s[80:81]
	s_mov_b32 m0, s56
	v_readfirstlane_b32 s56, v134
	global_load_lds_dwordx4 v[246:247], off
	v_lshl_add_u64 v[246:247], v[244:245], 0, s[80:81]
	s_mov_b32 m0, s56
	s_nop 0
	global_load_lds_dwordx4 v[246:247], off
	s_barrier
	s_waitcnt lgkmcnt(0)
	s_waitcnt lgkmcnt(0)
	v_mfma_f32_16x16x32_bf16 v[12:15], v[226:229], v[186:189], v[12:15]
	v_mfma_f32_16x16x32_bf16 v[24:27], v[234:237], v[186:189], v[24:27]
	v_mfma_f32_16x16x32_bf16 v[36:39], v[226:229], v[194:197], v[36:39]
	v_mfma_f32_16x16x32_bf16 v[48:51], v[234:237], v[194:197], v[48:51]
	v_mfma_f32_16x16x32_bf16 v[60:63], v[226:229], v[202:205], v[60:63]
	v_mfma_f32_16x16x32_bf16 v[72:75], v[234:237], v[202:205], v[72:75]
	v_mfma_f32_16x16x32_bf16 v[80:83], v[226:229], v[218:221], v[80:83]
	v_mfma_f32_16x16x32_bf16 v[88:91], v[234:237], v[218:221], v[88:91]
	v_mfma_f32_16x16x32_bf16 v[12:15], v[230:233], v[190:193], v[12:15]
	v_mfma_f32_16x16x32_bf16 v[24:27], v[238:241], v[190:193], v[24:27]
	v_mfma_f32_16x16x32_bf16 v[36:39], v[230:233], v[198:201], v[36:39]
	v_mfma_f32_16x16x32_bf16 v[48:51], v[238:241], v[198:201], v[48:51]
	v_mfma_f32_16x16x32_bf16 v[60:63], v[230:233], v[208:211], v[60:63]
	v_mfma_f32_16x16x32_bf16 v[72:75], v[238:241], v[208:211], v[72:75]
	v_mfma_f32_16x16x32_bf16 v[80:83], v[230:233], v[222:225], v[80:83]
	v_mfma_f32_16x16x32_bf16 v[88:91], v[238:241], v[222:225], v[88:91]
	v_readfirstlane_b32 s56, v167
	v_lshl_add_u64 v[214:215], v[214:215], 0, s[16:17]
	s_mov_b32 m0, s56
	v_readfirstlane_b32 s56, v168
	s_barrier
	ds_read_b128 v[186:189], v163 offset:49152
	ds_read_b128 v[190:193], v163 offset:50176
	ds_read_b128 v[194:197], v162 offset:49152
	ds_read_b128 v[198:201], v162 offset:50176
	ds_read_b128 v[202:205], v161 offset:49152
	ds_read_b128 v[208:211], v161 offset:50176
	ds_read_b128 v[218:221], v160 offset:49152
	ds_read_b128 v[222:225], v160 offset:50176
	global_load_lds_dwordx4 v[214:215], off
	v_lshl_add_u64 v[214:215], v[216:217], 0, s[16:17]
	s_mov_b32 m0, s56
	s_nop 0
	global_load_lds_dwordx4 v[214:215], off
	s_barrier
; #define STAGE(P, BASE, br, kt) STAGET(tid_, P, BASE, br, kt)
; #define LDA(dst, b, h) UFOR(m, 4) UFOR(k, 2) \
;     dst[m][k] = *reinterpret_cast<const bf16x8*>((char*)SA(b, h) + lds_byte(wr * 64 + m * 16 + fr, k * 32 + fq * 8))
; #define LDB(dst, b, h) UFOR(n, 2) UFOR(k, 2) \
;     dst[n][k] = *reinterpret_cast<const bf16x8*>((char*)SB(b, h) + lds_byte(wc * 32 + n * 16 + fr, k * 32 + fq * 8))
; #define MMA(ai, bj, At, Bq) do { __builtin_amdgcn_s_setprio(1); \
;     UFOR(m, 4) UFOR(n, 2) UFOR(k, 2) \
;       acc[ai][bj][m][n] = __builtin_amdgcn_mfma_f32_16x16x32_bf16(Bq[n][k], At[m][k], acc[ai][bj][m][n], 0, 0, 0); \
;     __builtin_amdgcn_s_setprio(0); } while (0)
; #define WAIT_V(n) asm volatile("s_waitcnt vmcnt(" #n ")" ::: "memory")
; #define WAIT_L(n) asm volatile("s_waitcnt lgkmcnt(" #n ")" ::: "memory")
; #define BAR __builtin_amdgcn_s_barrier()
; #define SCHED __builtin_amdgcn_sched_barrier(0)
; template <int EPI, int K, int KL> ...
;     ...
;     BAR; WAIT_L(0); MMA(1, 0, At, B0); BAR; SCHED;
;     STAGE(SB(1, 1), Bt, bcol + HALF, t + 3);
;     WAIT_V(6); BAR; MMA(1, 1, At, B1); BAR;
;   }
;   { LDB(B0, 0, 0); LDA(At, 0, 0); STAGE(SA(1, 1), A, brow + HALF, nt - 1);
;     BAR; WAIT_L(0); MMA(0, 0, At, B0); BAR;
	s_waitcnt lgkmcnt(0)
	s_waitcnt lgkmcnt(0)
	v_mfma_f32_16x16x32_bf16 v[20:23], v[136:139], v[186:189], v[20:23]
	v_mfma_f32_16x16x32_bf16 v[32:35], v[178:181], v[186:189], v[32:35]
	v_mfma_f32_16x16x32_bf16 v[44:47], v[136:139], v[194:197], v[44:47]
	v_mfma_f32_16x16x32_bf16 v[56:59], v[178:181], v[194:197], v[56:59]
	v_mfma_f32_16x16x32_bf16 v[68:71], v[136:139], v[202:205], v[68:71]
	v_mfma_f32_16x16x32_bf16 v[76:79], v[178:181], v[202:205], v[76:79]
	v_mfma_f32_16x16x32_bf16 v[84:87], v[136:139], v[218:221], v[84:87]
	v_mfma_f32_16x16x32_bf16 v[92:95], v[178:181], v[218:221], v[92:95]
	v_mfma_f32_16x16x32_bf16 v[20:23], v[174:177], v[190:193], v[20:23]
	v_mfma_f32_16x16x32_bf16 v[32:35], v[182:185], v[190:193], v[32:35]
	v_mfma_f32_16x16x32_bf16 v[44:47], v[174:177], v[198:201], v[44:47]
	v_mfma_f32_16x16x32_bf16 v[56:59], v[182:185], v[198:201], v[56:59]
	v_mfma_f32_16x16x32_bf16 v[68:71], v[174:177], v[208:211], v[68:71]
	v_mfma_f32_16x16x32_bf16 v[76:79], v[182:185], v[208:211], v[76:79]
	v_mfma_f32_16x16x32_bf16 v[84:87], v[174:177], v[222:225], v[84:87]
	v_mfma_f32_16x16x32_bf16 v[92:95], v[182:185], v[222:225], v[92:95]
	s_barrier
	v_readfirstlane_b32 s56, v170
	v_add_u32_e32 v134, 0x2000, v170
	v_lshl_add_u64 v[136:137], v[242:243], 0, s[90:91]
	s_mov_b32 m0, s56
	v_readfirstlane_b32 s56, v134
	global_load_lds_dwordx4 v[136:137], off
	v_lshl_add_u64 v[136:137], v[244:245], 0, s[90:91]
	s_mov_b32 m0, s56
	s_nop 0
	global_load_lds_dwordx4 v[136:137], off
	s_waitcnt vmcnt(6)
	s_barrier
	v_mfma_f32_16x16x32_bf16 v[96:99], v[226:229], v[186:189], v[96:99]
	v_mfma_f32_16x16x32_bf16 v[100:103], v[234:237], v[186:189], v[100:103]
	v_mfma_f32_16x16x32_bf16 v[104:107], v[226:229], v[194:197], v[104:107]
	v_mfma_f32_16x16x32_bf16 v[108:111], v[234:237], v[194:197], v[108:111]
	v_mfma_f32_16x16x32_bf16 v[112:115], v[226:229], v[202:205], v[112:115]
	v_mfma_f32_16x16x32_bf16 v[116:119], v[234:237], v[202:205], v[116:119]
	v_mfma_f32_16x16x32_bf16 v[120:123], v[226:229], v[218:221], v[120:123]
	v_mfma_f32_16x16x32_bf16 v[124:127], v[234:237], v[218:221], v[124:127]
	v_mfma_f32_16x16x32_bf16 v[96:99], v[230:233], v[190:193], v[96:99]
	v_mfma_f32_16x16x32_bf16 v[100:103], v[238:241], v[190:193], v[100:103]
	v_mfma_f32_16x16x32_bf16 v[104:107], v[230:233], v[198:201], v[104:107]
	v_mfma_f32_16x16x32_bf16 v[108:111], v[238:241], v[198:201], v[108:111]
	v_mfma_f32_16x16x32_bf16 v[112:115], v[230:233], v[208:211], v[112:115]
	v_mfma_f32_16x16x32_bf16 v[116:119], v[238:241], v[208:211], v[116:119]
	v_mfma_f32_16x16x32_bf16 v[120:123], v[230:233], v[222:225], v[120:123]
	v_mfma_f32_16x16x32_bf16 v[124:127], v[238:241], v[222:225], v[124:127]
	s_add_i32 s53, s53, 2
	v_lshl_add_u64 v[144:145], v[144:145], 0, s[20:21]
	v_lshl_add_u64 v[146:147], v[146:147], 0, s[20:21]
	v_lshl_add_u64 v[148:149], v[148:149], 0, s[20:21]
	s_cmp_lt_u32 s53, 28
	v_lshl_add_u64 v[150:151], v[150:151], 0, s[20:21]
	s_cbranch_scc1 .Lkrot_1107
	s_barrier
	s_add_u32 s40, s40, 0x80f80
	s_addc_u32 s41, s41, 0
	v_lshl_add_u64 v[130:131], s[40:41], 0, v[130:131]
	v_readfirstlane_b32 s53, v172
	v_lshl_add_u64 v[128:129], v[128:129], 1, v[130:131]
	s_mov_b32 m0, s53
	ds_read_b128 v[136:139], v171
	ds_read_b128 v[144:147], v171 offset:1024
	ds_read_b128 v[148:151], v171 offset:2048
	ds_read_b128 v[174:177], v171 offset:3072
	ds_read_b128 v[178:181], v163
	ds_read_b128 v[182:185], v163 offset:1024
	ds_read_b128 v[186:189], v162
	ds_read_b128 v[190:193], v162 offset:1024
	ds_read_b128 v[194:197], v161
	ds_read_b128 v[198:201], v161 offset:1024
	ds_read_b128 v[202:205], v160
	ds_read_b128 v[208:211], v160 offset:1024
	global_load_lds_dwordx4 v[128:129], off
	v_lshl_add_u64 v[128:129], s[40:41], 0, v[142:143]
	v_readfirstlane_b32 s40, v173
	v_lshl_add_u64 v[128:129], v[140:141], 1, v[128:129]
	s_mov_b32 m0, s40
	s_nop 0
	global_load_lds_dwordx4 v[128:129], off
	s_barrier
	s_waitcnt lgkmcnt(0)
	s_waitcnt lgkmcnt(0)
	v_mfma_f32_16x16x32_bf16 v[0:3], v[136:139], v[178:181], v[0:3]
	v_mfma_f32_16x16x32_bf16 v[4:7], v[148:151], v[178:181], v[4:7]
	v_mfma_f32_16x16x32_bf16 v[8:11], v[136:139], v[186:189], v[8:11]
	v_mfma_f32_16x16x32_bf16 v[16:19], v[148:151], v[186:189], v[16:19]
	v_mfma_f32_16x16x32_bf16 v[28:31], v[136:139], v[194:197], v[28:31]
	v_mfma_f32_16x16x32_bf16 v[40:43], v[148:151], v[194:197], v[40:43]
	v_mfma_f32_16x16x32_bf16 v[52:55], v[136:139], v[202:205], v[52:55]
	v_mfma_f32_16x16x32_bf16 v[64:67], v[148:151], v[202:205], v[64:67]
	v_mfma_f32_16x16x32_bf16 v[0:3], v[144:147], v[182:185], v[0:3]
	v_mfma_f32_16x16x32_bf16 v[4:7], v[174:177], v[182:185], v[4:7]
	v_mfma_f32_16x16x32_bf16 v[8:11], v[144:147], v[190:193], v[8:11]
	v_mfma_f32_16x16x32_bf16 v[16:19], v[174:177], v[190:193], v[16:19]
	v_mfma_f32_16x16x32_bf16 v[28:31], v[144:147], v[198:201], v[28:31]
	v_mfma_f32_16x16x32_bf16 v[40:43], v[174:177], v[198:201], v[40:43]
	v_mfma_f32_16x16x32_bf16 v[52:55], v[144:147], v[208:211], v[52:55]
	v_mfma_f32_16x16x32_bf16 v[64:67], v[174:177], v[208:211], v[64:67]
	s_barrier
	ds_read_b128 v[128:131], v169
	ds_read_b128 v[140:143], v169 offset:1024
	ds_read_b128 v[170:173], v169 offset:2048
	ds_read_b128 v[218:221], v169 offset:3072
	s_barrier
; #define LDA(dst, b, h) UFOR(m, 4) UFOR(k, 2) \
;     dst[m][k] = *reinterpret_cast<const bf16x8*>((char*)SA(b, h) + lds_byte(wr * 64 + m * 16 + fr, k * 32 + fq * 8))
; #define LDB(dst, b, h) UFOR(n, 2) UFOR(k, 2) \
;     dst[n][k] = *reinterpret_cast<const bf16x8*>((char*)SB(b, h) + lds_byte(wc * 32 + n * 16 + fr, k * 32 + fq * 8))
; #define MMA(ai, bj, At, Bq) do { __builtin_amdgcn_s_setprio(1); \
;     UFOR(m, 4) UFOR(n, 2) UFOR(k, 2) \
;       acc[ai][bj][m][n] = __builtin_amdgcn_mfma_f32_16x16x32_bf16(Bq[n][k], At[m][k], acc[ai][bj][m][n], 0, 0, 0); \
;     __builtin_amdgcn_s_setprio(0); } while (0)
; #define WAIT_V(n) asm volatile("s_waitcnt vmcnt(" #n ")" ::: "memory")
; #define WAIT_L(n) asm volatile("s_waitcnt lgkmcnt(" #n ")" ::: "memory")
; #define BAR __builtin_amdgcn_s_barrier()
; template <int EPI, int K, int KL> ...
;     ...
;     LDB(B1, 0, 1); BAR; WAIT_L(0); MMA(0, 1, At, B1); BAR;
;     LDA(At, 0, 1); WAIT_V(4); BAR; WAIT_L(0); MMA(1, 0, At, B0); MMA(1, 1, At, B1); BAR; }
;   { LDB(B0, 1, 0); LDA(At, 1, 0); WAIT_V(2); BAR; WAIT_L(0); MMA(0, 0, At, B0); BAR;
	s_waitcnt lgkmcnt(0)
	s_waitcnt lgkmcnt(0)
	v_mfma_f32_16x16x32_bf16 v[12:15], v[128:131], v[178:181], v[12:15]
	v_mfma_f32_16x16x32_bf16 v[24:27], v[170:173], v[178:181], v[24:27]
	v_mfma_f32_16x16x32_bf16 v[36:39], v[128:131], v[186:189], v[36:39]
	v_mfma_f32_16x16x32_bf16 v[48:51], v[170:173], v[186:189], v[48:51]
	v_mfma_f32_16x16x32_bf16 v[60:63], v[128:131], v[194:197], v[60:63]
	v_mfma_f32_16x16x32_bf16 v[72:75], v[170:173], v[194:197], v[72:75]
	v_mfma_f32_16x16x32_bf16 v[80:83], v[128:131], v[202:205], v[80:83]
	v_mfma_f32_16x16x32_bf16 v[12:15], v[140:143], v[182:185], v[12:15]
	v_mfma_f32_16x16x32_bf16 v[24:27], v[218:221], v[182:185], v[24:27]
	v_mfma_f32_16x16x32_bf16 v[36:39], v[140:143], v[190:193], v[36:39]
	v_mfma_f32_16x16x32_bf16 v[48:51], v[218:221], v[190:193], v[48:51]
	v_mfma_f32_16x16x32_bf16 v[60:63], v[140:143], v[198:201], v[60:63]
	v_mfma_f32_16x16x32_bf16 v[72:75], v[218:221], v[198:201], v[72:75]
	v_mfma_f32_16x16x32_bf16 v[178:181], v[140:143], v[208:211], v[80:83]
	v_mfma_f32_16x16x32_bf16 v[80:83], v[170:173], v[202:205], v[88:91]
	v_mfma_f32_16x16x32_bf16 v[182:185], v[218:221], v[208:211], v[80:83]
	s_barrier
	s_nop 5
	ds_read_b128 v[80:83], v163 offset:16384
	ds_read_b128 v[88:91], v163 offset:17408
	ds_read_b128 v[186:189], v162 offset:16384
	ds_read_b128 v[190:193], v162 offset:17408
	ds_read_b128 v[194:197], v161 offset:16384
	ds_read_b128 v[198:201], v161 offset:17408
	ds_read_b128 v[202:205], v160 offset:16384
	ds_read_b128 v[208:211], v160 offset:17408
	s_waitcnt vmcnt(4)
	s_barrier
	s_waitcnt lgkmcnt(0)
	s_waitcnt lgkmcnt(0)
	v_mfma_f32_16x16x32_bf16 v[56:59], v[148:151], v[186:189], v[56:59]
	v_mfma_f32_16x16x32_bf16 v[222:225], v[174:177], v[190:193], v[56:59]
	v_mfma_f32_16x16x32_bf16 v[56:59], v[136:139], v[194:197], v[68:71]
	v_mfma_f32_16x16x32_bf16 v[226:229], v[144:147], v[198:201], v[56:59]
	v_mfma_f32_16x16x32_bf16 v[56:59], v[148:151], v[194:197], v[76:79]
	v_mfma_f32_16x16x32_bf16 v[20:23], v[136:139], v[80:83], v[20:23]
	v_mfma_f32_16x16x32_bf16 v[32:35], v[148:151], v[80:83], v[32:35]
	v_mfma_f32_16x16x32_bf16 v[44:47], v[136:139], v[186:189], v[44:47]
	v_mfma_f32_16x16x32_bf16 v[230:233], v[174:177], v[198:201], v[56:59]
	v_mfma_f32_16x16x32_bf16 v[56:59], v[136:139], v[202:205], v[84:87]
	v_mfma_f32_16x16x32_bf16 v[20:23], v[144:147], v[88:91], v[20:23]
	v_mfma_f32_16x16x32_bf16 v[32:35], v[174:177], v[88:91], v[32:35]
	v_mfma_f32_16x16x32_bf16 v[44:47], v[144:147], v[190:193], v[44:47]
	v_mfma_f32_16x16x32_bf16 v[136:139], v[144:147], v[208:211], v[56:59]
	v_mfma_f32_16x16x32_bf16 v[56:59], v[148:151], v[202:205], v[92:95]
	v_mfma_f32_16x16x32_bf16 v[144:147], v[174:177], v[208:211], v[56:59]
	v_mfma_f32_16x16x32_bf16 v[56:59], v[128:131], v[80:83], v[96:99]
	v_mfma_f32_16x16x32_bf16 v[148:151], v[140:143], v[88:91], v[56:59]
	v_mfma_f32_16x16x32_bf16 v[56:59], v[170:173], v[80:83], v[100:103]
	v_mfma_f32_16x16x32_bf16 v[174:177], v[218:221], v[88:91], v[56:59]
	v_mfma_f32_16x16x32_bf16 v[56:59], v[128:131], v[186:189], v[104:107]
	v_mfma_f32_16x16x32_bf16 v[234:237], v[140:143], v[190:193], v[56:59]
	v_mfma_f32_16x16x32_bf16 v[56:59], v[170:173], v[186:189], v[108:111]
	v_mfma_f32_16x16x32_bf16 v[186:189], v[218:221], v[190:193], v[56:59]
	v_mfma_f32_16x16x32_bf16 v[56:59], v[128:131], v[194:197], v[112:115]
	v_mfma_f32_16x16x32_bf16 v[190:193], v[140:143], v[198:201], v[56:59]
	v_mfma_f32_16x16x32_bf16 v[56:59], v[170:173], v[194:197], v[116:119]
	v_mfma_f32_16x16x32_bf16 v[194:197], v[218:221], v[198:201], v[56:59]
	v_mfma_f32_16x16x32_bf16 v[56:59], v[128:131], v[202:205], v[120:123]
	v_mfma_f32_16x16x32_bf16 v[128:131], v[140:143], v[208:211], v[56:59]
	v_mfma_f32_16x16x32_bf16 v[56:59], v[170:173], v[202:205], v[124:127]
	v_mfma_f32_16x16x32_bf16 v[140:143], v[218:221], v[208:211], v[56:59]
	s_barrier
	ds_read_b128 v[168:171], v166
	ds_read_b128 v[198:201], v166 offset:1024
	ds_read_b128 v[202:205], v166 offset:2048
	ds_read_b128 v[208:211], v166 offset:3072
	s_nop 1
	ds_read_b128 v[56:59], v163 offset:32768
	ds_read_b128 v[68:71], v163 offset:33792
	ds_read_b128 v[76:79], v162 offset:32768
	ds_read_b128 v[80:83], v162 offset:33792
	ds_read_b128 v[218:221], v161 offset:32768
	ds_read_b128 v[238:241], v161 offset:33792
	ds_read_b128 v[242:245], v160 offset:32768
	ds_read_b128 v[246:249], v160 offset:33792
	s_waitcnt vmcnt(2)
	s_barrier
; #define LDA(dst, b, h) UFOR(m, 4) UFOR(k, 2) \
;     dst[m][k] = *reinterpret_cast<const bf16x8*>((char*)SA(b, h) + lds_byte(wr * 64 + m * 16 + fr, k * 32 + fq * 8))
; #define LDB(dst, b, h) UFOR(n, 2) UFOR(k, 2) \
;     dst[n][k] = *reinterpret_cast<const bf16x8*>((char*)SB(b, h) + lds_byte(wc * 32 + n * 16 + fr, k * 32 + fq * 8))
; #define MMA(ai, bj, At, Bq) do { __builtin_amdgcn_s_setprio(1); \
;     UFOR(m, 4) UFOR(n, 2) UFOR(k, 2) \
;       acc[ai][bj][m][n] = __builtin_amdgcn_mfma_f32_16x16x32_bf16(Bq[n][k], At[m][k], acc[ai][bj][m][n], 0, 0, 0); \
;     __builtin_amdgcn_s_setprio(0); } while (0)
; #define WAIT_V(n) asm volatile("s_waitcnt vmcnt(" #n ")" ::: "memory")
; #define WAIT_L(n) asm volatile("s_waitcnt lgkmcnt(" #n ")" ::: "memory")
; #define BAR __builtin_amdgcn_s_barrier()
; template <int EPI, int K, int KL> ...
;     ...
;   { LDB(B0, 1, 0); LDA(At, 1, 0); WAIT_V(2); BAR; WAIT_L(0); MMA(0, 0, At, B0); BAR;
;     LDB(B1, 1, 1); WAIT_V(0); BAR; WAIT_L(0); MMA(0, 1, At, B1); BAR;
;     LDA(At, 1, 1); BAR; WAIT_L(0); MMA(1, 0, At, B0); MMA(1, 1, At, B1); BAR; }
;   if (wr == 0) BAR;
	s_waitcnt lgkmcnt(0)
	s_waitcnt lgkmcnt(0)
	v_mfma_f32_16x16x32_bf16 v[0:3], v[168:171], v[56:59], v[0:3]
	v_mfma_f32_16x16x32_bf16 v[124:127], v[198:201], v[68:71], v[0:3]
	v_mfma_f32_16x16x32_bf16 v[0:3], v[202:205], v[56:59], v[4:7]
	v_mfma_f32_16x16x32_bf16 v[120:123], v[208:211], v[68:71], v[0:3]
	v_mfma_f32_16x16x32_bf16 v[0:3], v[168:171], v[76:79], v[8:11]
	v_mfma_f32_16x16x32_bf16 v[116:119], v[198:201], v[80:83], v[0:3]
	v_mfma_f32_16x16x32_bf16 v[0:3], v[202:205], v[76:79], v[16:19]
	v_mfma_f32_16x16x32_bf16 v[112:115], v[208:211], v[80:83], v[0:3]
	v_mfma_f32_16x16x32_bf16 v[0:3], v[168:171], v[218:221], v[28:31]
	v_mfma_f32_16x16x32_bf16 v[108:111], v[198:201], v[238:241], v[0:3]
	v_mfma_f32_16x16x32_bf16 v[0:3], v[202:205], v[218:221], v[40:43]
	v_mfma_f32_16x16x32_bf16 v[104:107], v[208:211], v[238:241], v[0:3]
	v_mfma_f32_16x16x32_bf16 v[0:3], v[168:171], v[242:245], v[52:55]
	v_mfma_f32_16x16x32_bf16 v[100:103], v[198:201], v[246:249], v[0:3]
	v_mfma_f32_16x16x32_bf16 v[0:3], v[202:205], v[242:245], v[64:67]
	v_mfma_f32_16x16x32_bf16 v[96:99], v[208:211], v[246:249], v[0:3]
	s_barrier
	s_nop 5
	ds_read_b128 v[0:3], v164
	ds_read_b128 v[4:7], v164 offset:1024
	ds_read_b128 v[214:217], v164 offset:2048
	ds_read_b128 v[164:167], v164 offset:3072
	s_waitcnt vmcnt(0)
	s_barrier
	s_waitcnt lgkmcnt(0)
	s_waitcnt lgkmcnt(0)
	v_mfma_f32_16x16x32_bf16 v[8:11], v[0:3], v[56:59], v[12:15]
	v_mfma_f32_16x16x32_bf16 v[92:95], v[4:7], v[68:71], v[8:11]
	v_mfma_f32_16x16x32_bf16 v[8:11], v[214:217], v[56:59], v[24:27]
	v_mfma_f32_16x16x32_bf16 v[88:91], v[164:167], v[68:71], v[8:11]
	v_mfma_f32_16x16x32_bf16 v[8:11], v[0:3], v[76:79], v[36:39]
	v_mfma_f32_16x16x32_bf16 v[84:87], v[4:7], v[80:83], v[8:11]
	v_mfma_f32_16x16x32_bf16 v[8:11], v[214:217], v[76:79], v[48:51]
	v_mfma_f32_16x16x32_bf16 v[80:83], v[164:167], v[80:83], v[8:11]
	v_mfma_f32_16x16x32_bf16 v[8:11], v[0:3], v[218:221], v[60:63]
	v_mfma_f32_16x16x32_bf16 v[76:79], v[4:7], v[238:241], v[8:11]
	v_mfma_f32_16x16x32_bf16 v[8:11], v[214:217], v[218:221], v[72:75]
	v_mfma_f32_16x16x32_bf16 v[72:75], v[164:167], v[238:241], v[8:11]
	v_mfma_f32_16x16x32_bf16 v[8:11], v[0:3], v[242:245], v[178:181]
	v_mfma_f32_16x16x32_bf16 v[68:71], v[4:7], v[246:249], v[8:11]
	v_mfma_f32_16x16x32_bf16 v[8:11], v[214:217], v[242:245], v[182:185]
	v_mfma_f32_16x16x32_bf16 v[64:67], v[164:167], v[246:249], v[8:11]
	s_barrier
	s_nop 5
	ds_read_b128 v[8:11], v163 offset:49152
	ds_read_b128 v[12:15], v163 offset:50176
	ds_read_b128 v[16:19], v162 offset:49152
	ds_read_b128 v[178:181], v162 offset:50176
	ds_read_b128 v[182:185], v161 offset:49152
	ds_read_b128 v[218:221], v161 offset:50176
	ds_read_b128 v[238:241], v160 offset:49152
	ds_read_b128 v[158:161], v160 offset:50176
	s_barrier
	s_waitcnt lgkmcnt(0)
	s_waitcnt lgkmcnt(0)
	v_mfma_f32_16x16x32_bf16 v[20:23], v[168:171], v[8:11], v[20:23]
	v_mfma_f32_16x16x32_bf16 v[60:63], v[198:201], v[12:15], v[20:23]
	v_mfma_f32_16x16x32_bf16 v[20:23], v[202:205], v[8:11], v[32:35]
	v_mfma_f32_16x16x32_bf16 v[56:59], v[208:211], v[12:15], v[20:23]
	v_mfma_f32_16x16x32_bf16 v[20:23], v[168:171], v[16:19], v[44:47]
	v_mfma_f32_16x16x32_bf16 v[52:55], v[198:201], v[178:181], v[20:23]
	v_mfma_f32_16x16x32_bf16 v[20:23], v[202:205], v[16:19], v[222:225]
	v_mfma_f32_16x16x32_bf16 v[48:51], v[208:211], v[178:181], v[20:23]
	v_mfma_f32_16x16x32_bf16 v[20:23], v[168:171], v[182:185], v[226:229]
	v_mfma_f32_16x16x32_bf16 v[44:47], v[198:201], v[218:221], v[20:23]
	v_mfma_f32_16x16x32_bf16 v[20:23], v[202:205], v[182:185], v[230:233]
	v_mfma_f32_16x16x32_bf16 v[40:43], v[208:211], v[218:221], v[20:23]
	v_mfma_f32_16x16x32_bf16 v[20:23], v[168:171], v[238:241], v[136:139]
	v_mfma_f32_16x16x32_bf16 v[36:39], v[198:201], v[158:161], v[20:23]
	v_mfma_f32_16x16x32_bf16 v[20:23], v[202:205], v[238:241], v[144:147]
	v_mfma_f32_16x16x32_bf16 v[32:35], v[208:211], v[158:161], v[20:23]
	v_mfma_f32_16x16x32_bf16 v[20:23], v[0:3], v[8:11], v[148:151]
	v_mfma_f32_16x16x32_bf16 v[8:11], v[214:217], v[8:11], v[174:177]
	v_mfma_f32_16x16x32_bf16 v[24:27], v[164:167], v[12:15], v[8:11]
	v_mfma_f32_16x16x32_bf16 v[8:11], v[0:3], v[16:19], v[234:237]
	v_mfma_f32_16x16x32_bf16 v[28:31], v[4:7], v[12:15], v[20:23]
	v_mfma_f32_16x16x32_bf16 v[20:23], v[4:7], v[178:181], v[8:11]
	v_mfma_f32_16x16x32_bf16 v[8:11], v[214:217], v[16:19], v[186:189]
	v_mfma_f32_16x16x32_bf16 v[16:19], v[164:167], v[178:181], v[8:11]
	v_mfma_f32_16x16x32_bf16 v[8:11], v[0:3], v[182:185], v[190:193]
	v_mfma_f32_16x16x32_bf16 v[0:3], v[0:3], v[238:241], v[128:131]
	v_mfma_f32_16x16x32_bf16 v[12:15], v[4:7], v[218:221], v[8:11]
	v_mfma_f32_16x16x32_bf16 v[8:11], v[214:217], v[182:185], v[194:197]
	v_mfma_f32_16x16x32_bf16 v[4:7], v[4:7], v[158:161], v[0:3]
	v_mfma_f32_16x16x32_bf16 v[0:3], v[214:217], v[238:241], v[140:143]
	v_mfma_f32_16x16x32_bf16 v[8:11], v[164:167], v[218:221], v[8:11]
	v_mfma_f32_16x16x32_bf16 v[0:3], v[164:167], v[158:161], v[0:3]
	s_movk_i32 s40, 0x100
	v_cmp_gt_u32_e32 vcc, s40, v152
	s_barrier
	s_and_saveexec_b64 s[40:41], vcc
	s_cbranch_execz .LBB0_1110
	s_barrier

; #define STAGE(P, BASE, br, kt) STAGET(tid_, P, BASE, br, kt)
; #define LDA(dst, b, h) UFOR(m, 4) UFOR(k, 2) \
;     dst[m][k] = *reinterpret_cast<const bf16x8*>((char*)SA(b, h) + lds_byte(wr * 64 + m * 16 + fr, k * 32 + fq * 8))
; #define LDB(dst, b, h) UFOR(n, 2) UFOR(k, 2) \
;     dst[n][k] = *reinterpret_cast<const bf16x8*>((char*)SB(b, h) + lds_byte(wc * 32 + n * 16 + fr, k * 32 + fq * 8))
; #define MMA(ai, bj, At, Bq) do { __builtin_amdgcn_s_setprio(1); \
;     UFOR(m, 4) UFOR(n, 2) UFOR(k, 2) \
;       acc[ai][bj][m][n] = __builtin_amdgcn_mfma_f32_16x16x32_bf16(Bq[n][k], At[m][k], acc[ai][bj][m][n], 0, 0, 0); \
;     __builtin_amdgcn_s_setprio(0); } while (0)
; #define WAIT_V(n) asm volatile("s_waitcnt vmcnt(" #n ")" ::: "memory")
; #define WAIT_L(n) asm volatile("s_waitcnt lgkmcnt(" #n ")" ::: "memory")
; #define BAR __builtin_amdgcn_s_barrier()
; #define SCHED __builtin_amdgcn_sched_barrier(0)
; template <int EPI, int K, int KL> ...
;     ...
;     LDB(B0, 0, 0); SCHED; LDA(At, 0, 0); STAGE(SA(1, 1), A, brow + HALF, t + 1);
;     WAIT_L(8); BAR; WAIT_L(0); MMA(0, 0, At, B0); BAR; SCHED;
;     LDB(B1, 0, 1); STAGE(SB(0, 0), Bt, bcol, t + 2);
;     BAR; WAIT_L(0); MMA(0, 1, At, B1); BAR;
;     LDA(At, 0, 1); STAGE(SA(0, 0), A, brow, t + 2);
;     BAR; WAIT_L(0); MMA(1, 0, At, B0); BAR; SCHED;
;     STAGE(SB(0, 1), Bt, bcol + HALF, t + 2);
;     WAIT_V(6); BAR; MMA(1, 1, At, B1); BAR;
;     LDB(B0, 1, 0); SCHED; LDA(At, 1, 0); STAGE(SA(0, 1), A, brow + HALF, t + 2);
;     WAIT_L(8); BAR; WAIT_L(0); MMA(0, 0, At, B0); BAR; SCHED;
;     LDB(B1, 1, 1); STAGE(SB(1, 0), Bt, bcol, t + 3);
;     BAR; WAIT_L(0); MMA(0, 1, At, B1); BAR;
.LBB0_1184:
	ds_read_b128 v[136:139], v170
	ds_read_b128 v[174:177], v170 offset:1024
	ds_read_b128 v[178:181], v170 offset:2048
	ds_read_b128 v[182:185], v170 offset:3072
	ds_read_b128 v[186:189], v162
	ds_read_b128 v[190:193], v162 offset:1024
	ds_read_b128 v[194:197], v161
	ds_read_b128 v[198:201], v161 offset:1024
	ds_read_b128 v[202:205], v160
	ds_read_b128 v[208:211], v160 offset:1024
	ds_read_b128 v[214:217], v159
	ds_read_b128 v[218:221], v159 offset:1024
	v_add_u32_e32 v171, 0xc000, v157
	v_lshl_add_u64 v[238:239], s[92:93], 0, v[148:149]
	v_readfirstlane_b32 s54, v171
	v_lshl_add_u64 v[172:173], v[238:239], 0, s[86:87]
	s_mov_b32 m0, s54
	s_nop 0
	global_load_lds_dwordx4 v[172:173], off
	v_add_u32_e32 v172, 0xe000, v157
	v_lshl_add_u64 v[240:241], s[92:93], 0, v[150:151]
	v_readfirstlane_b32 s54, v172
	v_lshl_add_u64 v[222:223], v[240:241], 0, s[86:87]
	s_mov_b32 m0, s54
	s_nop 0
	global_load_lds_dwordx4 v[222:223], off
	s_waitcnt lgkmcnt(8)
	s_barrier
	s_waitcnt lgkmcnt(0)
	s_waitcnt lgkmcnt(0)
	v_mfma_f32_16x16x32_bf16 v[124:127], v[136:139], v[186:189], v[124:127]
	v_mfma_f32_16x16x32_bf16 v[120:123], v[178:181], v[186:189], v[120:123]
	v_mfma_f32_16x16x32_bf16 v[116:119], v[136:139], v[194:197], v[116:119]
	v_mfma_f32_16x16x32_bf16 v[112:115], v[178:181], v[194:197], v[112:115]
	v_mfma_f32_16x16x32_bf16 v[108:111], v[136:139], v[202:205], v[108:111]
	v_mfma_f32_16x16x32_bf16 v[104:107], v[178:181], v[202:205], v[104:107]
	v_mfma_f32_16x16x32_bf16 v[100:103], v[136:139], v[214:217], v[100:103]
	v_mfma_f32_16x16x32_bf16 v[96:99], v[178:181], v[214:217], v[96:99]
	v_mfma_f32_16x16x32_bf16 v[124:127], v[174:177], v[190:193], v[124:127]
	v_mfma_f32_16x16x32_bf16 v[120:123], v[182:185], v[190:193], v[120:123]
	v_mfma_f32_16x16x32_bf16 v[116:119], v[174:177], v[198:201], v[116:119]
	v_mfma_f32_16x16x32_bf16 v[112:115], v[182:185], v[198:201], v[112:115]
	v_mfma_f32_16x16x32_bf16 v[108:111], v[174:177], v[208:211], v[108:111]
	v_mfma_f32_16x16x32_bf16 v[104:107], v[182:185], v[208:211], v[104:107]
	v_mfma_f32_16x16x32_bf16 v[100:103], v[174:177], v[218:221], v[100:103]
	v_mfma_f32_16x16x32_bf16 v[96:99], v[182:185], v[218:221], v[96:99]
	s_barrier
	ds_read_b128 v[222:225], v169
	ds_read_b128 v[226:229], v169 offset:1024
	ds_read_b128 v[230:233], v169 offset:2048
	ds_read_b128 v[234:237], v169 offset:3072
	v_lshl_add_u64 v[242:243], s[92:93], 0, v[144:145]
	v_readfirstlane_b32 s54, v156
	v_lshl_add_u64 v[244:245], v[242:243], 0, s[22:23]
	s_mov_b32 m0, s54
	v_add_u32_e32 v134, 0x2000, v156
	global_load_lds_dwordx4 v[244:245], off
	v_lshl_add_u64 v[244:245], s[92:93], 0, v[146:147]
	v_readfirstlane_b32 s54, v134
	v_lshl_add_u64 v[246:247], v[244:245], 0, s[22:23]
	s_mov_b32 m0, s54
	s_nop 0
	global_load_lds_dwordx4 v[246:247], off
	s_barrier
	s_waitcnt lgkmcnt(0)
	s_waitcnt lgkmcnt(0)
	v_mfma_f32_16x16x32_bf16 v[92:95], v[222:225], v[186:189], v[92:95]
	v_mfma_f32_16x16x32_bf16 v[88:91], v[230:233], v[186:189], v[88:91]
	v_mfma_f32_16x16x32_bf16 v[84:87], v[222:225], v[194:197], v[84:87]
	v_mfma_f32_16x16x32_bf16 v[80:83], v[230:233], v[194:197], v[80:83]
	v_mfma_f32_16x16x32_bf16 v[76:79], v[222:225], v[202:205], v[76:79]
	v_mfma_f32_16x16x32_bf16 v[72:75], v[230:233], v[202:205], v[72:75]
	v_mfma_f32_16x16x32_bf16 v[68:71], v[222:225], v[214:217], v[68:71]
	v_mfma_f32_16x16x32_bf16 v[64:67], v[230:233], v[214:217], v[64:67]
	v_mfma_f32_16x16x32_bf16 v[92:95], v[226:229], v[190:193], v[92:95]
	v_mfma_f32_16x16x32_bf16 v[88:91], v[234:237], v[190:193], v[88:91]
	v_mfma_f32_16x16x32_bf16 v[84:87], v[226:229], v[198:201], v[84:87]
	v_mfma_f32_16x16x32_bf16 v[80:83], v[234:237], v[198:201], v[80:83]
	v_mfma_f32_16x16x32_bf16 v[76:79], v[226:229], v[208:211], v[76:79]
	v_mfma_f32_16x16x32_bf16 v[72:75], v[234:237], v[208:211], v[72:75]
	v_mfma_f32_16x16x32_bf16 v[68:71], v[226:229], v[218:221], v[68:71]
	v_mfma_f32_16x16x32_bf16 v[64:67], v[234:237], v[218:221], v[64:67]
	v_readfirstlane_b32 s54, v157
	v_add_u32_e32 v134, 0x2000, v157
	v_lshl_add_u64 v[246:247], v[238:239], 0, s[34:35]
	s_mov_b32 m0, s54
	v_readfirstlane_b32 s54, v134
	s_barrier
	ds_read_b128 v[186:189], v162 offset:16384
	ds_read_b128 v[190:193], v162 offset:17408
	ds_read_b128 v[194:197], v161 offset:16384
	ds_read_b128 v[198:201], v161 offset:17408
	ds_read_b128 v[202:205], v160 offset:16384
	ds_read_b128 v[208:211], v160 offset:17408
	ds_read_b128 v[214:217], v159 offset:16384
	ds_read_b128 v[218:221], v159 offset:17408
	global_load_lds_dwordx4 v[246:247], off
	v_lshl_add_u64 v[246:247], v[240:241], 0, s[34:35]
	s_mov_b32 m0, s54
	s_nop 0
	global_load_lds_dwordx4 v[246:247], off
	s_barrier
	s_waitcnt lgkmcnt(0)
	s_waitcnt lgkmcnt(0)
	v_mfma_f32_16x16x32_bf16 v[60:63], v[136:139], v[186:189], v[60:63]
	v_mfma_f32_16x16x32_bf16 v[56:59], v[178:181], v[186:189], v[56:59]
	v_mfma_f32_16x16x32_bf16 v[52:55], v[136:139], v[194:197], v[52:55]
	v_mfma_f32_16x16x32_bf16 v[48:51], v[178:181], v[194:197], v[48:51]
	v_mfma_f32_16x16x32_bf16 v[44:47], v[136:139], v[202:205], v[44:47]
	v_mfma_f32_16x16x32_bf16 v[40:43], v[178:181], v[202:205], v[40:43]
	v_mfma_f32_16x16x32_bf16 v[36:39], v[136:139], v[214:217], v[36:39]
	v_mfma_f32_16x16x32_bf16 v[32:35], v[178:181], v[214:217], v[32:35]
	v_mfma_f32_16x16x32_bf16 v[60:63], v[174:177], v[190:193], v[60:63]
	v_mfma_f32_16x16x32_bf16 v[56:59], v[182:185], v[190:193], v[56:59]
	v_mfma_f32_16x16x32_bf16 v[52:55], v[174:177], v[198:201], v[52:55]
	v_mfma_f32_16x16x32_bf16 v[48:51], v[182:185], v[198:201], v[48:51]
	v_mfma_f32_16x16x32_bf16 v[44:47], v[174:177], v[208:211], v[44:47]
	v_mfma_f32_16x16x32_bf16 v[40:43], v[182:185], v[208:211], v[40:43]
	v_mfma_f32_16x16x32_bf16 v[36:39], v[174:177], v[218:221], v[36:39]
	v_mfma_f32_16x16x32_bf16 v[32:35], v[182:185], v[218:221], v[32:35]
	s_barrier
; #define STAGE(P, BASE, br, kt) STAGET(tid_, P, BASE, br, kt)
; #define LDA(dst, b, h) UFOR(m, 4) UFOR(k, 2) \
;     dst[m][k] = *reinterpret_cast<const bf16x8*>((char*)SA(b, h) + lds_byte(wr * 64 + m * 16 + fr, k * 32 + fq * 8))
; #define LDB(dst, b, h) UFOR(n, 2) UFOR(k, 2) \
;     dst[n][k] = *reinterpret_cast<const bf16x8*>((char*)SB(b, h) + lds_byte(wc * 32 + n * 16 + fr, k * 32 + fq * 8))
; #define MMA(ai, bj, At, Bq) do { __builtin_amdgcn_s_setprio(1); \
;     UFOR(m, 4) UFOR(n, 2) UFOR(k, 2) \
;       acc[ai][bj][m][n] = __builtin_amdgcn_mfma_f32_16x16x32_bf16(Bq[n][k], At[m][k], acc[ai][bj][m][n], 0, 0, 0); \
;     __builtin_amdgcn_s_setprio(0); } while (0)
; #define WAIT_V(n) asm volatile("s_waitcnt vmcnt(" #n ")" ::: "memory")
; #define WAIT_L(n) asm volatile("s_waitcnt lgkmcnt(" #n ")" ::: "memory")
; #define BAR __builtin_amdgcn_s_barrier()
; #define SCHED __builtin_amdgcn_sched_barrier(0)
; template <int EPI, int K, int KL> ...
;     ...
;     STAGE(SB(0, 1), Bt, bcol + HALF, t + 2);
;     WAIT_V(6); BAR; MMA(1, 1, At, B1); BAR;
;     LDB(B0, 1, 0); SCHED; LDA(At, 1, 0); STAGE(SA(0, 1), A, brow + HALF, t + 2);
;     WAIT_L(8); BAR; WAIT_L(0); MMA(0, 0, At, B0); BAR; SCHED;
;     LDB(B1, 1, 1); STAGE(SB(1, 0), Bt, bcol, t + 3);
;     BAR; WAIT_L(0); MMA(0, 1, At, B1); BAR;
;     LDA(At, 1, 1); STAGE(SA(1, 0), A, brow, t + 3);
;     BAR; WAIT_L(0); MMA(1, 0, At, B0); BAR; SCHED;
;     STAGE(SB(1, 1), Bt, bcol + HALF, t + 3);
;     WAIT_V(6); BAR; MMA(1, 1, At, B1); BAR;
	v_readfirstlane_b32 s54, v158
	v_add_u32_e32 v134, 0x2000, v158
	v_lshl_add_u64 v[136:137], v[242:243], 0, s[24:25]
	s_mov_b32 m0, s54
	v_readfirstlane_b32 s54, v134
	global_load_lds_dwordx4 v[136:137], off
	v_lshl_add_u64 v[136:137], v[244:245], 0, s[24:25]
	s_mov_b32 m0, s54
	s_nop 0
	global_load_lds_dwordx4 v[136:137], off
	s_waitcnt vmcnt(6)
	s_barrier
	v_mfma_f32_16x16x32_bf16 v[28:31], v[222:225], v[186:189], v[28:31]
	v_mfma_f32_16x16x32_bf16 v[24:27], v[230:233], v[186:189], v[24:27]
	v_mfma_f32_16x16x32_bf16 v[20:23], v[222:225], v[194:197], v[20:23]
	v_mfma_f32_16x16x32_bf16 v[16:19], v[230:233], v[194:197], v[16:19]
	v_mfma_f32_16x16x32_bf16 v[12:15], v[222:225], v[202:205], v[12:15]
	v_mfma_f32_16x16x32_bf16 v[8:11], v[230:233], v[202:205], v[8:11]
	v_mfma_f32_16x16x32_bf16 v[4:7], v[222:225], v[214:217], v[4:7]
	v_mfma_f32_16x16x32_bf16 v[0:3], v[230:233], v[214:217], v[0:3]
	v_mfma_f32_16x16x32_bf16 v[28:31], v[226:229], v[190:193], v[28:31]
	v_mfma_f32_16x16x32_bf16 v[24:27], v[234:237], v[190:193], v[24:27]
	v_mfma_f32_16x16x32_bf16 v[20:23], v[226:229], v[198:201], v[20:23]
	v_mfma_f32_16x16x32_bf16 v[16:19], v[234:237], v[198:201], v[16:19]
	v_mfma_f32_16x16x32_bf16 v[12:15], v[226:229], v[208:211], v[12:15]
	v_mfma_f32_16x16x32_bf16 v[8:11], v[234:237], v[208:211], v[8:11]
	v_mfma_f32_16x16x32_bf16 v[4:7], v[226:229], v[218:221], v[4:7]
	v_mfma_f32_16x16x32_bf16 v[0:3], v[234:237], v[218:221], v[0:3]
	s_barrier
	ds_read_b128 v[136:139], v165
	ds_read_b128 v[174:177], v165 offset:1024
	ds_read_b128 v[178:181], v165 offset:2048
	ds_read_b128 v[182:185], v165 offset:3072
	ds_read_b128 v[186:189], v162 offset:32768
	ds_read_b128 v[190:193], v162 offset:33792
	ds_read_b128 v[194:197], v161 offset:32768
	ds_read_b128 v[198:201], v161 offset:33792
	ds_read_b128 v[202:205], v160 offset:32768
	ds_read_b128 v[208:211], v160 offset:33792
	ds_read_b128 v[214:217], v159 offset:32768
	ds_read_b128 v[218:221], v159 offset:33792
	v_add_u32_e32 v134, 0x4000, v157
	v_lshl_add_u64 v[222:223], v[238:239], 0, s[28:29]
	v_readfirstlane_b32 s54, v134
	v_add_u32_e32 v134, 0x6000, v157
	s_mov_b32 m0, s54
	v_readfirstlane_b32 s54, v134
	global_load_lds_dwordx4 v[222:223], off
	v_lshl_add_u64 v[222:223], v[240:241], 0, s[28:29]
	s_mov_b32 m0, s54
	s_nop 0
	global_load_lds_dwordx4 v[222:223], off
	s_waitcnt lgkmcnt(8)
	s_barrier
	s_waitcnt lgkmcnt(0)
	s_waitcnt lgkmcnt(0)
	v_mfma_f32_16x16x32_bf16 v[124:127], v[136:139], v[186:189], v[124:127]
	v_mfma_f32_16x16x32_bf16 v[120:123], v[178:181], v[186:189], v[120:123]
	v_mfma_f32_16x16x32_bf16 v[116:119], v[136:139], v[194:197], v[116:119]
	v_mfma_f32_16x16x32_bf16 v[112:115], v[178:181], v[194:197], v[112:115]
	v_mfma_f32_16x16x32_bf16 v[108:111], v[136:139], v[202:205], v[108:111]
	v_mfma_f32_16x16x32_bf16 v[104:107], v[178:181], v[202:205], v[104:107]
	v_mfma_f32_16x16x32_bf16 v[100:103], v[136:139], v[214:217], v[100:103]
	v_mfma_f32_16x16x32_bf16 v[96:99], v[178:181], v[214:217], v[96:99]
	v_mfma_f32_16x16x32_bf16 v[124:127], v[174:177], v[190:193], v[124:127]
	v_mfma_f32_16x16x32_bf16 v[120:123], v[182:185], v[190:193], v[120:123]
	v_mfma_f32_16x16x32_bf16 v[116:119], v[174:177], v[198:201], v[116:119]
	v_mfma_f32_16x16x32_bf16 v[112:115], v[182:185], v[198:201], v[112:115]
	v_mfma_f32_16x16x32_bf16 v[108:111], v[174:177], v[208:211], v[108:111]
	v_mfma_f32_16x16x32_bf16 v[104:107], v[182:185], v[208:211], v[104:107]
	v_mfma_f32_16x16x32_bf16 v[100:103], v[174:177], v[218:221], v[100:103]
	v_mfma_f32_16x16x32_bf16 v[96:99], v[182:185], v[218:221], v[96:99]
	s_barrier
	ds_read_b128 v[222:225], v163
	ds_read_b128 v[226:229], v163 offset:1024
	ds_read_b128 v[230:233], v163 offset:2048
	ds_read_b128 v[234:237], v163 offset:3072
	v_readfirstlane_b32 s54, v164
	v_add_u32_e32 v134, 0x2000, v164
	v_lshl_add_u64 v[246:247], v[242:243], 0, s[94:95]
	s_mov_b32 m0, s54
	v_readfirstlane_b32 s54, v134
	global_load_lds_dwordx4 v[246:247], off
	v_lshl_add_u64 v[246:247], v[244:245], 0, s[94:95]
	s_mov_b32 m0, s54
	s_nop 0
	global_load_lds_dwordx4 v[246:247], off
	s_barrier
	s_waitcnt lgkmcnt(0)
	s_waitcnt lgkmcnt(0)
	v_mfma_f32_16x16x32_bf16 v[92:95], v[222:225], v[186:189], v[92:95]
	v_mfma_f32_16x16x32_bf16 v[88:91], v[230:233], v[186:189], v[88:91]
	v_mfma_f32_16x16x32_bf16 v[84:87], v[222:225], v[194:197], v[84:87]
	v_mfma_f32_16x16x32_bf16 v[80:83], v[230:233], v[194:197], v[80:83]
	v_mfma_f32_16x16x32_bf16 v[76:79], v[222:225], v[202:205], v[76:79]
	v_mfma_f32_16x16x32_bf16 v[72:75], v[230:233], v[202:205], v[72:75]
	v_mfma_f32_16x16x32_bf16 v[68:71], v[222:225], v[214:217], v[68:71]
	v_mfma_f32_16x16x32_bf16 v[64:67], v[230:233], v[214:217], v[64:67]
	v_mfma_f32_16x16x32_bf16 v[92:95], v[226:229], v[190:193], v[92:95]
	v_mfma_f32_16x16x32_bf16 v[88:91], v[234:237], v[190:193], v[88:91]
	v_mfma_f32_16x16x32_bf16 v[84:87], v[226:229], v[198:201], v[84:87]
	v_mfma_f32_16x16x32_bf16 v[80:83], v[234:237], v[198:201], v[80:83]
	v_mfma_f32_16x16x32_bf16 v[76:79], v[226:229], v[208:211], v[76:79]
	v_mfma_f32_16x16x32_bf16 v[72:75], v[234:237], v[208:211], v[72:75]
	v_mfma_f32_16x16x32_bf16 v[68:71], v[226:229], v[218:221], v[68:71]
	v_mfma_f32_16x16x32_bf16 v[64:67], v[234:237], v[218:221], v[64:67]
	v_readfirstlane_b32 s54, v166
	v_lshl_add_u64 v[238:239], v[238:239], 0, s[4:5]
	s_mov_b32 m0, s54
	v_readfirstlane_b32 s54, v167
	s_barrier
	ds_read_b128 v[186:189], v162 offset:49152
	ds_read_b128 v[190:193], v162 offset:50176
	ds_read_b128 v[194:197], v161 offset:49152
	ds_read_b128 v[198:201], v161 offset:50176
	ds_read_b128 v[202:205], v160 offset:49152
	ds_read_b128 v[208:211], v160 offset:50176
	ds_read_b128 v[214:217], v159 offset:49152
	ds_read_b128 v[218:221], v159 offset:50176
	global_load_lds_dwordx4 v[238:239], off
	v_lshl_add_u64 v[238:239], v[240:241], 0, s[4:5]
	s_mov_b32 m0, s54
	s_nop 0
	global_load_lds_dwordx4 v[238:239], off
	s_barrier
; #define STAGE(P, BASE, br, kt) STAGET(tid_, P, BASE, br, kt)
; #define LDA(dst, b, h) UFOR(m, 4) UFOR(k, 2) \
;     dst[m][k] = *reinterpret_cast<const bf16x8*>((char*)SA(b, h) + lds_byte(wr * 64 + m * 16 + fr, k * 32 + fq * 8))
; #define LDB(dst, b, h) UFOR(n, 2) UFOR(k, 2) \
;     dst[n][k] = *reinterpret_cast<const bf16x8*>((char*)SB(b, h) + lds_byte(wc * 32 + n * 16 + fr, k * 32 + fq * 8))
; #define MMA(ai, bj, At, Bq) do { __builtin_amdgcn_s_setprio(1); \
;     UFOR(m, 4) UFOR(n, 2) UFOR(k, 2) \
;       acc[ai][bj][m][n] = __builtin_amdgcn_mfma_f32_16x16x32_bf16(Bq[n][k], At[m][k], acc[ai][bj][m][n], 0, 0, 0); \
;     __builtin_amdgcn_s_setprio(0); } while (0)
; #define WAIT_V(n) asm volatile("s_waitcnt vmcnt(" #n ")" ::: "memory")
; #define WAIT_L(n) asm volatile("s_waitcnt lgkmcnt(" #n ")" ::: "memory")
; #define BAR __builtin_amdgcn_s_barrier()
; #define SCHED __builtin_amdgcn_sched_barrier(0)
; template <int EPI, int K, int KL> ...
;     ...
;     LDA(At, 1, 1); STAGE(SA(1, 0), A, brow, t + 3);
;     BAR; WAIT_L(0); MMA(1, 0, At, B0); BAR; SCHED;
;     STAGE(SB(1, 1), Bt, bcol + HALF, t + 3);
;     WAIT_V(6); BAR; MMA(1, 1, At, B1); BAR;
;   }
;   { LDB(B0, 0, 0); LDA(At, 0, 0); STAGE(SA(1, 1), A, brow + HALF, nt - 1);
;     BAR; WAIT_L(0); MMA(0, 0, At, B0); BAR;
;     LDB(B1, 0, 1); BAR; WAIT_L(0); MMA(0, 1, At, B1); BAR;
	s_waitcnt lgkmcnt(0)
	s_waitcnt lgkmcnt(0)
	v_mfma_f32_16x16x32_bf16 v[60:63], v[136:139], v[186:189], v[60:63]
	v_mfma_f32_16x16x32_bf16 v[56:59], v[178:181], v[186:189], v[56:59]
	v_mfma_f32_16x16x32_bf16 v[52:55], v[136:139], v[194:197], v[52:55]
	v_mfma_f32_16x16x32_bf16 v[48:51], v[178:181], v[194:197], v[48:51]
	v_mfma_f32_16x16x32_bf16 v[44:47], v[136:139], v[202:205], v[44:47]
	v_mfma_f32_16x16x32_bf16 v[40:43], v[178:181], v[202:205], v[40:43]
	v_mfma_f32_16x16x32_bf16 v[36:39], v[136:139], v[214:217], v[36:39]
	v_mfma_f32_16x16x32_bf16 v[32:35], v[178:181], v[214:217], v[32:35]
	v_mfma_f32_16x16x32_bf16 v[60:63], v[174:177], v[190:193], v[60:63]
	v_mfma_f32_16x16x32_bf16 v[56:59], v[182:185], v[190:193], v[56:59]
	v_mfma_f32_16x16x32_bf16 v[52:55], v[174:177], v[198:201], v[52:55]
	v_mfma_f32_16x16x32_bf16 v[48:51], v[182:185], v[198:201], v[48:51]
	v_mfma_f32_16x16x32_bf16 v[44:47], v[174:177], v[208:211], v[44:47]
	v_mfma_f32_16x16x32_bf16 v[40:43], v[182:185], v[208:211], v[40:43]
	v_mfma_f32_16x16x32_bf16 v[36:39], v[174:177], v[218:221], v[36:39]
	v_mfma_f32_16x16x32_bf16 v[32:35], v[182:185], v[218:221], v[32:35]
	s_barrier
	v_readfirstlane_b32 s54, v168
	v_add_u32_e32 v134, 0x2000, v168
	v_lshl_add_u64 v[136:137], v[242:243], 0, s[10:11]
	s_mov_b32 m0, s54
	v_readfirstlane_b32 s54, v134
	global_load_lds_dwordx4 v[136:137], off
	v_lshl_add_u64 v[136:137], v[244:245], 0, s[10:11]
	s_mov_b32 m0, s54
	s_nop 0
	global_load_lds_dwordx4 v[136:137], off
	s_waitcnt vmcnt(6)
	s_barrier
	v_mfma_f32_16x16x32_bf16 v[28:31], v[222:225], v[186:189], v[28:31]
	v_mfma_f32_16x16x32_bf16 v[24:27], v[230:233], v[186:189], v[24:27]
	v_mfma_f32_16x16x32_bf16 v[20:23], v[222:225], v[194:197], v[20:23]
	v_mfma_f32_16x16x32_bf16 v[16:19], v[230:233], v[194:197], v[16:19]
	v_mfma_f32_16x16x32_bf16 v[12:15], v[222:225], v[202:205], v[12:15]
	v_mfma_f32_16x16x32_bf16 v[8:11], v[230:233], v[202:205], v[8:11]
	v_mfma_f32_16x16x32_bf16 v[4:7], v[222:225], v[214:217], v[4:7]
	v_mfma_f32_16x16x32_bf16 v[0:3], v[230:233], v[214:217], v[0:3]
	v_mfma_f32_16x16x32_bf16 v[28:31], v[226:229], v[190:193], v[28:31]
	v_mfma_f32_16x16x32_bf16 v[24:27], v[234:237], v[190:193], v[24:27]
	v_mfma_f32_16x16x32_bf16 v[20:23], v[226:229], v[198:201], v[20:23]
	v_mfma_f32_16x16x32_bf16 v[16:19], v[234:237], v[198:201], v[16:19]
	v_mfma_f32_16x16x32_bf16 v[12:15], v[226:229], v[208:211], v[12:15]
	v_mfma_f32_16x16x32_bf16 v[8:11], v[234:237], v[208:211], v[8:11]
	v_mfma_f32_16x16x32_bf16 v[4:7], v[226:229], v[218:221], v[4:7]
	v_mfma_f32_16x16x32_bf16 v[0:3], v[234:237], v[218:221], v[0:3]
	s_add_i32 s19, s19, 2
	v_lshl_add_u64 v[144:145], v[144:145], 0, s[20:21]
	v_lshl_add_u64 v[146:147], v[146:147], 0, s[20:21]
	v_lshl_add_u64 v[148:149], v[148:149], 0, s[20:21]
	s_cmpk_lt_u32 s19, 0x54
	v_lshl_add_u64 v[150:151], v[150:151], 0, s[20:21]
	s_cbranch_scc1 .Lkrot_1184
	s_barrier
	s_add_u32 s52, s52, 0x162b80
	s_addc_u32 s53, s53, 0
	v_lshl_add_u64 v[130:131], s[52:53], 0, v[130:131]
	v_readfirstlane_b32 s19, v171
	v_lshl_add_u64 v[128:129], v[128:129], 1, v[130:131]
	s_mov_b32 m0, s19
	ds_read_b128 v[136:139], v170
	ds_read_b128 v[144:147], v170 offset:1024
	ds_read_b128 v[148:151], v170 offset:2048
	ds_read_b128 v[174:177], v170 offset:3072
	ds_read_b128 v[178:181], v162
	ds_read_b128 v[182:185], v162 offset:1024
	ds_read_b128 v[186:189], v161
	ds_read_b128 v[190:193], v161 offset:1024
	ds_read_b128 v[194:197], v160
	ds_read_b128 v[198:201], v160 offset:1024
	ds_read_b128 v[202:205], v159
	ds_read_b128 v[208:211], v159 offset:1024
	global_load_lds_dwordx4 v[128:129], off
	v_lshl_add_u64 v[128:129], s[52:53], 0, v[142:143]
	v_readfirstlane_b32 s19, v172
	v_lshl_add_u64 v[128:129], v[140:141], 1, v[128:129]
	s_mov_b32 m0, s19
	s_nop 0
	global_load_lds_dwordx4 v[128:129], off
	s_barrier
	s_waitcnt lgkmcnt(0)
	s_waitcnt lgkmcnt(0)
	v_mfma_f32_16x16x32_bf16 v[120:123], v[148:151], v[178:181], v[120:123]
	v_mfma_f32_16x16x32_bf16 v[116:119], v[136:139], v[186:189], v[116:119]
	v_mfma_f32_16x16x32_bf16 v[112:115], v[148:151], v[186:189], v[112:115]
	v_mfma_f32_16x16x32_bf16 v[108:111], v[136:139], v[194:197], v[108:111]
	v_mfma_f32_16x16x32_bf16 v[104:107], v[148:151], v[194:197], v[104:107]
	v_mfma_f32_16x16x32_bf16 v[100:103], v[136:139], v[202:205], v[100:103]
	v_mfma_f32_16x16x32_bf16 v[96:99], v[148:151], v[202:205], v[96:99]
	v_mfma_f32_16x16x32_bf16 v[124:127], v[136:139], v[178:181], v[124:127]
	v_mfma_f32_16x16x32_bf16 v[120:123], v[174:177], v[182:185], v[120:123]
	v_mfma_f32_16x16x32_bf16 v[116:119], v[144:147], v[190:193], v[116:119]
	v_mfma_f32_16x16x32_bf16 v[112:115], v[174:177], v[190:193], v[112:115]
	v_mfma_f32_16x16x32_bf16 v[108:111], v[144:147], v[198:201], v[108:111]
	v_mfma_f32_16x16x32_bf16 v[104:107], v[174:177], v[198:201], v[104:107]
	v_mfma_f32_16x16x32_bf16 v[100:103], v[144:147], v[208:211], v[100:103]
	v_mfma_f32_16x16x32_bf16 v[96:99], v[174:177], v[208:211], v[96:99]
	v_mfma_f32_16x16x32_bf16 v[124:127], v[144:147], v[182:185], v[124:127]
	s_barrier
	ds_read_b128 v[128:131], v169
	ds_read_b128 v[140:143], v169 offset:1024
	ds_read_b128 v[170:173], v169 offset:2048
	ds_read_b128 v[166:169], v169 offset:3072
	s_barrier
; #define LDA(dst, b, h) UFOR(m, 4) UFOR(k, 2) \
;     dst[m][k] = *reinterpret_cast<const bf16x8*>((char*)SA(b, h) + lds_byte(wr * 64 + m * 16 + fr, k * 32 + fq * 8))
; #define LDB(dst, b, h) UFOR(n, 2) UFOR(k, 2) \
;     dst[n][k] = *reinterpret_cast<const bf16x8*>((char*)SB(b, h) + lds_byte(wc * 32 + n * 16 + fr, k * 32 + fq * 8))
; #define MMA(ai, bj, At, Bq) do { __builtin_amdgcn_s_setprio(1); \
;     UFOR(m, 4) UFOR(n, 2) UFOR(k, 2) \
;       acc[ai][bj][m][n] = __builtin_amdgcn_mfma_f32_16x16x32_bf16(Bq[n][k], At[m][k], acc[ai][bj][m][n], 0, 0, 0); \
;     __builtin_amdgcn_s_setprio(0); } while (0)
; #define WAIT_V(n) asm volatile("s_waitcnt vmcnt(" #n ")" ::: "memory")
; #define WAIT_L(n) asm volatile("s_waitcnt lgkmcnt(" #n ")" ::: "memory")
; #define BAR __builtin_amdgcn_s_barrier()
; template <int EPI, int K, int KL> ...
;     ...
;     LDB(B1, 0, 1); BAR; WAIT_L(0); MMA(0, 1, At, B1); BAR;
;     LDA(At, 0, 1); WAIT_V(4); BAR; WAIT_L(0); MMA(1, 0, At, B0); MMA(1, 1, At, B1); BAR; }
;   { LDB(B0, 1, 0); LDA(At, 1, 0); WAIT_V(2); BAR; WAIT_L(0); MMA(0, 0, At, B0); BAR;
	s_waitcnt lgkmcnt(0)
	s_waitcnt lgkmcnt(0)
	v_mfma_f32_16x16x32_bf16 v[80:83], v[170:173], v[186:189], v[80:83]
	v_mfma_f32_16x16x32_bf16 v[76:79], v[128:131], v[194:197], v[76:79]
	v_mfma_f32_16x16x32_bf16 v[68:71], v[128:131], v[202:205], v[68:71]
	v_mfma_f32_16x16x32_bf16 v[64:67], v[170:173], v[202:205], v[64:67]
	v_mfma_f32_16x16x32_bf16 v[92:95], v[128:131], v[178:181], v[92:95]
	v_mfma_f32_16x16x32_bf16 v[88:91], v[170:173], v[178:181], v[88:91]
	v_mfma_f32_16x16x32_bf16 v[84:87], v[128:131], v[186:189], v[84:87]
	v_mfma_f32_16x16x32_bf16 v[80:83], v[166:169], v[190:193], v[80:83]
	v_mfma_f32_16x16x32_bf16 v[76:79], v[140:143], v[198:201], v[76:79]
	v_mfma_f32_16x16x32_bf16 v[72:75], v[170:173], v[194:197], v[72:75]
	v_mfma_f32_16x16x32_bf16 v[68:71], v[140:143], v[208:211], v[68:71]
	v_mfma_f32_16x16x32_bf16 v[64:67], v[166:169], v[208:211], v[64:67]
	v_mfma_f32_16x16x32_bf16 v[214:217], v[140:143], v[182:185], v[92:95]
	v_mfma_f32_16x16x32_bf16 v[178:181], v[166:169], v[182:185], v[88:91]
	v_mfma_f32_16x16x32_bf16 v[182:185], v[140:143], v[190:193], v[84:87]
	v_mfma_f32_16x16x32_bf16 v[186:189], v[166:169], v[198:201], v[72:75]
	s_barrier
	s_nop 0
	ds_read_b128 v[72:75], v162 offset:16384
	ds_read_b128 v[84:87], v162 offset:17408
	ds_read_b128 v[88:91], v161 offset:16384
	ds_read_b128 v[92:95], v161 offset:17408
	ds_read_b128 v[190:193], v160 offset:16384
	ds_read_b128 v[194:197], v160 offset:17408
	ds_read_b128 v[198:201], v159 offset:16384
	ds_read_b128 v[202:205], v159 offset:17408
	s_waitcnt vmcnt(4)
	s_barrier
	s_waitcnt lgkmcnt(0)
	s_waitcnt lgkmcnt(0)
	v_mfma_f32_16x16x32_bf16 v[48:51], v[148:151], v[88:91], v[48:51]
	v_mfma_f32_16x16x32_bf16 v[40:43], v[148:151], v[190:193], v[40:43]
	v_mfma_f32_16x16x32_bf16 v[36:39], v[136:139], v[198:201], v[36:39]
	v_mfma_f32_16x16x32_bf16 v[32:35], v[148:151], v[198:201], v[32:35]
	v_mfma_f32_16x16x32_bf16 v[60:63], v[136:139], v[72:75], v[60:63]
	v_mfma_f32_16x16x32_bf16 v[56:59], v[148:151], v[72:75], v[56:59]
	v_mfma_f32_16x16x32_bf16 v[52:55], v[136:139], v[88:91], v[52:55]
	v_mfma_f32_16x16x32_bf16 v[48:51], v[174:177], v[92:95], v[48:51]
	v_mfma_f32_16x16x32_bf16 v[44:47], v[136:139], v[190:193], v[44:47]
	v_mfma_f32_16x16x32_bf16 v[40:43], v[174:177], v[194:197], v[40:43]
	v_mfma_f32_16x16x32_bf16 v[36:39], v[144:147], v[202:205], v[36:39]
	v_mfma_f32_16x16x32_bf16 v[32:35], v[174:177], v[202:205], v[32:35]
	v_mfma_f32_16x16x32_bf16 v[208:211], v[144:147], v[84:87], v[60:63]
	v_mfma_f32_16x16x32_bf16 v[218:221], v[174:177], v[84:87], v[56:59]
	v_mfma_f32_16x16x32_bf16 v[222:225], v[144:147], v[92:95], v[52:55]
	v_mfma_f32_16x16x32_bf16 v[226:229], v[144:147], v[194:197], v[44:47]
	v_mfma_f32_16x16x32_bf16 v[0:3], v[170:173], v[198:201], v[0:3]
	v_mfma_f32_16x16x32_bf16 v[28:31], v[128:131], v[72:75], v[28:31]
	v_mfma_f32_16x16x32_bf16 v[24:27], v[170:173], v[72:75], v[24:27]
	v_mfma_f32_16x16x32_bf16 v[20:23], v[128:131], v[88:91], v[20:23]
	v_mfma_f32_16x16x32_bf16 v[16:19], v[170:173], v[88:91], v[16:19]
	v_mfma_f32_16x16x32_bf16 v[12:15], v[128:131], v[190:193], v[12:15]
	v_mfma_f32_16x16x32_bf16 v[8:11], v[170:173], v[190:193], v[8:11]
	v_mfma_f32_16x16x32_bf16 v[4:7], v[128:131], v[198:201], v[4:7]
	v_mfma_f32_16x16x32_bf16 v[0:3], v[166:169], v[202:205], v[0:3]
	v_mfma_f32_16x16x32_bf16 v[136:139], v[140:143], v[84:87], v[28:31]
	v_mfma_f32_16x16x32_bf16 v[144:147], v[166:169], v[84:87], v[24:27]
	v_mfma_f32_16x16x32_bf16 v[148:151], v[140:143], v[92:95], v[20:23]
	v_mfma_f32_16x16x32_bf16 v[174:177], v[166:169], v[92:95], v[16:19]
	v_mfma_f32_16x16x32_bf16 v[230:233], v[140:143], v[194:197], v[12:15]
	v_mfma_f32_16x16x32_bf16 v[190:193], v[166:169], v[194:197], v[8:11]
	v_mfma_f32_16x16x32_bf16 v[140:143], v[140:143], v[202:205], v[4:7]
	s_barrier
	s_nop 0
	ds_read_b128 v[4:7], v165
	ds_read_b128 v[8:11], v165 offset:1024
	ds_read_b128 v[16:19], v165 offset:2048
	ds_read_b128 v[164:167], v165 offset:3072
	ds_read_b128 v[12:15], v162 offset:32768
	ds_read_b128 v[20:23], v162 offset:33792
	ds_read_b128 v[24:27], v161 offset:32768
	ds_read_b128 v[44:47], v161 offset:33792
	ds_read_b128 v[168:171], v160 offset:32768
	ds_read_b128 v[194:197], v160 offset:33792
	ds_read_b128 v[198:201], v159 offset:32768
	ds_read_b128 v[202:205], v159 offset:33792
	s_waitcnt vmcnt(2)
	s_barrier
; #define LDA(dst, b, h) UFOR(m, 4) UFOR(k, 2) \
;     dst[m][k] = *reinterpret_cast<const bf16x8*>((char*)SA(b, h) + lds_byte(wr * 64 + m * 16 + fr, k * 32 + fq * 8))
; #define LDB(dst, b, h) UFOR(n, 2) UFOR(k, 2) \
;     dst[n][k] = *reinterpret_cast<const bf16x8*>((char*)SB(b, h) + lds_byte(wc * 32 + n * 16 + fr, k * 32 + fq * 8))
; #define MMA(ai, bj, At, Bq) do { __builtin_amdgcn_s_setprio(1); \
;     UFOR(m, 4) UFOR(n, 2) UFOR(k, 2) \
;       acc[ai][bj][m][n] = __builtin_amdgcn_mfma_f32_16x16x32_bf16(Bq[n][k], At[m][k], acc[ai][bj][m][n], 0, 0, 0); \
;     __builtin_amdgcn_s_setprio(0); } while (0)
; #define WAIT_V(n) asm volatile("s_waitcnt vmcnt(" #n ")" ::: "memory")
; #define WAIT_L(n) asm volatile("s_waitcnt lgkmcnt(" #n ")" ::: "memory")
; #define BAR __builtin_amdgcn_s_barrier()
; template <int EPI, int K, int KL> ...
;     ...
;   { LDB(B0, 1, 0); LDA(At, 1, 0); WAIT_V(2); BAR; WAIT_L(0); MMA(0, 0, At, B0); BAR;
;     LDB(B1, 1, 1); WAIT_V(0); BAR; WAIT_L(0); MMA(0, 1, At, B1); BAR;
;     LDA(At, 1, 1); BAR; WAIT_L(0); MMA(1, 0, At, B0); MMA(1, 1, At, B1); BAR; }
;   if (wr == 0) BAR;
;   if (EPI != EPI_UPG && EPI != EPI_PART && has_next) {
	s_waitcnt lgkmcnt(0)
	s_waitcnt lgkmcnt(0)
	v_mfma_f32_16x16x32_bf16 v[28:31], v[4:7], v[12:15], v[124:127]
	v_mfma_f32_16x16x32_bf16 v[128:131], v[8:11], v[20:23], v[28:31]
	v_mfma_f32_16x16x32_bf16 v[28:31], v[16:19], v[12:15], v[120:123]
	v_mfma_f32_16x16x32_bf16 v[92:95], v[164:167], v[20:23], v[28:31]
	v_mfma_f32_16x16x32_bf16 v[28:31], v[4:7], v[24:27], v[116:119]
	v_mfma_f32_16x16x32_bf16 v[120:123], v[8:11], v[44:47], v[28:31]
	v_mfma_f32_16x16x32_bf16 v[28:31], v[16:19], v[24:27], v[112:115]
	v_mfma_f32_16x16x32_bf16 v[88:91], v[164:167], v[44:47], v[28:31]
	v_mfma_f32_16x16x32_bf16 v[28:31], v[4:7], v[168:171], v[108:111]
	v_mfma_f32_16x16x32_bf16 v[116:119], v[8:11], v[194:197], v[28:31]
	v_mfma_f32_16x16x32_bf16 v[28:31], v[16:19], v[168:171], v[104:107]
	v_mfma_f32_16x16x32_bf16 v[84:87], v[164:167], v[194:197], v[28:31]
	v_mfma_f32_16x16x32_bf16 v[28:31], v[4:7], v[198:201], v[100:103]
	v_mfma_f32_16x16x32_bf16 v[108:111], v[8:11], v[202:205], v[28:31]
	v_mfma_f32_16x16x32_bf16 v[28:31], v[16:19], v[198:201], v[96:99]
	v_mfma_f32_16x16x32_bf16 v[72:75], v[164:167], v[202:205], v[28:31]
	s_barrier
	ds_read_b128 v[124:127], v163
	ds_read_b128 v[234:237], v163 offset:1024
	ds_read_b128 v[238:241], v163 offset:2048
	ds_read_b128 v[242:245], v163 offset:3072
	s_waitcnt vmcnt(0)
	s_barrier
	s_waitcnt lgkmcnt(0)
	s_waitcnt lgkmcnt(0)
	v_mfma_f32_16x16x32_bf16 v[28:31], v[124:127], v[12:15], v[214:217]
	v_mfma_f32_16x16x32_bf16 v[12:15], v[238:241], v[12:15], v[178:181]
	v_mfma_f32_16x16x32_bf16 v[60:63], v[234:237], v[20:23], v[28:31]
	v_mfma_f32_16x16x32_bf16 v[28:31], v[242:245], v[20:23], v[12:15]
	v_mfma_f32_16x16x32_bf16 v[12:15], v[124:127], v[24:27], v[182:185]
	v_mfma_f32_16x16x32_bf16 v[56:59], v[234:237], v[44:47], v[12:15]
	v_mfma_f32_16x16x32_bf16 v[12:15], v[238:241], v[24:27], v[80:83]
	v_mfma_f32_16x16x32_bf16 v[24:27], v[242:245], v[44:47], v[12:15]
	v_mfma_f32_16x16x32_bf16 v[12:15], v[124:127], v[168:171], v[76:79]
	v_mfma_f32_16x16x32_bf16 v[52:55], v[234:237], v[194:197], v[12:15]
	v_mfma_f32_16x16x32_bf16 v[12:15], v[238:241], v[168:171], v[186:189]
	v_mfma_f32_16x16x32_bf16 v[20:23], v[242:245], v[194:197], v[12:15]
	v_mfma_f32_16x16x32_bf16 v[12:15], v[124:127], v[198:201], v[68:71]
	v_mfma_f32_16x16x32_bf16 v[44:47], v[234:237], v[202:205], v[12:15]
	v_mfma_f32_16x16x32_bf16 v[12:15], v[238:241], v[198:201], v[64:67]
	v_mfma_f32_16x16x32_bf16 v[12:15], v[242:245], v[202:205], v[12:15]
	s_barrier
	ds_read_b128 v[168:171], v162 offset:49152
	ds_read_b128 v[178:181], v162 offset:50176
	ds_read_b128 v[182:185], v161 offset:49152
	ds_read_b128 v[186:189], v161 offset:50176
	ds_read_b128 v[194:197], v160 offset:49152
	ds_read_b128 v[160:163], v160 offset:50176
	ds_read_b128 v[198:201], v159 offset:49152
	ds_read_b128 v[156:159], v159 offset:50176
	s_barrier
	s_waitcnt lgkmcnt(0)
	s_waitcnt lgkmcnt(0)
	v_mfma_f32_16x16x32_bf16 v[64:67], v[4:7], v[168:171], v[208:211]
	v_mfma_f32_16x16x32_bf16 v[112:115], v[8:11], v[178:181], v[64:67]
	v_mfma_f32_16x16x32_bf16 v[64:67], v[16:19], v[168:171], v[218:221]
	v_mfma_f32_16x16x32_bf16 v[48:51], v[16:19], v[182:185], v[48:51]
	v_mfma_f32_16x16x32_bf16 v[80:83], v[164:167], v[178:181], v[64:67]
	v_mfma_f32_16x16x32_bf16 v[64:67], v[4:7], v[182:185], v[222:225]
	v_mfma_f32_16x16x32_bf16 v[76:79], v[164:167], v[186:189], v[48:51]
	v_mfma_f32_16x16x32_bf16 v[48:51], v[4:7], v[194:197], v[226:229]
	v_mfma_f32_16x16x32_bf16 v[4:7], v[4:7], v[198:201], v[36:39]
	v_mfma_f32_16x16x32_bf16 v[40:43], v[16:19], v[194:197], v[40:43]
	v_mfma_f32_16x16x32_bf16 v[96:99], v[8:11], v[156:159], v[4:7]
	v_mfma_f32_16x16x32_bf16 v[4:7], v[16:19], v[198:201], v[32:35]
	v_mfma_f32_16x16x32_bf16 v[104:107], v[8:11], v[186:189], v[64:67]
	v_mfma_f32_16x16x32_bf16 v[100:103], v[8:11], v[160:163], v[48:51]
	v_mfma_f32_16x16x32_bf16 v[68:71], v[164:167], v[160:163], v[40:43]
	v_mfma_f32_16x16x32_bf16 v[64:67], v[164:167], v[156:159], v[4:7]
	v_mfma_f32_16x16x32_bf16 v[4:7], v[124:127], v[168:171], v[136:139]
	v_mfma_f32_16x16x32_bf16 v[48:51], v[234:237], v[178:181], v[4:7]
	v_mfma_f32_16x16x32_bf16 v[4:7], v[238:241], v[168:171], v[144:147]
	v_mfma_f32_16x16x32_bf16 v[16:19], v[242:245], v[178:181], v[4:7]
	v_mfma_f32_16x16x32_bf16 v[4:7], v[124:127], v[182:185], v[148:151]
	v_mfma_f32_16x16x32_bf16 v[40:43], v[234:237], v[186:189], v[4:7]
	v_mfma_f32_16x16x32_bf16 v[4:7], v[238:241], v[182:185], v[174:177]
	v_mfma_f32_16x16x32_bf16 v[8:11], v[242:245], v[186:189], v[4:7]
	v_mfma_f32_16x16x32_bf16 v[4:7], v[124:127], v[194:197], v[230:233]
	v_mfma_f32_16x16x32_bf16 v[36:39], v[234:237], v[160:163], v[4:7]
	v_mfma_f32_16x16x32_bf16 v[4:7], v[238:241], v[194:197], v[190:193]
	v_mfma_f32_16x16x32_bf16 v[32:35], v[124:127], v[198:201], v[140:143]
	v_mfma_f32_16x16x32_bf16 v[0:3], v[238:241], v[198:201], v[0:3]
	v_mfma_f32_16x16x32_bf16 v[4:7], v[242:245], v[160:163], v[4:7]
	v_mfma_f32_16x16x32_bf16 v[32:35], v[234:237], v[156:159], v[32:35]
	v_mfma_f32_16x16x32_bf16 v[0:3], v[242:245], v[156:159], v[0:3]
	s_movk_i32 s19, 0x100
	v_cmp_gt_u32_e32 vcc, s19, v154
	s_barrier
	s_and_saveexec_b64 s[52:53], vcc
	s_cbranch_execnz .LBB0_1189
	s_or_b64 exec, exec, s[52:53]
	s_andn2_b64 vcc, exec, s[50:51]
	s_cbranch_vccz .LBB0_1190

; #define STAGE(P, BASE, br, kt) STAGET(tid_, P, BASE, br, kt)
; #define LDA(dst, b, h) UFOR(m, 4) UFOR(k, 2) \
;     dst[m][k] = *reinterpret_cast<const bf16x8*>((char*)SA(b, h) + lds_byte(wr * 64 + m * 16 + fr, k * 32 + fq * 8))
; #define LDB(dst, b, h) UFOR(n, 2) UFOR(k, 2) \
;     dst[n][k] = *reinterpret_cast<const bf16x8*>((char*)SB(b, h) + lds_byte(wc * 32 + n * 16 + fr, k * 32 + fq * 8))
; #define MMA(ai, bj, At, Bq) do { __builtin_amdgcn_s_setprio(1); \
;     UFOR(m, 4) UFOR(n, 2) UFOR(k, 2) \
;       acc[ai][bj][m][n] = __builtin_amdgcn_mfma_f32_16x16x32_bf16(Bq[n][k], At[m][k], acc[ai][bj][m][n], 0, 0, 0); \
;     __builtin_amdgcn_s_setprio(0); } while (0)
; #define WAIT_V(n) asm volatile("s_waitcnt vmcnt(" #n ")" ::: "memory")
; #define WAIT_L(n) asm volatile("s_waitcnt lgkmcnt(" #n ")" ::: "memory")
; #define BAR __builtin_amdgcn_s_barrier()
; #define SCHED __builtin_amdgcn_sched_barrier(0)
; template <int EPI, int K, int KL> ...
;     ...
;     LDB(B0, 0, 0); SCHED; LDA(At, 0, 0); STAGE(SA(1, 1), A, brow + HALF, t + 1);
;     WAIT_L(8); BAR; WAIT_L(0); MMA(0, 0, At, B0); BAR; SCHED;
;     LDB(B1, 0, 1); STAGE(SB(0, 0), Bt, bcol, t + 2);
;     BAR; WAIT_L(0); MMA(0, 1, At, B1); BAR;
;     LDA(At, 0, 1); STAGE(SA(0, 0), A, brow, t + 2);
;     BAR; WAIT_L(0); MMA(1, 0, At, B0); BAR; SCHED;
;     STAGE(SB(0, 1), Bt, bcol + HALF, t + 2);
;     WAIT_V(6); BAR; MMA(1, 1, At, B1); BAR;
;     LDB(B0, 1, 0); SCHED; LDA(At, 1, 0); STAGE(SA(0, 1), A, brow + HALF, t + 2);
;     WAIT_L(8); BAR; WAIT_L(0); MMA(0, 0, At, B0); BAR; SCHED;
;     LDB(B1, 1, 1); STAGE(SB(1, 0), Bt, bcol, t + 3);
;     BAR; WAIT_L(0); MMA(0, 1, At, B1); BAR;
.LBB0_1204:
	ds_read_b128 v[136:139], v175
	ds_read_b128 v[178:181], v175 offset:1024
	ds_read_b128 v[182:185], v175 offset:2048
	ds_read_b128 v[186:189], v175 offset:3072
	ds_read_b128 v[190:193], v160
	ds_read_b128 v[194:197], v160 offset:1024
	ds_read_b128 v[198:201], v159
	ds_read_b128 v[202:205], v159 offset:1024
	ds_read_b128 v[208:211], v158
	ds_read_b128 v[214:217], v158 offset:1024
	ds_read_b128 v[218:221], v157
	ds_read_b128 v[222:225], v157 offset:1024
	v_add_u32_e32 v176, 0xc000, v161
	v_lshl_add_u64 v[152:153], v[148:149], 0, s[44:45]
	v_readfirstlane_b32 s15, v176
	v_lshl_add_u64 v[154:155], v[152:153], 0, s[58:59]
	s_mov_b32 m0, s15
	v_add_u32_e32 v177, 0xe000, v161
	global_load_lds_dwordx4 v[154:155], off
	v_lshl_add_u64 v[154:155], v[150:151], 0, s[44:45]
	v_readfirstlane_b32 s15, v177
	v_lshl_add_u64 v[226:227], v[154:155], 0, s[58:59]
	s_mov_b32 m0, s15
	s_nop 0
	global_load_lds_dwordx4 v[226:227], off
	s_waitcnt lgkmcnt(8)
	s_barrier
	s_waitcnt lgkmcnt(0)
	s_waitcnt lgkmcnt(0)
	v_mfma_f32_16x16x32_bf16 v[124:127], v[136:139], v[190:193], v[124:127]
	v_mfma_f32_16x16x32_bf16 v[120:123], v[182:185], v[190:193], v[120:123]
	v_mfma_f32_16x16x32_bf16 v[116:119], v[136:139], v[198:201], v[116:119]
	v_mfma_f32_16x16x32_bf16 v[112:115], v[182:185], v[198:201], v[112:115]
	v_mfma_f32_16x16x32_bf16 v[108:111], v[136:139], v[208:211], v[108:111]
	v_mfma_f32_16x16x32_bf16 v[104:107], v[182:185], v[208:211], v[104:107]
	v_mfma_f32_16x16x32_bf16 v[100:103], v[136:139], v[218:221], v[100:103]
	v_mfma_f32_16x16x32_bf16 v[96:99], v[182:185], v[218:221], v[96:99]
	v_mfma_f32_16x16x32_bf16 v[124:127], v[178:181], v[194:197], v[124:127]
	v_mfma_f32_16x16x32_bf16 v[120:123], v[186:189], v[194:197], v[120:123]
	v_mfma_f32_16x16x32_bf16 v[116:119], v[178:181], v[202:205], v[116:119]
	v_mfma_f32_16x16x32_bf16 v[112:115], v[186:189], v[202:205], v[112:115]
	v_mfma_f32_16x16x32_bf16 v[108:111], v[178:181], v[214:217], v[108:111]
	v_mfma_f32_16x16x32_bf16 v[104:107], v[186:189], v[214:217], v[104:107]
	v_mfma_f32_16x16x32_bf16 v[100:103], v[178:181], v[222:225], v[100:103]
	v_mfma_f32_16x16x32_bf16 v[96:99], v[186:189], v[222:225], v[96:99]
	s_barrier
	ds_read_b128 v[226:229], v173
	ds_read_b128 v[230:233], v173 offset:1024
	ds_read_b128 v[234:237], v173 offset:2048
	ds_read_b128 v[238:241], v173 offset:3072
	v_lshl_add_u64 v[242:243], v[144:145], 0, s[44:45]
	v_readfirstlane_b32 s15, v156
	v_lshl_add_u64 v[244:245], v[242:243], 0, s[22:23]
	s_mov_b32 m0, s15
	v_add_u32_e32 v248, 0x2000, v156
	global_load_lds_dwordx4 v[244:245], off
	v_lshl_add_u64 v[244:245], v[146:147], 0, s[44:45]
	v_readfirstlane_b32 s15, v248
	v_lshl_add_u64 v[246:247], v[244:245], 0, s[22:23]
	s_mov_b32 m0, s15
	s_nop 0
	global_load_lds_dwordx4 v[246:247], off
	s_barrier
	s_waitcnt lgkmcnt(0)
	s_waitcnt lgkmcnt(0)
	v_mfma_f32_16x16x32_bf16 v[92:95], v[226:229], v[190:193], v[92:95]
	v_mfma_f32_16x16x32_bf16 v[88:91], v[234:237], v[190:193], v[88:91]
	v_mfma_f32_16x16x32_bf16 v[84:87], v[226:229], v[198:201], v[84:87]
	v_mfma_f32_16x16x32_bf16 v[80:83], v[234:237], v[198:201], v[80:83]
	v_mfma_f32_16x16x32_bf16 v[76:79], v[226:229], v[208:211], v[76:79]
	v_mfma_f32_16x16x32_bf16 v[72:75], v[234:237], v[208:211], v[72:75]
	v_mfma_f32_16x16x32_bf16 v[68:71], v[226:229], v[218:221], v[68:71]
	v_mfma_f32_16x16x32_bf16 v[64:67], v[234:237], v[218:221], v[64:67]
	v_mfma_f32_16x16x32_bf16 v[92:95], v[230:233], v[194:197], v[92:95]
	v_mfma_f32_16x16x32_bf16 v[88:91], v[238:241], v[194:197], v[88:91]
	v_mfma_f32_16x16x32_bf16 v[84:87], v[230:233], v[202:205], v[84:87]
	v_mfma_f32_16x16x32_bf16 v[80:83], v[238:241], v[202:205], v[80:83]
	v_mfma_f32_16x16x32_bf16 v[76:79], v[230:233], v[214:217], v[76:79]
	v_mfma_f32_16x16x32_bf16 v[72:75], v[238:241], v[214:217], v[72:75]
	v_mfma_f32_16x16x32_bf16 v[68:71], v[230:233], v[222:225], v[68:71]
	v_mfma_f32_16x16x32_bf16 v[64:67], v[238:241], v[222:225], v[64:67]
	v_readfirstlane_b32 s15, v161
	v_lshl_add_u64 v[246:247], v[152:153], 0, s[60:61]
	s_mov_b32 m0, s15
	v_readfirstlane_b32 s15, v162
	s_barrier
	ds_read_b128 v[190:193], v160 offset:16384
	ds_read_b128 v[194:197], v160 offset:17408
	ds_read_b128 v[198:201], v159 offset:16384
	ds_read_b128 v[202:205], v159 offset:17408
	ds_read_b128 v[208:211], v158 offset:16384
	ds_read_b128 v[214:217], v158 offset:17408
	ds_read_b128 v[218:221], v157 offset:16384
	ds_read_b128 v[222:225], v157 offset:17408
	global_load_lds_dwordx4 v[246:247], off
	v_lshl_add_u64 v[246:247], v[154:155], 0, s[60:61]
	s_mov_b32 m0, s15
	s_nop 0
	global_load_lds_dwordx4 v[246:247], off
	s_barrier
	s_waitcnt lgkmcnt(0)
	s_waitcnt lgkmcnt(0)
	v_mfma_f32_16x16x32_bf16 v[60:63], v[136:139], v[190:193], v[60:63]
	v_mfma_f32_16x16x32_bf16 v[56:59], v[182:185], v[190:193], v[56:59]
	v_mfma_f32_16x16x32_bf16 v[52:55], v[136:139], v[198:201], v[52:55]
	v_mfma_f32_16x16x32_bf16 v[48:51], v[182:185], v[198:201], v[48:51]
	v_mfma_f32_16x16x32_bf16 v[44:47], v[136:139], v[208:211], v[44:47]
	v_mfma_f32_16x16x32_bf16 v[40:43], v[182:185], v[208:211], v[40:43]
	v_mfma_f32_16x16x32_bf16 v[36:39], v[136:139], v[218:221], v[36:39]
	v_mfma_f32_16x16x32_bf16 v[32:35], v[182:185], v[218:221], v[32:35]
	v_mfma_f32_16x16x32_bf16 v[60:63], v[178:181], v[194:197], v[60:63]
	v_mfma_f32_16x16x32_bf16 v[56:59], v[186:189], v[194:197], v[56:59]
	v_mfma_f32_16x16x32_bf16 v[52:55], v[178:181], v[202:205], v[52:55]
	v_mfma_f32_16x16x32_bf16 v[48:51], v[186:189], v[202:205], v[48:51]
	v_mfma_f32_16x16x32_bf16 v[44:47], v[178:181], v[214:217], v[44:47]
	v_mfma_f32_16x16x32_bf16 v[40:43], v[186:189], v[214:217], v[40:43]
	v_mfma_f32_16x16x32_bf16 v[36:39], v[178:181], v[222:225], v[36:39]
	v_mfma_f32_16x16x32_bf16 v[32:35], v[186:189], v[222:225], v[32:35]
	s_barrier
; #define STAGE(P, BASE, br, kt) STAGET(tid_, P, BASE, br, kt)
; #define LDA(dst, b, h) UFOR(m, 4) UFOR(k, 2) \
;     dst[m][k] = *reinterpret_cast<const bf16x8*>((char*)SA(b, h) + lds_byte(wr * 64 + m * 16 + fr, k * 32 + fq * 8))
; #define LDB(dst, b, h) UFOR(n, 2) UFOR(k, 2) \
;     dst[n][k] = *reinterpret_cast<const bf16x8*>((char*)SB(b, h) + lds_byte(wc * 32 + n * 16 + fr, k * 32 + fq * 8))
; #define MMA(ai, bj, At, Bq) do { __builtin_amdgcn_s_setprio(1); \
;     UFOR(m, 4) UFOR(n, 2) UFOR(k, 2) \
;       acc[ai][bj][m][n] = __builtin_amdgcn_mfma_f32_16x16x32_bf16(Bq[n][k], At[m][k], acc[ai][bj][m][n], 0, 0, 0); \
;     __builtin_amdgcn_s_setprio(0); } while (0)
; #define WAIT_V(n) asm volatile("s_waitcnt vmcnt(" #n ")" ::: "memory")
; #define WAIT_L(n) asm volatile("s_waitcnt lgkmcnt(" #n ")" ::: "memory")
; #define BAR __builtin_amdgcn_s_barrier()
; #define SCHED __builtin_amdgcn_sched_barrier(0)
; template <int EPI, int K, int KL> ...
;     ...
;     STAGE(SB(0, 1), Bt, bcol + HALF, t + 2);
;     WAIT_V(6); BAR; MMA(1, 1, At, B1); BAR;
;     LDB(B0, 1, 0); SCHED; LDA(At, 1, 0); STAGE(SA(0, 1), A, brow + HALF, t + 2);
;     WAIT_L(8); BAR; WAIT_L(0); MMA(0, 0, At, B0); BAR; SCHED;
;     LDB(B1, 1, 1); STAGE(SB(1, 0), Bt, bcol, t + 3);
;     BAR; WAIT_L(0); MMA(0, 1, At, B1); BAR;
;     LDA(At, 1, 1); STAGE(SA(1, 0), A, brow, t + 3);
;     BAR; WAIT_L(0); MMA(1, 0, At, B0); BAR; SCHED;
;     STAGE(SB(1, 1), Bt, bcol + HALF, t + 3);
;     WAIT_V(6); BAR; MMA(1, 1, At, B1); BAR;
	v_readfirstlane_b32 s15, v164
	v_add_u32_e32 v138, 0x2000, v164
	v_lshl_add_u64 v[136:137], v[242:243], 0, s[24:25]
	s_mov_b32 m0, s15
	v_readfirstlane_b32 s15, v138
	global_load_lds_dwordx4 v[136:137], off
	v_lshl_add_u64 v[136:137], v[244:245], 0, s[24:25]
	s_mov_b32 m0, s15
	s_nop 0
	global_load_lds_dwordx4 v[136:137], off
	s_waitcnt vmcnt(6)
	s_barrier
	v_mfma_f32_16x16x32_bf16 v[28:31], v[226:229], v[190:193], v[28:31]
	v_mfma_f32_16x16x32_bf16 v[24:27], v[234:237], v[190:193], v[24:27]
	v_mfma_f32_16x16x32_bf16 v[20:23], v[226:229], v[198:201], v[20:23]
	v_mfma_f32_16x16x32_bf16 v[16:19], v[234:237], v[198:201], v[16:19]
	v_mfma_f32_16x16x32_bf16 v[12:15], v[226:229], v[208:211], v[12:15]
	v_mfma_f32_16x16x32_bf16 v[8:11], v[234:237], v[208:211], v[8:11]
	v_mfma_f32_16x16x32_bf16 v[4:7], v[226:229], v[218:221], v[4:7]
	v_mfma_f32_16x16x32_bf16 v[0:3], v[234:237], v[218:221], v[0:3]
	v_mfma_f32_16x16x32_bf16 v[28:31], v[230:233], v[194:197], v[28:31]
	v_mfma_f32_16x16x32_bf16 v[24:27], v[238:241], v[194:197], v[24:27]
	v_mfma_f32_16x16x32_bf16 v[20:23], v[230:233], v[202:205], v[20:23]
	v_mfma_f32_16x16x32_bf16 v[16:19], v[238:241], v[202:205], v[16:19]
	v_mfma_f32_16x16x32_bf16 v[12:15], v[230:233], v[214:217], v[12:15]
	v_mfma_f32_16x16x32_bf16 v[8:11], v[238:241], v[214:217], v[8:11]
	v_mfma_f32_16x16x32_bf16 v[4:7], v[230:233], v[222:225], v[4:7]
	v_mfma_f32_16x16x32_bf16 v[0:3], v[238:241], v[222:225], v[0:3]
	s_barrier
	ds_read_b128 v[136:139], v166
	ds_read_b128 v[178:181], v166 offset:1024
	ds_read_b128 v[182:185], v166 offset:2048
	ds_read_b128 v[186:189], v166 offset:3072
	ds_read_b128 v[190:193], v160 offset:32768
	ds_read_b128 v[194:197], v160 offset:33792
	ds_read_b128 v[198:201], v159 offset:32768
	ds_read_b128 v[202:205], v159 offset:33792
	ds_read_b128 v[208:211], v158 offset:32768
	ds_read_b128 v[214:217], v158 offset:33792
	ds_read_b128 v[218:221], v157 offset:32768
	ds_read_b128 v[222:225], v157 offset:33792
	v_readfirstlane_b32 s15, v165
	v_lshl_add_u64 v[226:227], v[152:153], 0, s[62:63]
	s_mov_b32 m0, s15
	v_readfirstlane_b32 s15, v167
	global_load_lds_dwordx4 v[226:227], off
	v_lshl_add_u64 v[226:227], v[154:155], 0, s[62:63]
	s_mov_b32 m0, s15
	s_nop 0
	global_load_lds_dwordx4 v[226:227], off
	s_waitcnt lgkmcnt(8)
	s_barrier
	s_waitcnt lgkmcnt(0)
	s_waitcnt lgkmcnt(0)
	v_mfma_f32_16x16x32_bf16 v[124:127], v[136:139], v[190:193], v[124:127]
	v_mfma_f32_16x16x32_bf16 v[120:123], v[182:185], v[190:193], v[120:123]
	v_mfma_f32_16x16x32_bf16 v[116:119], v[136:139], v[198:201], v[116:119]
	v_mfma_f32_16x16x32_bf16 v[112:115], v[182:185], v[198:201], v[112:115]
	v_mfma_f32_16x16x32_bf16 v[108:111], v[136:139], v[208:211], v[108:111]
	v_mfma_f32_16x16x32_bf16 v[104:107], v[182:185], v[208:211], v[104:107]
	v_mfma_f32_16x16x32_bf16 v[100:103], v[136:139], v[218:221], v[100:103]
	v_mfma_f32_16x16x32_bf16 v[96:99], v[182:185], v[218:221], v[96:99]
	v_mfma_f32_16x16x32_bf16 v[124:127], v[178:181], v[194:197], v[124:127]
	v_mfma_f32_16x16x32_bf16 v[120:123], v[186:189], v[194:197], v[120:123]
	v_mfma_f32_16x16x32_bf16 v[116:119], v[178:181], v[202:205], v[116:119]
	v_mfma_f32_16x16x32_bf16 v[112:115], v[186:189], v[202:205], v[112:115]
	v_mfma_f32_16x16x32_bf16 v[108:111], v[178:181], v[214:217], v[108:111]
	v_mfma_f32_16x16x32_bf16 v[104:107], v[186:189], v[214:217], v[104:107]
	v_mfma_f32_16x16x32_bf16 v[100:103], v[178:181], v[222:225], v[100:103]
	v_mfma_f32_16x16x32_bf16 v[96:99], v[186:189], v[222:225], v[96:99]
	s_barrier
	ds_read_b128 v[226:229], v163
	ds_read_b128 v[230:233], v163 offset:1024
	ds_read_b128 v[234:237], v163 offset:2048
	ds_read_b128 v[238:241], v163 offset:3072
	v_readfirstlane_b32 s15, v168
	v_lshl_add_u64 v[246:247], v[242:243], 0, s[94:95]
	s_mov_b32 m0, s15
	v_readfirstlane_b32 s15, v169
	global_load_lds_dwordx4 v[246:247], off
	v_lshl_add_u64 v[246:247], v[244:245], 0, s[94:95]
	s_mov_b32 m0, s15
	s_nop 0
	global_load_lds_dwordx4 v[246:247], off
	s_barrier
	s_waitcnt lgkmcnt(0)
	s_waitcnt lgkmcnt(0)
	v_mfma_f32_16x16x32_bf16 v[92:95], v[226:229], v[190:193], v[92:95]
	v_mfma_f32_16x16x32_bf16 v[88:91], v[234:237], v[190:193], v[88:91]
	v_mfma_f32_16x16x32_bf16 v[84:87], v[226:229], v[198:201], v[84:87]
	v_mfma_f32_16x16x32_bf16 v[80:83], v[234:237], v[198:201], v[80:83]
	v_mfma_f32_16x16x32_bf16 v[76:79], v[226:229], v[208:211], v[76:79]
	v_mfma_f32_16x16x32_bf16 v[72:75], v[234:237], v[208:211], v[72:75]
	v_mfma_f32_16x16x32_bf16 v[68:71], v[226:229], v[218:221], v[68:71]
	v_mfma_f32_16x16x32_bf16 v[64:67], v[234:237], v[218:221], v[64:67]
	v_mfma_f32_16x16x32_bf16 v[92:95], v[230:233], v[194:197], v[92:95]
	v_mfma_f32_16x16x32_bf16 v[88:91], v[238:241], v[194:197], v[88:91]
	v_mfma_f32_16x16x32_bf16 v[84:87], v[230:233], v[202:205], v[84:87]
	v_mfma_f32_16x16x32_bf16 v[80:83], v[238:241], v[202:205], v[80:83]
	v_mfma_f32_16x16x32_bf16 v[76:79], v[230:233], v[214:217], v[76:79]
	v_mfma_f32_16x16x32_bf16 v[72:75], v[238:241], v[214:217], v[72:75]
	v_mfma_f32_16x16x32_bf16 v[68:71], v[230:233], v[222:225], v[68:71]
	v_mfma_f32_16x16x32_bf16 v[64:67], v[238:241], v[222:225], v[64:67]
	v_readfirstlane_b32 s15, v170
	v_lshl_add_u64 v[152:153], v[152:153], 0, s[64:65]
	s_mov_b32 m0, s15
	v_readfirstlane_b32 s15, v171
	s_barrier
	ds_read_b128 v[190:193], v160 offset:49152
	ds_read_b128 v[194:197], v160 offset:50176
	ds_read_b128 v[198:201], v159 offset:49152
	ds_read_b128 v[202:205], v159 offset:50176
	ds_read_b128 v[208:211], v158 offset:49152
	ds_read_b128 v[214:217], v158 offset:50176
	ds_read_b128 v[218:221], v157 offset:49152
	ds_read_b128 v[222:225], v157 offset:50176
	global_load_lds_dwordx4 v[152:153], off
	v_lshl_add_u64 v[152:153], v[154:155], 0, s[64:65]
	s_mov_b32 m0, s15
	s_nop 0
	global_load_lds_dwordx4 v[152:153], off
	s_barrier
; #define STAGE(P, BASE, br, kt) STAGET(tid_, P, BASE, br, kt)
; #define LDA(dst, b, h) UFOR(m, 4) UFOR(k, 2) \
;     dst[m][k] = *reinterpret_cast<const bf16x8*>((char*)SA(b, h) + lds_byte(wr * 64 + m * 16 + fr, k * 32 + fq * 8))
; #define LDB(dst, b, h) UFOR(n, 2) UFOR(k, 2) \
;     dst[n][k] = *reinterpret_cast<const bf16x8*>((char*)SB(b, h) + lds_byte(wc * 32 + n * 16 + fr, k * 32 + fq * 8))
; #define MMA(ai, bj, At, Bq) do { __builtin_amdgcn_s_setprio(1); \
;     UFOR(m, 4) UFOR(n, 2) UFOR(k, 2) \
;       acc[ai][bj][m][n] = __builtin_amdgcn_mfma_f32_16x16x32_bf16(Bq[n][k], At[m][k], acc[ai][bj][m][n], 0, 0, 0); \
;     __builtin_amdgcn_s_setprio(0); } while (0)
; #define WAIT_V(n) asm volatile("s_waitcnt vmcnt(" #n ")" ::: "memory")
; #define WAIT_L(n) asm volatile("s_waitcnt lgkmcnt(" #n ")" ::: "memory")
; #define BAR __builtin_amdgcn_s_barrier()
; #define SCHED __builtin_amdgcn_sched_barrier(0)
; template <int EPI, int K, int KL> ...
;     ...
;     LDA(At, 1, 1); STAGE(SA(1, 0), A, brow, t + 3);
;     BAR; WAIT_L(0); MMA(1, 0, At, B0); BAR; SCHED;
;     STAGE(SB(1, 1), Bt, bcol + HALF, t + 3);
;     WAIT_V(6); BAR; MMA(1, 1, At, B1); BAR;
;   }
;   { LDB(B0, 0, 0); LDA(At, 0, 0); STAGE(SA(1, 1), A, brow + HALF, nt - 1);
;     BAR; WAIT_L(0); MMA(0, 0, At, B0); BAR;
;     LDB(B1, 0, 1); BAR; WAIT_L(0); MMA(0, 1, At, B1); BAR;
	s_waitcnt lgkmcnt(0)
	s_waitcnt lgkmcnt(0)
	v_mfma_f32_16x16x32_bf16 v[60:63], v[136:139], v[190:193], v[60:63]
	v_mfma_f32_16x16x32_bf16 v[56:59], v[182:185], v[190:193], v[56:59]
	v_mfma_f32_16x16x32_bf16 v[52:55], v[136:139], v[198:201], v[52:55]
	v_mfma_f32_16x16x32_bf16 v[48:51], v[182:185], v[198:201], v[48:51]
	v_mfma_f32_16x16x32_bf16 v[44:47], v[136:139], v[208:211], v[44:47]
	v_mfma_f32_16x16x32_bf16 v[40:43], v[182:185], v[208:211], v[40:43]
	v_mfma_f32_16x16x32_bf16 v[36:39], v[136:139], v[218:221], v[36:39]
	v_mfma_f32_16x16x32_bf16 v[32:35], v[182:185], v[218:221], v[32:35]
	v_mfma_f32_16x16x32_bf16 v[60:63], v[178:181], v[194:197], v[60:63]
	v_mfma_f32_16x16x32_bf16 v[56:59], v[186:189], v[194:197], v[56:59]
	v_mfma_f32_16x16x32_bf16 v[52:55], v[178:181], v[202:205], v[52:55]
	v_mfma_f32_16x16x32_bf16 v[48:51], v[186:189], v[202:205], v[48:51]
	v_mfma_f32_16x16x32_bf16 v[44:47], v[178:181], v[214:217], v[44:47]
	v_mfma_f32_16x16x32_bf16 v[40:43], v[186:189], v[214:217], v[40:43]
	v_mfma_f32_16x16x32_bf16 v[36:39], v[178:181], v[222:225], v[36:39]
	v_mfma_f32_16x16x32_bf16 v[32:35], v[186:189], v[222:225], v[32:35]
	s_barrier
	v_readfirstlane_b32 s15, v172
	v_lshl_add_u64 v[136:137], v[242:243], 0, s[10:11]
	s_mov_b32 m0, s15
	v_readfirstlane_b32 s15, v174
	global_load_lds_dwordx4 v[136:137], off
	v_lshl_add_u64 v[136:137], v[244:245], 0, s[10:11]
	s_mov_b32 m0, s15
	s_nop 0
	global_load_lds_dwordx4 v[136:137], off
	s_waitcnt vmcnt(6)
	s_barrier
	v_mfma_f32_16x16x32_bf16 v[28:31], v[226:229], v[190:193], v[28:31]
	v_mfma_f32_16x16x32_bf16 v[24:27], v[234:237], v[190:193], v[24:27]
	v_mfma_f32_16x16x32_bf16 v[20:23], v[226:229], v[198:201], v[20:23]
	v_mfma_f32_16x16x32_bf16 v[16:19], v[234:237], v[198:201], v[16:19]
	v_mfma_f32_16x16x32_bf16 v[12:15], v[226:229], v[208:211], v[12:15]
	v_mfma_f32_16x16x32_bf16 v[8:11], v[234:237], v[208:211], v[8:11]
	v_mfma_f32_16x16x32_bf16 v[4:7], v[226:229], v[218:221], v[4:7]
	v_mfma_f32_16x16x32_bf16 v[0:3], v[234:237], v[218:221], v[0:3]
	v_mfma_f32_16x16x32_bf16 v[28:31], v[230:233], v[194:197], v[28:31]
	v_mfma_f32_16x16x32_bf16 v[24:27], v[238:241], v[194:197], v[24:27]
	v_mfma_f32_16x16x32_bf16 v[20:23], v[230:233], v[202:205], v[20:23]
	v_mfma_f32_16x16x32_bf16 v[16:19], v[238:241], v[202:205], v[16:19]
	v_mfma_f32_16x16x32_bf16 v[12:15], v[230:233], v[214:217], v[12:15]
	v_mfma_f32_16x16x32_bf16 v[8:11], v[238:241], v[214:217], v[8:11]
	v_mfma_f32_16x16x32_bf16 v[4:7], v[230:233], v[222:225], v[4:7]
	v_mfma_f32_16x16x32_bf16 v[0:3], v[238:241], v[222:225], v[0:3]
	s_add_i32 s14, s14, 2
	v_lshl_add_u64 v[144:145], v[144:145], 0, s[20:21]
	v_lshl_add_u64 v[146:147], v[146:147], 0, s[20:21]
	v_lshl_add_u64 v[148:149], v[148:149], 0, s[20:21]
	s_cmp_lt_u32 s14, 4
	v_lshl_add_u64 v[150:151], v[150:151], 0, s[20:21]
	s_cbranch_scc1 .Lkrot_1204
	s_barrier
	s_add_u32 s14, s46, 0x160380
	s_addc_u32 s15, s47, 0
	v_lshl_add_u64 v[142:143], s[14:15], 0, v[142:143]
	v_readfirstlane_b32 s18, v176
	v_lshl_add_u64 v[128:129], v[128:129], 1, v[142:143]
	s_mov_b32 m0, s18
	ds_read_b128 v[136:139], v175
	ds_read_b128 v[144:147], v175 offset:1024
	ds_read_b128 v[148:151], v175 offset:2048
	ds_read_b128 v[168:171], v175 offset:3072
	ds_read_b128 v[178:181], v160
	ds_read_b128 v[182:185], v160 offset:1024
	ds_read_b128 v[186:189], v159
	ds_read_b128 v[190:193], v159 offset:1024
	ds_read_b128 v[194:197], v158
	ds_read_b128 v[198:201], v158 offset:1024
	ds_read_b128 v[202:205], v157
	ds_read_b128 v[208:211], v157 offset:1024
	global_load_lds_dwordx4 v[128:129], off
	v_lshl_add_u64 v[128:129], s[14:15], 0, v[140:141]
	v_readfirstlane_b32 s14, v177
	v_lshl_add_u64 v[128:129], v[130:131], 1, v[128:129]
	s_mov_b32 m0, s14
	s_nop 0
	global_load_lds_dwordx4 v[128:129], off
	s_barrier
	s_waitcnt lgkmcnt(0)
	s_waitcnt lgkmcnt(0)
	v_mfma_f32_16x16x32_bf16 v[124:127], v[136:139], v[178:181], v[124:127]
	v_mfma_f32_16x16x32_bf16 v[120:123], v[148:151], v[178:181], v[120:123]
	v_mfma_f32_16x16x32_bf16 v[116:119], v[136:139], v[186:189], v[116:119]
	v_mfma_f32_16x16x32_bf16 v[112:115], v[148:151], v[186:189], v[112:115]
	v_mfma_f32_16x16x32_bf16 v[108:111], v[136:139], v[194:197], v[108:111]
	v_mfma_f32_16x16x32_bf16 v[104:107], v[148:151], v[194:197], v[104:107]
	v_mfma_f32_16x16x32_bf16 v[100:103], v[136:139], v[202:205], v[100:103]
	v_mfma_f32_16x16x32_bf16 v[96:99], v[148:151], v[202:205], v[96:99]
	v_mfma_f32_16x16x32_bf16 v[124:127], v[144:147], v[182:185], v[124:127]
	v_mfma_f32_16x16x32_bf16 v[120:123], v[168:171], v[182:185], v[120:123]
	v_mfma_f32_16x16x32_bf16 v[116:119], v[144:147], v[190:193], v[116:119]
	v_mfma_f32_16x16x32_bf16 v[112:115], v[168:171], v[190:193], v[112:115]
	v_mfma_f32_16x16x32_bf16 v[108:111], v[144:147], v[198:201], v[108:111]
	v_mfma_f32_16x16x32_bf16 v[104:107], v[168:171], v[198:201], v[104:107]
	v_mfma_f32_16x16x32_bf16 v[100:103], v[144:147], v[208:211], v[100:103]
	v_mfma_f32_16x16x32_bf16 v[96:99], v[168:171], v[208:211], v[96:99]
	s_barrier
	ds_read_b128 v[128:131], v173
	ds_read_b128 v[140:143], v173 offset:1024
	ds_read_b128 v[174:177], v173 offset:2048
	ds_read_b128 v[214:217], v173 offset:3072
	s_barrier
; #define LDA(dst, b, h) UFOR(m, 4) UFOR(k, 2) \
;     dst[m][k] = *reinterpret_cast<const bf16x8*>((char*)SA(b, h) + lds_byte(wr * 64 + m * 16 + fr, k * 32 + fq * 8))
; #define LDB(dst, b, h) UFOR(n, 2) UFOR(k, 2) \
;     dst[n][k] = *reinterpret_cast<const bf16x8*>((char*)SB(b, h) + lds_byte(wc * 32 + n * 16 + fr, k * 32 + fq * 8))
; #define MMA(ai, bj, At, Bq) do { __builtin_amdgcn_s_setprio(1); \
;     UFOR(m, 4) UFOR(n, 2) UFOR(k, 2) \
;       acc[ai][bj][m][n] = __builtin_amdgcn_mfma_f32_16x16x32_bf16(Bq[n][k], At[m][k], acc[ai][bj][m][n], 0, 0, 0); \
;     __builtin_amdgcn_s_setprio(0); } while (0)
; #define WAIT_V(n) asm volatile("s_waitcnt vmcnt(" #n ")" ::: "memory")
; #define WAIT_L(n) asm volatile("s_waitcnt lgkmcnt(" #n ")" ::: "memory")
; #define BAR __builtin_amdgcn_s_barrier()
; template <int EPI, int K, int KL> ...
;     ...
;     LDB(B1, 0, 1); BAR; WAIT_L(0); MMA(0, 1, At, B1); BAR;
;     LDA(At, 0, 1); WAIT_V(4); BAR; WAIT_L(0); MMA(1, 0, At, B0); MMA(1, 1, At, B1); BAR; }
;   { LDB(B0, 1, 0); LDA(At, 1, 0); WAIT_V(2); BAR; WAIT_L(0); MMA(0, 0, At, B0); BAR;
	s_waitcnt lgkmcnt(0)
	s_waitcnt lgkmcnt(0)
	v_mfma_f32_16x16x32_bf16 v[92:95], v[128:131], v[178:181], v[92:95]
	v_mfma_f32_16x16x32_bf16 v[88:91], v[174:177], v[178:181], v[88:91]
	v_mfma_f32_16x16x32_bf16 v[84:87], v[128:131], v[186:189], v[84:87]
	v_mfma_f32_16x16x32_bf16 v[80:83], v[174:177], v[186:189], v[80:83]
	v_mfma_f32_16x16x32_bf16 v[76:79], v[128:131], v[194:197], v[76:79]
	v_mfma_f32_16x16x32_bf16 v[68:71], v[128:131], v[202:205], v[68:71]
	v_mfma_f32_16x16x32_bf16 v[64:67], v[174:177], v[202:205], v[64:67]
	v_mfma_f32_16x16x32_bf16 v[92:95], v[140:143], v[182:185], v[92:95]
	v_mfma_f32_16x16x32_bf16 v[88:91], v[214:217], v[182:185], v[88:91]
	v_mfma_f32_16x16x32_bf16 v[84:87], v[140:143], v[190:193], v[84:87]
	v_mfma_f32_16x16x32_bf16 v[80:83], v[214:217], v[190:193], v[80:83]
	v_mfma_f32_16x16x32_bf16 v[76:79], v[140:143], v[198:201], v[76:79]
	v_mfma_f32_16x16x32_bf16 v[72:75], v[174:177], v[194:197], v[72:75]
	v_mfma_f32_16x16x32_bf16 v[68:71], v[140:143], v[208:211], v[68:71]
	v_mfma_f32_16x16x32_bf16 v[64:67], v[214:217], v[208:211], v[64:67]
	v_mfma_f32_16x16x32_bf16 v[178:181], v[214:217], v[198:201], v[72:75]
	s_barrier
	s_nop 3
	ds_read_b128 v[72:75], v160 offset:16384
	ds_read_b128 v[182:185], v160 offset:17408
	ds_read_b128 v[186:189], v159 offset:16384
	ds_read_b128 v[190:193], v159 offset:17408
	ds_read_b128 v[194:197], v158 offset:16384
	ds_read_b128 v[198:201], v158 offset:17408
	ds_read_b128 v[202:205], v157 offset:16384
	ds_read_b128 v[208:211], v157 offset:17408
	s_waitcnt vmcnt(4)
	s_barrier
	s_waitcnt lgkmcnt(0)
	s_waitcnt lgkmcnt(0)
	v_mfma_f32_16x16x32_bf16 v[48:51], v[148:151], v[186:189], v[48:51]
	v_mfma_f32_16x16x32_bf16 v[60:63], v[136:139], v[72:75], v[60:63]
	v_mfma_f32_16x16x32_bf16 v[56:59], v[148:151], v[72:75], v[56:59]
	v_mfma_f32_16x16x32_bf16 v[52:55], v[136:139], v[186:189], v[52:55]
	v_mfma_f32_16x16x32_bf16 v[48:51], v[168:171], v[190:193], v[48:51]
	v_mfma_f32_16x16x32_bf16 v[44:47], v[136:139], v[194:197], v[44:47]
	v_mfma_f32_16x16x32_bf16 v[40:43], v[148:151], v[194:197], v[40:43]
	v_mfma_f32_16x16x32_bf16 v[36:39], v[136:139], v[202:205], v[36:39]
	v_mfma_f32_16x16x32_bf16 v[32:35], v[148:151], v[202:205], v[32:35]
	v_mfma_f32_16x16x32_bf16 v[218:221], v[144:147], v[182:185], v[60:63]
	v_mfma_f32_16x16x32_bf16 v[222:225], v[168:171], v[182:185], v[56:59]
	v_mfma_f32_16x16x32_bf16 v[226:229], v[144:147], v[190:193], v[52:55]
	v_mfma_f32_16x16x32_bf16 v[230:233], v[144:147], v[198:201], v[44:47]
	v_mfma_f32_16x16x32_bf16 v[234:237], v[168:171], v[198:201], v[40:43]
	v_mfma_f32_16x16x32_bf16 v[136:139], v[144:147], v[208:211], v[36:39]
	v_mfma_f32_16x16x32_bf16 v[144:147], v[168:171], v[208:211], v[32:35]
	v_mfma_f32_16x16x32_bf16 v[28:31], v[128:131], v[72:75], v[28:31]
	v_mfma_f32_16x16x32_bf16 v[24:27], v[174:177], v[72:75], v[24:27]
	v_mfma_f32_16x16x32_bf16 v[20:23], v[128:131], v[186:189], v[20:23]
	v_mfma_f32_16x16x32_bf16 v[16:19], v[174:177], v[186:189], v[16:19]
	v_mfma_f32_16x16x32_bf16 v[12:15], v[128:131], v[194:197], v[12:15]
	v_mfma_f32_16x16x32_bf16 v[8:11], v[174:177], v[194:197], v[8:11]
	v_mfma_f32_16x16x32_bf16 v[4:7], v[128:131], v[202:205], v[4:7]
	v_mfma_f32_16x16x32_bf16 v[0:3], v[174:177], v[202:205], v[0:3]
	v_mfma_f32_16x16x32_bf16 v[148:151], v[140:143], v[182:185], v[28:31]
	v_mfma_f32_16x16x32_bf16 v[168:171], v[214:217], v[182:185], v[24:27]
	v_mfma_f32_16x16x32_bf16 v[182:185], v[140:143], v[190:193], v[20:23]
	v_mfma_f32_16x16x32_bf16 v[186:189], v[214:217], v[190:193], v[16:19]
	v_mfma_f32_16x16x32_bf16 v[190:193], v[140:143], v[198:201], v[12:15]
	v_mfma_f32_16x16x32_bf16 v[194:197], v[214:217], v[198:201], v[8:11]
	v_mfma_f32_16x16x32_bf16 v[128:131], v[140:143], v[208:211], v[4:7]
	v_mfma_f32_16x16x32_bf16 v[140:143], v[214:217], v[208:211], v[0:3]
	s_barrier
	ds_read_b128 v[172:175], v166
	ds_read_b128 v[198:201], v166 offset:1024
	ds_read_b128 v[202:205], v166 offset:2048
	ds_read_b128 v[164:167], v166 offset:3072
	ds_read_b128 v[20:23], v160 offset:32768
	ds_read_b128 v[24:27], v160 offset:33792
	ds_read_b128 v[28:31], v159 offset:32768
	ds_read_b128 v[32:35], v159 offset:33792
	ds_read_b128 v[36:39], v158 offset:32768
	ds_read_b128 v[208:211], v158 offset:33792
	ds_read_b128 v[214:217], v157 offset:32768
	ds_read_b128 v[238:241], v157 offset:33792
	s_waitcnt vmcnt(2)
	s_barrier
; #define LDA(dst, b, h) UFOR(m, 4) UFOR(k, 2) \
;     dst[m][k] = *reinterpret_cast<const bf16x8*>((char*)SA(b, h) + lds_byte(wr * 64 + m * 16 + fr, k * 32 + fq * 8))
; #define LDB(dst, b, h) UFOR(n, 2) UFOR(k, 2) \
;     dst[n][k] = *reinterpret_cast<const bf16x8*>((char*)SB(b, h) + lds_byte(wc * 32 + n * 16 + fr, k * 32 + fq * 8))
; #define MMA(ai, bj, At, Bq) do { __builtin_amdgcn_s_setprio(1); \
;     UFOR(m, 4) UFOR(n, 2) UFOR(k, 2) \
;       acc[ai][bj][m][n] = __builtin_amdgcn_mfma_f32_16x16x32_bf16(Bq[n][k], At[m][k], acc[ai][bj][m][n], 0, 0, 0); \
;     __builtin_amdgcn_s_setprio(0); } while (0)
; #define WAIT_V(n) asm volatile("s_waitcnt vmcnt(" #n ")" ::: "memory")
; #define WAIT_L(n) asm volatile("s_waitcnt lgkmcnt(" #n ")" ::: "memory")
; #define BAR __builtin_amdgcn_s_barrier()
; template <int EPI, int K, int KL> ...
;     ...
;   { LDB(B0, 1, 0); LDA(At, 1, 0); WAIT_V(2); BAR; WAIT_L(0); MMA(0, 0, At, B0); BAR;
;     LDB(B1, 1, 1); WAIT_V(0); BAR; WAIT_L(0); MMA(0, 1, At, B1); BAR;
;     LDA(At, 1, 1); BAR; WAIT_L(0); MMA(1, 0, At, B0); MMA(1, 1, At, B1); BAR; }
;   if (wr == 0) BAR;
	s_waitcnt lgkmcnt(0)
	s_waitcnt lgkmcnt(0)
	v_mfma_f32_16x16x32_bf16 v[0:3], v[172:175], v[20:23], v[124:127]
	v_mfma_f32_16x16x32_bf16 v[44:47], v[198:201], v[24:27], v[0:3]
	v_mfma_f32_16x16x32_bf16 v[0:3], v[202:205], v[20:23], v[120:123]
	v_mfma_f32_16x16x32_bf16 v[52:55], v[164:167], v[24:27], v[0:3]
	v_mfma_f32_16x16x32_bf16 v[0:3], v[172:175], v[28:31], v[116:119]
	v_mfma_f32_16x16x32_bf16 v[40:43], v[198:201], v[32:35], v[0:3]
	v_mfma_f32_16x16x32_bf16 v[0:3], v[202:205], v[28:31], v[112:115]
	v_mfma_f32_16x16x32_bf16 v[16:19], v[164:167], v[32:35], v[0:3]
	v_mfma_f32_16x16x32_bf16 v[0:3], v[172:175], v[36:39], v[108:111]
	v_mfma_f32_16x16x32_bf16 v[8:11], v[198:201], v[208:211], v[0:3]
	v_mfma_f32_16x16x32_bf16 v[0:3], v[202:205], v[36:39], v[104:107]
	v_mfma_f32_16x16x32_bf16 v[12:15], v[164:167], v[208:211], v[0:3]
	v_mfma_f32_16x16x32_bf16 v[0:3], v[172:175], v[214:217], v[100:103]
	v_mfma_f32_16x16x32_bf16 v[4:7], v[202:205], v[214:217], v[96:99]
	v_mfma_f32_16x16x32_bf16 v[0:3], v[198:201], v[238:241], v[0:3]
	v_mfma_f32_16x16x32_bf16 v[4:7], v[164:167], v[238:241], v[4:7]
	s_barrier
	ds_read_b128 v[108:111], v163
	ds_read_b128 v[242:245], v163 offset:1024
	ds_read_b128 v[246:249], v163 offset:2048
	ds_read_b128 v[152:155], v163 offset:3072
	s_waitcnt vmcnt(0)
	s_barrier
	s_waitcnt lgkmcnt(0)
	s_waitcnt lgkmcnt(0)
	v_mfma_f32_16x16x32_bf16 v[56:59], v[108:111], v[20:23], v[92:95]
	v_mfma_f32_16x16x32_bf16 v[20:23], v[246:249], v[20:23], v[88:91]
	v_mfma_f32_16x16x32_bf16 v[72:75], v[152:155], v[24:27], v[20:23]
	v_mfma_f32_16x16x32_bf16 v[20:23], v[108:111], v[28:31], v[84:87]
	v_mfma_f32_16x16x32_bf16 v[60:63], v[242:245], v[24:27], v[56:59]
	v_mfma_f32_16x16x32_bf16 v[56:59], v[242:245], v[32:35], v[20:23]
	v_mfma_f32_16x16x32_bf16 v[20:23], v[246:249], v[28:31], v[80:83]
	v_mfma_f32_16x16x32_bf16 v[20:23], v[152:155], v[32:35], v[20:23]
	v_mfma_f32_16x16x32_bf16 v[24:27], v[108:111], v[36:39], v[76:79]
	v_mfma_f32_16x16x32_bf16 v[28:31], v[246:249], v[36:39], v[178:181]
	v_mfma_f32_16x16x32_bf16 v[32:35], v[108:111], v[214:217], v[68:71]
	v_mfma_f32_16x16x32_bf16 v[36:39], v[246:249], v[214:217], v[64:67]
	v_mfma_f32_16x16x32_bf16 v[24:27], v[242:245], v[208:211], v[24:27]
	v_mfma_f32_16x16x32_bf16 v[28:31], v[152:155], v[208:211], v[28:31]
	v_mfma_f32_16x16x32_bf16 v[32:35], v[242:245], v[238:241], v[32:35]
	v_mfma_f32_16x16x32_bf16 v[36:39], v[152:155], v[238:241], v[36:39]
	s_barrier
	ds_read_b128 v[88:91], v160 offset:49152
	ds_read_b128 v[92:95], v160 offset:50176
	ds_read_b128 v[96:99], v159 offset:49152
	ds_read_b128 v[100:103], v159 offset:50176
	ds_read_b128 v[104:107], v158 offset:49152
	ds_read_b128 v[158:161], v158 offset:50176
	ds_read_b128 v[176:179], v157 offset:49152
	ds_read_b128 v[208:211], v157 offset:50176
	s_barrier
	s_waitcnt lgkmcnt(0)
	s_waitcnt lgkmcnt(0)
	v_mfma_f32_16x16x32_bf16 v[48:51], v[202:205], v[96:99], v[48:51]
	v_mfma_f32_16x16x32_bf16 v[64:67], v[172:175], v[88:91], v[218:221]
	v_mfma_f32_16x16x32_bf16 v[116:119], v[164:167], v[100:103], v[48:51]
	v_mfma_f32_16x16x32_bf16 v[48:51], v[172:175], v[104:107], v[230:233]
	v_mfma_f32_16x16x32_bf16 v[120:123], v[198:201], v[92:95], v[64:67]
	v_mfma_f32_16x16x32_bf16 v[64:67], v[202:205], v[88:91], v[222:225]
	v_mfma_f32_16x16x32_bf16 v[76:79], v[198:201], v[158:161], v[48:51]
	v_mfma_f32_16x16x32_bf16 v[48:51], v[202:205], v[104:107], v[234:237]
	v_mfma_f32_16x16x32_bf16 v[124:127], v[164:167], v[92:95], v[64:67]
	v_mfma_f32_16x16x32_bf16 v[64:67], v[172:175], v[96:99], v[226:229]
	v_mfma_f32_16x16x32_bf16 v[80:83], v[164:167], v[158:161], v[48:51]
	v_mfma_f32_16x16x32_bf16 v[48:51], v[172:175], v[176:179], v[136:139]
	v_mfma_f32_16x16x32_bf16 v[112:115], v[198:201], v[100:103], v[64:67]
	v_mfma_f32_16x16x32_bf16 v[64:67], v[198:201], v[208:211], v[48:51]
	v_mfma_f32_16x16x32_bf16 v[48:51], v[202:205], v[176:179], v[144:147]
	v_mfma_f32_16x16x32_bf16 v[68:71], v[164:167], v[208:211], v[48:51]
	v_mfma_f32_16x16x32_bf16 v[48:51], v[108:111], v[88:91], v[148:151]
	v_mfma_f32_16x16x32_bf16 v[84:87], v[242:245], v[92:95], v[48:51]
	v_mfma_f32_16x16x32_bf16 v[48:51], v[246:249], v[88:91], v[168:171]
	v_mfma_f32_16x16x32_bf16 v[88:91], v[152:155], v[92:95], v[48:51]
	v_mfma_f32_16x16x32_bf16 v[48:51], v[108:111], v[96:99], v[182:185]
	v_mfma_f32_16x16x32_bf16 v[92:95], v[242:245], v[100:103], v[48:51]
	v_mfma_f32_16x16x32_bf16 v[48:51], v[246:249], v[96:99], v[186:189]
	v_mfma_f32_16x16x32_bf16 v[96:99], v[152:155], v[100:103], v[48:51]
	v_mfma_f32_16x16x32_bf16 v[48:51], v[108:111], v[104:107], v[190:193]
	v_mfma_f32_16x16x32_bf16 v[100:103], v[242:245], v[158:161], v[48:51]
	v_mfma_f32_16x16x32_bf16 v[48:51], v[246:249], v[104:107], v[194:197]
	v_mfma_f32_16x16x32_bf16 v[104:107], v[152:155], v[158:161], v[48:51]
	v_mfma_f32_16x16x32_bf16 v[48:51], v[108:111], v[176:179], v[128:131]
	v_mfma_f32_16x16x32_bf16 v[108:111], v[242:245], v[208:211], v[48:51]
	v_mfma_f32_16x16x32_bf16 v[48:51], v[246:249], v[176:179], v[140:143]
	v_mfma_f32_16x16x32_bf16 v[48:51], v[152:155], v[208:211], v[48:51]
	s_movk_i32 s14, 0x100
	v_cmp_gt_u32_e32 vcc, s14, v132
	s_barrier
	s_and_saveexec_b64 s[44:45], vcc
	s_cbranch_execz .LBB0_1200
	s_barrier
	s_branch .LBB0_1200
